# GEMM loops: back-edge rotation - loop counter/pointer SALU moved in front of the last MFMA-segment barrier
# baseline (speedup 1.0000x reference)
; #define PG8_STAGE(bufoff, gbase, voff) do { _Pragma("unroll") for (int _i = 0; _i < 2; ++_i) \
;         __builtin_amdgcn_global_load_lds((const unsigned*)((const char*)(gbase) + (voff)[_i]), (PG8_LAS unsigned*)(lds + (bufoff) + ldsw + _i * 8192), 16, 0, 0); } while (0)
; #define PG8_LDA(dst, b, h) do { _Pragma("unroll") for (int m = 0; m < 4; ++m) _Pragma("unroll") for (int k = 0; k < 2; ++k) dst[m][k] = *(const PG8_LAS bf16x8*)(lds + PG8_SA(b, h) + aoff + m * 2048 + k * 1024); } while (0)
; #define PG8_LDB(dst, b, h) do { _Pragma("unroll") for (int n = 0; n < 2; ++n) _Pragma("unroll") for (int k = 0; k < 2; ++k) dst[n][k] = *(const PG8_LAS bf16x8*)(lds + PG8_SB(b, h) + boff + n * 2048 + k * 1024); } while (0)
; #define PG8_MMA(ai, bj, At, Bt) do { __builtin_amdgcn_s_setprio(1); _Pragma("unroll") for (int m = 0; m < 4; ++m) _Pragma("unroll") for (int n = 0; n < 2; ++n) _Pragma("unroll") for (int k = 0; k < 2; ++k) \
;         acc[ai][bj][m][n] = __builtin_amdgcn_mfma_f32_16x16x32_bf16(Bt[n][k], At[m][k], acc[ai][bj][m][n], 0, 0, 0); __builtin_amdgcn_s_setprio(0); } while (0)
; #define PG8_WAIT_V(n) asm volatile("s_waitcnt vmcnt(" #n ")" ::: "memory")
; #define PG8_WAIT_L(n) asm volatile("s_waitcnt lgkmcnt(" #n ")" ::: "memory")
; #define PG8_BAR __builtin_amdgcn_s_barrier()
; #define PG8_SCHED __builtin_amdgcn_sched_barrier(0)
; template <class Epi, class Sched, bool ALIGN_EPI = false, bool SP2 = false>
; __device__ __forceinline__ void gemm_phase(PG8_LAS unsigned char* lds, const Gemm g, const Sched& S, const Epi& E) {
;     ...
;             PG8_LDB(B0, 0, 0); PG8_LDB(B1, 0, 1); PG8_SCHED; PG8_LDA(At, 0, 0); PG8_STAGE(PG8_SA(1, 1), a1 + hstep, voffA);
;             PG8_WAIT_V(8); PG8_WAIT_L(0); PG8_BAR; PG8_MMA(0, 0, At, B0); PG8_MMA(0, 1, At, B1); PG8_BAR; PG8_SCHED;
;             PG8_LDA(At, 0, 1); PG8_STAGE(PG8_SB(0, 0), b2, voffB); PG8_STAGE(PG8_SB(0, 1), b2 + hstep, voffB); PG8_STAGE(PG8_SA(0, 0), a2, voffA);
;             PG8_WAIT_V(8); PG8_WAIT_L(0); PG8_BAR; PG8_MMA(1, 0, At, B0); PG8_MMA(1, 1, At, B1); PG8_BAR; PG8_SCHED;
.LBB0_175:
	ds_read_b128 v[140:143], v177
	ds_read_b128 v[144:147], v177 offset:1024
	ds_read_b128 v[148:151], v177 offset:2048
	ds_read_b128 v[152:155], v177 offset:3072
	ds_read_b128 v[156:159], v178
	ds_read_b128 v[160:163], v178 offset:1024
	ds_read_b128 v[164:167], v178 offset:2048
	ds_read_b128 v[168:171], v178 offset:3072
	s_add_u32 s60, s58, 0xfffc0080
	s_addc_u32 s61, s59, -1
	s_cmp_eq_u32 s74, 12
	s_cselect_b32 s63, s3, s61
	s_cselect_b32 s62, s41, s60
	s_cselect_b32 s61, s45, s73
	s_cselect_b32 s60, s71, s72
	v_lshl_add_u64 v[172:173], s[58:59], 0, v[136:137]
	s_add_i32 m0, s28, 0xc000
	ds_read_b128 v[182:185], v179
	ds_read_b128 v[186:189], v179 offset:1024
	ds_read_b128 v[190:193], v179 offset:2048
	ds_read_b128 v[194:197], v179 offset:3072
	ds_read_b128 v[202:205], v179 offset:4096
	ds_read_b128 v[206:209], v179 offset:5120
	ds_read_b128 v[210:213], v179 offset:6144
	ds_read_b128 v[214:217], v179 offset:7168
	global_load_lds_dwordx4 v[172:173], off
	v_lshl_add_u64 v[172:173], s[58:59], 0, v[138:139]
	s_add_i32 m0, s28, 0xe000
	s_nop 0
	global_load_lds_dwordx4 v[172:173], off
	s_waitcnt vmcnt(8)
	s_waitcnt lgkmcnt(0)
	s_barrier
	s_setprio 1
	s_waitcnt lgkmcnt(0)
	v_mfma_f32_16x16x32_bf16 v[124:127], v[140:143], v[182:185], v[124:127]
	v_mfma_f32_16x16x32_bf16 v[120:123], v[148:151], v[182:185], v[120:123]
	v_mfma_f32_16x16x32_bf16 v[108:111], v[140:143], v[190:193], v[108:111]
	v_mfma_f32_16x16x32_bf16 v[104:107], v[148:151], v[190:193], v[104:107]
	v_mfma_f32_16x16x32_bf16 v[92:95], v[140:143], v[202:205], v[92:95]
	v_mfma_f32_16x16x32_bf16 v[88:91], v[148:151], v[202:205], v[88:91]
	v_mfma_f32_16x16x32_bf16 v[76:79], v[140:143], v[210:213], v[76:79]
	v_mfma_f32_16x16x32_bf16 v[72:75], v[148:151], v[210:213], v[72:75]
	v_mfma_f32_16x16x32_bf16 v[124:127], v[144:147], v[186:189], v[124:127]
	v_mfma_f32_16x16x32_bf16 v[120:123], v[152:155], v[186:189], v[120:123]
	v_mfma_f32_16x16x32_bf16 v[108:111], v[144:147], v[194:197], v[108:111]
	v_mfma_f32_16x16x32_bf16 v[104:107], v[152:155], v[194:197], v[104:107]
	v_mfma_f32_16x16x32_bf16 v[92:95], v[144:147], v[206:209], v[92:95]
	v_mfma_f32_16x16x32_bf16 v[88:91], v[152:155], v[206:209], v[88:91]
	v_mfma_f32_16x16x32_bf16 v[76:79], v[144:147], v[214:217], v[76:79]
	v_mfma_f32_16x16x32_bf16 v[72:75], v[152:155], v[214:217], v[72:75]
	s_setprio 0
	s_setprio 1
	v_mfma_f32_16x16x32_bf16 v[116:119], v[156:159], v[182:185], v[116:119]
	v_mfma_f32_16x16x32_bf16 v[112:115], v[164:167], v[182:185], v[112:115]
	v_mfma_f32_16x16x32_bf16 v[100:103], v[156:159], v[190:193], v[100:103]
	v_mfma_f32_16x16x32_bf16 v[96:99], v[164:167], v[190:193], v[96:99]
	v_mfma_f32_16x16x32_bf16 v[84:87], v[156:159], v[202:205], v[84:87]
	v_mfma_f32_16x16x32_bf16 v[80:83], v[164:167], v[202:205], v[80:83]
	v_mfma_f32_16x16x32_bf16 v[68:71], v[156:159], v[210:213], v[68:71]
	v_mfma_f32_16x16x32_bf16 v[64:67], v[164:167], v[210:213], v[64:67]
	v_mfma_f32_16x16x32_bf16 v[116:119], v[160:163], v[186:189], v[116:119]
	v_mfma_f32_16x16x32_bf16 v[112:115], v[168:171], v[186:189], v[112:115]
	v_mfma_f32_16x16x32_bf16 v[100:103], v[160:163], v[194:197], v[100:103]
	v_mfma_f32_16x16x32_bf16 v[96:99], v[168:171], v[194:197], v[96:99]
	v_mfma_f32_16x16x32_bf16 v[84:87], v[160:163], v[206:209], v[84:87]
	v_mfma_f32_16x16x32_bf16 v[80:83], v[168:171], v[206:209], v[80:83]
	v_mfma_f32_16x16x32_bf16 v[68:71], v[160:163], v[214:217], v[68:71]
	v_mfma_f32_16x16x32_bf16 v[64:67], v[168:171], v[214:217], v[64:67]
	s_setprio 0
	s_barrier
	s_add_i32 s75, s67, s21
	v_lshl_add_u64 v[172:173], s[60:61], 0, v[132:133]
	s_mov_b32 m0, s75
	ds_read_b128 v[182:185], v179 offset:16384
	ds_read_b128 v[186:189], v179 offset:17408
	ds_read_b128 v[190:193], v179 offset:18432
	ds_read_b128 v[194:197], v179 offset:19456
	ds_read_b128 v[202:205], v179 offset:20480
	ds_read_b128 v[206:209], v179 offset:21504
	ds_read_b128 v[210:213], v179 offset:22528
	ds_read_b128 v[214:217], v179 offset:23552
	global_load_lds_dwordx4 v[172:173], off
	s_add_i32 m0, s75, 0x2000
	s_add_u32 s76, s60, 0x40000
	v_lshl_add_u64 v[198:199], s[60:61], 0, v[128:129]
	s_addc_u32 s77, s61, 0
	s_add_i32 s75, s68, s21
	global_load_lds_dwordx4 v[198:199], off
	v_lshl_add_u64 v[218:219], s[76:77], 0, v[132:133]
	s_mov_b32 m0, s75
	v_lshl_add_u64 v[220:221], s[62:63], 0, v[130:131]
	global_load_lds_dwordx4 v[218:219], off
	v_lshl_add_u64 v[218:219], s[76:77], 0, v[128:129]
	s_add_i32 m0, s75, 0x2000
	s_nop 0
	global_load_lds_dwordx4 v[218:219], off
	v_lshl_add_u64 v[218:219], s[62:63], 0, v[134:135]
	s_mov_b32 m0, s28
	s_nop 0
	global_load_lds_dwordx4 v[218:219], off
	s_mov_b32 m0, s29
	s_nop 0
	global_load_lds_dwordx4 v[220:221], off
	s_waitcnt vmcnt(8)
	s_waitcnt lgkmcnt(0)
	s_barrier
; #define PG8_STAGE(bufoff, gbase, voff) do { _Pragma("unroll") for (int _i = 0; _i < 2; ++_i) \
;         __builtin_amdgcn_global_load_lds((const unsigned*)((const char*)(gbase) + (voff)[_i]), (PG8_LAS unsigned*)(lds + (bufoff) + ldsw + _i * 8192), 16, 0, 0); } while (0)
; #define PG8_LDA(dst, b, h) do { _Pragma("unroll") for (int m = 0; m < 4; ++m) _Pragma("unroll") for (int k = 0; k < 2; ++k) dst[m][k] = *(const PG8_LAS bf16x8*)(lds + PG8_SA(b, h) + aoff + m * 2048 + k * 1024); } while (0)
; #define PG8_LDB(dst, b, h) do { _Pragma("unroll") for (int n = 0; n < 2; ++n) _Pragma("unroll") for (int k = 0; k < 2; ++k) dst[n][k] = *(const PG8_LAS bf16x8*)(lds + PG8_SB(b, h) + boff + n * 2048 + k * 1024); } while (0)
; #define PG8_MMA(ai, bj, At, Bt) do { __builtin_amdgcn_s_setprio(1); _Pragma("unroll") for (int m = 0; m < 4; ++m) _Pragma("unroll") for (int n = 0; n < 2; ++n) _Pragma("unroll") for (int k = 0; k < 2; ++k) \
;         acc[ai][bj][m][n] = __builtin_amdgcn_mfma_f32_16x16x32_bf16(Bt[n][k], At[m][k], acc[ai][bj][m][n], 0, 0, 0); __builtin_amdgcn_s_setprio(0); } while (0)
; #define PG8_WAIT_V(n) asm volatile("s_waitcnt vmcnt(" #n ")" ::: "memory")
; #define PG8_WAIT_L(n) asm volatile("s_waitcnt lgkmcnt(" #n ")" ::: "memory")
; #define PG8_BAR __builtin_amdgcn_s_barrier()
; #define PG8_SCHED __builtin_amdgcn_sched_barrier(0)
; template <class Epi, class Sched, bool ALIGN_EPI = false, bool SP2 = false>
; __device__ __forceinline__ void gemm_phase(PG8_LAS unsigned char* lds, const Gemm g, const Sched& S, const Epi& E) {
;     ...
;             PG8_WAIT_V(8); PG8_WAIT_L(0); PG8_BAR; PG8_MMA(1, 0, At, B0); PG8_MMA(1, 1, At, B1); PG8_BAR; PG8_SCHED;
;             PG8_LDB(B0, 1, 0); PG8_LDB(B1, 1, 1); PG8_SCHED; PG8_LDA(At, 1, 0); PG8_STAGE(PG8_SA(0, 1), a2 + hstep, voffA);
;             PG8_WAIT_V(8); PG8_WAIT_L(0); PG8_BAR; PG8_MMA(0, 0, At, B0); PG8_MMA(0, 1, At, B1); PG8_BAR; PG8_SCHED;
	s_setprio 1
	s_waitcnt lgkmcnt(0)
	v_mfma_f32_16x16x32_bf16 v[60:63], v[140:143], v[182:185], v[60:63]
	v_mfma_f32_16x16x32_bf16 v[56:59], v[148:151], v[182:185], v[56:59]
	v_mfma_f32_16x16x32_bf16 v[44:47], v[140:143], v[190:193], v[44:47]
	v_mfma_f32_16x16x32_bf16 v[40:43], v[148:151], v[190:193], v[40:43]
	v_mfma_f32_16x16x32_bf16 v[28:31], v[140:143], v[202:205], v[28:31]
	v_mfma_f32_16x16x32_bf16 v[24:27], v[148:151], v[202:205], v[24:27]
	v_mfma_f32_16x16x32_bf16 v[12:15], v[140:143], v[210:213], v[12:15]
	v_mfma_f32_16x16x32_bf16 v[8:11], v[148:151], v[210:213], v[8:11]
	v_mfma_f32_16x16x32_bf16 v[60:63], v[144:147], v[186:189], v[60:63]
	v_mfma_f32_16x16x32_bf16 v[56:59], v[152:155], v[186:189], v[56:59]
	v_mfma_f32_16x16x32_bf16 v[44:47], v[144:147], v[194:197], v[44:47]
	v_mfma_f32_16x16x32_bf16 v[40:43], v[152:155], v[194:197], v[40:43]
	v_mfma_f32_16x16x32_bf16 v[28:31], v[144:147], v[206:209], v[28:31]
	v_mfma_f32_16x16x32_bf16 v[24:27], v[152:155], v[206:209], v[24:27]
	v_mfma_f32_16x16x32_bf16 v[12:15], v[144:147], v[214:217], v[12:15]
	v_mfma_f32_16x16x32_bf16 v[8:11], v[152:155], v[214:217], v[8:11]
	s_setprio 0
	s_setprio 1
	v_mfma_f32_16x16x32_bf16 v[52:55], v[156:159], v[182:185], v[52:55]
	v_mfma_f32_16x16x32_bf16 v[48:51], v[164:167], v[182:185], v[48:51]
	v_mfma_f32_16x16x32_bf16 v[36:39], v[156:159], v[190:193], v[36:39]
	v_mfma_f32_16x16x32_bf16 v[32:35], v[164:167], v[190:193], v[32:35]
	v_mfma_f32_16x16x32_bf16 v[20:23], v[156:159], v[202:205], v[20:23]
	v_mfma_f32_16x16x32_bf16 v[16:19], v[164:167], v[202:205], v[16:19]
	v_mfma_f32_16x16x32_bf16 v[4:7], v[156:159], v[210:213], v[4:7]
	v_mfma_f32_16x16x32_bf16 v[0:3], v[164:167], v[210:213], v[0:3]
	v_mfma_f32_16x16x32_bf16 v[52:55], v[160:163], v[186:189], v[52:55]
	v_mfma_f32_16x16x32_bf16 v[48:51], v[168:171], v[186:189], v[48:51]
	v_mfma_f32_16x16x32_bf16 v[36:39], v[160:163], v[194:197], v[36:39]
	v_mfma_f32_16x16x32_bf16 v[32:35], v[168:171], v[194:197], v[32:35]
	v_mfma_f32_16x16x32_bf16 v[20:23], v[160:163], v[206:209], v[20:23]
	v_mfma_f32_16x16x32_bf16 v[16:19], v[168:171], v[206:209], v[16:19]
	v_mfma_f32_16x16x32_bf16 v[4:7], v[160:163], v[214:217], v[4:7]
	v_mfma_f32_16x16x32_bf16 v[0:3], v[168:171], v[214:217], v[0:3]
	s_setprio 0
	s_barrier
	s_add_i32 s75, 0, 0x18000
	s_add_i32 s76, 0, 0x1c000
	v_add_u32_e32 v152, s75, v175
	v_add_u32_e32 v168, s76, v175
	ds_read_b128 v[140:143], v152
	ds_read_b128 v[144:147], v152 offset:1024
	ds_read_b128 v[148:151], v152 offset:2048
	ds_read_b128 v[152:155], v152 offset:3072
	ds_read_b128 v[156:159], v168
	ds_read_b128 v[160:163], v168 offset:1024
	ds_read_b128 v[164:167], v168 offset:2048
	ds_read_b128 v[168:171], v168 offset:3072
	s_add_u32 s62, s62, 0x40000
	s_addc_u32 s63, s63, 0
	s_mov_b32 m0, s30
	v_lshl_add_u64 v[222:223], s[62:63], 0, v[134:135]
	ds_read_b128 v[182:185], v179 offset:32768
	ds_read_b128 v[186:189], v179 offset:33792
	ds_read_b128 v[190:193], v179 offset:34816
	ds_read_b128 v[194:197], v179 offset:35840
	ds_read_b128 v[202:205], v179 offset:36864
	ds_read_b128 v[206:209], v179 offset:37888
	ds_read_b128 v[210:213], v179 offset:38912
	ds_read_b128 v[214:217], v179 offset:39936
	global_load_lds_dwordx4 v[222:223], off
	v_lshl_add_u64 v[222:223], s[62:63], 0, v[130:131]
	s_mov_b32 m0, s31
	s_nop 0
	global_load_lds_dwordx4 v[222:223], off
	s_waitcnt vmcnt(8)
	s_waitcnt lgkmcnt(0)
	s_barrier
	s_setprio 1
	s_waitcnt lgkmcnt(0)
	v_mfma_f32_16x16x32_bf16 v[124:127], v[140:143], v[182:185], v[124:127]
	v_mfma_f32_16x16x32_bf16 v[120:123], v[148:151], v[182:185], v[120:123]
	v_mfma_f32_16x16x32_bf16 v[108:111], v[140:143], v[190:193], v[108:111]
	v_mfma_f32_16x16x32_bf16 v[104:107], v[148:151], v[190:193], v[104:107]
	v_mfma_f32_16x16x32_bf16 v[92:95], v[140:143], v[202:205], v[92:95]
	v_mfma_f32_16x16x32_bf16 v[88:91], v[148:151], v[202:205], v[88:91]
	v_mfma_f32_16x16x32_bf16 v[76:79], v[140:143], v[210:213], v[76:79]
	v_mfma_f32_16x16x32_bf16 v[72:75], v[148:151], v[210:213], v[72:75]
	v_mfma_f32_16x16x32_bf16 v[124:127], v[144:147], v[186:189], v[124:127]
	v_mfma_f32_16x16x32_bf16 v[120:123], v[152:155], v[186:189], v[120:123]
	v_mfma_f32_16x16x32_bf16 v[108:111], v[144:147], v[194:197], v[108:111]
	v_mfma_f32_16x16x32_bf16 v[104:107], v[152:155], v[194:197], v[104:107]
	v_mfma_f32_16x16x32_bf16 v[92:95], v[144:147], v[206:209], v[92:95]
	v_mfma_f32_16x16x32_bf16 v[88:91], v[152:155], v[206:209], v[88:91]
	v_mfma_f32_16x16x32_bf16 v[76:79], v[144:147], v[214:217], v[76:79]
	v_mfma_f32_16x16x32_bf16 v[72:75], v[152:155], v[214:217], v[72:75]
	s_setprio 0
	s_setprio 1
	v_mfma_f32_16x16x32_bf16 v[116:119], v[156:159], v[182:185], v[116:119]
	v_mfma_f32_16x16x32_bf16 v[112:115], v[164:167], v[182:185], v[112:115]
	v_mfma_f32_16x16x32_bf16 v[100:103], v[156:159], v[190:193], v[100:103]
	v_mfma_f32_16x16x32_bf16 v[96:99], v[164:167], v[190:193], v[96:99]
	v_mfma_f32_16x16x32_bf16 v[84:87], v[156:159], v[202:205], v[84:87]
	v_mfma_f32_16x16x32_bf16 v[80:83], v[164:167], v[202:205], v[80:83]
	v_mfma_f32_16x16x32_bf16 v[68:71], v[156:159], v[210:213], v[68:71]
	v_mfma_f32_16x16x32_bf16 v[64:67], v[164:167], v[210:213], v[64:67]
	v_mfma_f32_16x16x32_bf16 v[116:119], v[160:163], v[186:189], v[116:119]
	v_mfma_f32_16x16x32_bf16 v[112:115], v[168:171], v[186:189], v[112:115]
	v_mfma_f32_16x16x32_bf16 v[100:103], v[160:163], v[194:197], v[100:103]
	v_mfma_f32_16x16x32_bf16 v[96:99], v[168:171], v[194:197], v[96:99]
	v_mfma_f32_16x16x32_bf16 v[84:87], v[160:163], v[206:209], v[84:87]
	v_mfma_f32_16x16x32_bf16 v[80:83], v[168:171], v[206:209], v[80:83]
	v_mfma_f32_16x16x32_bf16 v[68:71], v[160:163], v[214:217], v[68:71]
	v_mfma_f32_16x16x32_bf16 v[64:67], v[168:171], v[214:217], v[64:67]
	s_setprio 0
	s_barrier
; #define PG8_STAGE(bufoff, gbase, voff) do { _Pragma("unroll") for (int _i = 0; _i < 2; ++_i) \
;         __builtin_amdgcn_global_load_lds((const unsigned*)((const char*)(gbase) + (voff)[_i]), (PG8_LAS unsigned*)(lds + (bufoff) + ldsw + _i * 8192), 16, 0, 0); } while (0)
; #define PG8_LDA(dst, b, h) do { _Pragma("unroll") for (int m = 0; m < 4; ++m) _Pragma("unroll") for (int k = 0; k < 2; ++k) dst[m][k] = *(const PG8_LAS bf16x8*)(lds + PG8_SA(b, h) + aoff + m * 2048 + k * 1024); } while (0)
; #define PG8_MMA(ai, bj, At, Bt) do { __builtin_amdgcn_s_setprio(1); _Pragma("unroll") for (int m = 0; m < 4; ++m) _Pragma("unroll") for (int n = 0; n < 2; ++n) _Pragma("unroll") for (int k = 0; k < 2; ++k) \
;         acc[ai][bj][m][n] = __builtin_amdgcn_mfma_f32_16x16x32_bf16(Bt[n][k], At[m][k], acc[ai][bj][m][n], 0, 0, 0); __builtin_amdgcn_s_setprio(0); } while (0)
; #define PG8_WAIT_V(n) asm volatile("s_waitcnt vmcnt(" #n ")" ::: "memory")
; #define PG8_WAIT_L(n) asm volatile("s_waitcnt lgkmcnt(" #n ")" ::: "memory")
; #define PG8_BAR __builtin_amdgcn_s_barrier()
; #define PG8_SCHED __builtin_amdgcn_sched_barrier(0)
; template <class Epi, class Sched, bool ALIGN_EPI = false, bool SP2 = false>
; __device__ __forceinline__ void gemm_phase(PG8_LAS unsigned char* lds, const Gemm g, const Sched& S, const Epi& E) {
;     ...
;             PG8_LDA(At, 1, 1); PG8_STAGE(PG8_SB(1, 0), b3, voffB); PG8_STAGE(PG8_SB(1, 1), b3 + hstep, voffB); PG8_STAGE(PG8_SA(1, 0), a3, voffA);
;             PG8_WAIT_V(8); PG8_WAIT_L(0); PG8_BAR; PG8_MMA(1, 0, At, B0); PG8_MMA(1, 1, At, B1); PG8_BAR; PG8_SCHED;
	s_add_i32 s62, s75, s21
	v_lshl_add_u64 v[172:173], v[172:173], 0, s[36:37]
	s_mov_b32 m0, s62
	ds_read_b128 v[182:185], v179 offset:49152
	ds_read_b128 v[186:189], v179 offset:50176
	ds_read_b128 v[190:193], v179 offset:51200
	ds_read_b128 v[194:197], v179 offset:52224
	ds_read_b128 v[202:205], v179 offset:53248
	ds_read_b128 v[206:209], v179 offset:54272
	ds_read_b128 v[210:213], v179 offset:55296
	ds_read_b128 v[214:217], v179 offset:56320
	global_load_lds_dwordx4 v[172:173], off
	s_add_i32 m0, s62, 0x2000
	s_add_u32 s60, s60, 0x40080
	v_lshl_add_u64 v[172:173], v[198:199], 0, s[36:37]
	s_addc_u32 s61, s61, 0
	s_add_i32 s62, s76, s21
	global_load_lds_dwordx4 v[172:173], off
	v_lshl_add_u64 v[172:173], s[60:61], 0, v[132:133]
	s_mov_b32 m0, s62
	s_nop 0
	global_load_lds_dwordx4 v[172:173], off
	v_lshl_add_u64 v[172:173], s[60:61], 0, v[128:129]
	s_add_i32 m0, s62, 0x2000
	s_nop 0
	global_load_lds_dwordx4 v[172:173], off
	v_lshl_add_u64 v[172:173], v[218:219], 0, s[36:37]
	s_mov_b32 m0, s65
	s_nop 0
	global_load_lds_dwordx4 v[172:173], off
	v_lshl_add_u64 v[172:173], v[220:221], 0, s[36:37]
	s_mov_b32 m0, s66
	s_nop 0
	global_load_lds_dwordx4 v[172:173], off
	s_waitcnt vmcnt(8)
	s_waitcnt lgkmcnt(0)
	s_barrier
	s_setprio 1
	s_waitcnt lgkmcnt(0)
	v_mfma_f32_16x16x32_bf16 v[60:63], v[140:143], v[182:185], v[60:63]
	v_mfma_f32_16x16x32_bf16 v[56:59], v[148:151], v[182:185], v[56:59]
	v_mfma_f32_16x16x32_bf16 v[44:47], v[140:143], v[190:193], v[44:47]
	v_mfma_f32_16x16x32_bf16 v[40:43], v[148:151], v[190:193], v[40:43]
	v_mfma_f32_16x16x32_bf16 v[28:31], v[140:143], v[202:205], v[28:31]
	v_mfma_f32_16x16x32_bf16 v[24:27], v[148:151], v[202:205], v[24:27]
	v_mfma_f32_16x16x32_bf16 v[12:15], v[140:143], v[210:213], v[12:15]
	v_mfma_f32_16x16x32_bf16 v[8:11], v[148:151], v[210:213], v[8:11]
	v_mfma_f32_16x16x32_bf16 v[60:63], v[144:147], v[186:189], v[60:63]
	v_mfma_f32_16x16x32_bf16 v[56:59], v[152:155], v[186:189], v[56:59]
	v_mfma_f32_16x16x32_bf16 v[44:47], v[144:147], v[194:197], v[44:47]
	v_mfma_f32_16x16x32_bf16 v[40:43], v[152:155], v[194:197], v[40:43]
	v_mfma_f32_16x16x32_bf16 v[28:31], v[144:147], v[206:209], v[28:31]
	v_mfma_f32_16x16x32_bf16 v[24:27], v[152:155], v[206:209], v[24:27]
	v_mfma_f32_16x16x32_bf16 v[12:15], v[144:147], v[214:217], v[12:15]
	v_mfma_f32_16x16x32_bf16 v[8:11], v[152:155], v[214:217], v[8:11]
	s_setprio 0
	s_setprio 1
	v_mfma_f32_16x16x32_bf16 v[52:55], v[156:159], v[182:185], v[52:55]
	v_mfma_f32_16x16x32_bf16 v[48:51], v[164:167], v[182:185], v[48:51]
	v_mfma_f32_16x16x32_bf16 v[36:39], v[156:159], v[190:193], v[36:39]
	v_mfma_f32_16x16x32_bf16 v[32:35], v[164:167], v[190:193], v[32:35]
	v_mfma_f32_16x16x32_bf16 v[20:23], v[156:159], v[202:205], v[20:23]
	v_mfma_f32_16x16x32_bf16 v[16:19], v[164:167], v[202:205], v[16:19]
	v_mfma_f32_16x16x32_bf16 v[4:7], v[156:159], v[210:213], v[4:7]
	v_mfma_f32_16x16x32_bf16 v[0:3], v[164:167], v[210:213], v[0:3]
	v_mfma_f32_16x16x32_bf16 v[52:55], v[160:163], v[186:189], v[52:55]
	v_mfma_f32_16x16x32_bf16 v[48:51], v[168:171], v[186:189], v[48:51]
	v_mfma_f32_16x16x32_bf16 v[36:39], v[160:163], v[194:197], v[36:39]
	v_mfma_f32_16x16x32_bf16 v[32:35], v[168:171], v[194:197], v[32:35]
	v_mfma_f32_16x16x32_bf16 v[20:23], v[160:163], v[206:209], v[20:23]
	v_mfma_f32_16x16x32_bf16 v[16:19], v[168:171], v[206:209], v[16:19]
	v_mfma_f32_16x16x32_bf16 v[4:7], v[160:163], v[214:217], v[4:7]
	v_mfma_f32_16x16x32_bf16 v[0:3], v[168:171], v[214:217], v[0:3]
	s_setprio 0
	s_add_i32 s74, s74, 2
	s_add_u32 s58, s58, 0x100
	s_addc_u32 s59, s59, 0
	s_add_u32 s72, s72, 0x100
	s_addc_u32 s73, s73, 0
	s_barrier
	s_cmp_gt_u32 s74, 13
	s_cbranch_scc0 .LBB0_175
	s_and_b64 vcc, exec, s[38:39]
	s_cbranch_vccz .LBB0_178
	s_barrier

; #define PG8_STAGE(bufoff, gbase, voff) do { _Pragma("unroll") for (int _i = 0; _i < 2; ++_i) \
;         __builtin_amdgcn_global_load_lds((const unsigned*)((const char*)(gbase) + (voff)[_i]), (PG8_LAS unsigned*)(lds + (bufoff) + ldsw + _i * 8192), 16, 0, 0); } while (0)
; #define PG8_LDA(dst, b, h) do { _Pragma("unroll") for (int m = 0; m < 4; ++m) _Pragma("unroll") for (int k = 0; k < 2; ++k) dst[m][k] = *(const PG8_LAS bf16x8*)(lds + PG8_SA(b, h) + aoff + m * 2048 + k * 1024); } while (0)
; #define PG8_LDB(dst, b, h) do { _Pragma("unroll") for (int n = 0; n < 2; ++n) _Pragma("unroll") for (int k = 0; k < 2; ++k) dst[n][k] = *(const PG8_LAS bf16x8*)(lds + PG8_SB(b, h) + boff + n * 2048 + k * 1024); } while (0)
; #define PG8_MMA(ai, bj, At, Bt) do { __builtin_amdgcn_s_setprio(1); _Pragma("unroll") for (int m = 0; m < 4; ++m) _Pragma("unroll") for (int n = 0; n < 2; ++n) _Pragma("unroll") for (int k = 0; k < 2; ++k) \
;         acc[ai][bj][m][n] = __builtin_amdgcn_mfma_f32_16x16x32_bf16(Bt[n][k], At[m][k], acc[ai][bj][m][n], 0, 0, 0); __builtin_amdgcn_s_setprio(0); } while (0)
; #define PG8_WAIT_V(n) asm volatile("s_waitcnt vmcnt(" #n ")" ::: "memory")
; #define PG8_WAIT_L(n) asm volatile("s_waitcnt lgkmcnt(" #n ")" ::: "memory")
; #define PG8_BAR __builtin_amdgcn_s_barrier()
; #define PG8_SCHED __builtin_amdgcn_sched_barrier(0)
; template <class Epi, class Sched, bool ALIGN_EPI = false, bool SP2 = false>
; __device__ __forceinline__ void gemm_phase(PG8_LAS unsigned char* lds, const Gemm g, const Sched& S, const Epi& E) {
;     ...
;             PG8_LDB(B0, 0, 0); PG8_LDB(B1, 0, 1); PG8_SCHED; PG8_LDA(At, 0, 0); PG8_STAGE(PG8_SA(1, 1), a1 + hstep, voffA);
;             PG8_WAIT_V(8); PG8_WAIT_L(0); PG8_BAR; PG8_MMA(0, 0, At, B0); PG8_MMA(0, 1, At, B1); PG8_BAR; PG8_SCHED;
;             PG8_LDA(At, 0, 1); PG8_STAGE(PG8_SB(0, 0), b2, voffB); PG8_STAGE(PG8_SB(0, 1), b2 + hstep, voffB); PG8_STAGE(PG8_SA(0, 0), a2, voffA);
;             PG8_WAIT_V(8); PG8_WAIT_L(0); PG8_BAR; PG8_MMA(1, 0, At, B0); PG8_MMA(1, 1, At, B1); PG8_BAR; PG8_SCHED;
.LBB0_245:
	ds_read_b128 v[128:131], v156
	ds_read_b128 v[132:135], v156 offset:1024
	ds_read_b128 v[148:151], v156 offset:2048
	ds_read_b128 v[162:165], v156 offset:3072
	ds_read_b128 v[166:169], v157
	ds_read_b128 v[170:173], v157 offset:1024
	ds_read_b128 v[174:177], v157 offset:2048
	ds_read_b128 v[178:181], v157 offset:3072
	s_add_u32 s58, s56, 0xfff50080
	s_addc_u32 s59, s57, -1
	s_cmp_eq_u32 s85, 40
	s_cselect_b32 s61, s47, s59
	s_cselect_b32 s60, s46, s58
	s_cselect_b32 s59, s51, s84
	s_cselect_b32 s58, s50, s83
	s_mov_b32 m0, s71
	v_lshl_add_u64 v[152:153], s[56:57], 0, v[144:145]
	ds_read_b128 v[182:185], v158
	ds_read_b128 v[186:189], v158 offset:1024
	ds_read_b128 v[190:193], v158 offset:2048
	ds_read_b128 v[194:197], v158 offset:3072
	ds_read_b128 v[202:205], v158 offset:4096
	ds_read_b128 v[206:209], v158 offset:5120
	ds_read_b128 v[210:213], v158 offset:6144
	ds_read_b128 v[214:217], v158 offset:7168
	global_load_lds_dwordx4 v[152:153], off
	v_lshl_add_u64 v[152:153], s[56:57], 0, v[146:147]
	s_mov_b32 m0, s72
	s_nop 0
	global_load_lds_dwordx4 v[152:153], off
	s_waitcnt vmcnt(8)
	s_waitcnt lgkmcnt(0)
	s_barrier
	s_setprio 1
	s_waitcnt lgkmcnt(0)
	v_mfma_f32_16x16x32_bf16 v[124:127], v[128:131], v[182:185], v[124:127]
	v_mfma_f32_16x16x32_bf16 v[120:123], v[148:151], v[182:185], v[120:123]
	v_mfma_f32_16x16x32_bf16 v[108:111], v[128:131], v[190:193], v[108:111]
	v_mfma_f32_16x16x32_bf16 v[104:107], v[148:151], v[190:193], v[104:107]
	v_mfma_f32_16x16x32_bf16 v[92:95], v[128:131], v[202:205], v[92:95]
	v_mfma_f32_16x16x32_bf16 v[88:91], v[148:151], v[202:205], v[88:91]
	v_mfma_f32_16x16x32_bf16 v[76:79], v[128:131], v[210:213], v[76:79]
	v_mfma_f32_16x16x32_bf16 v[72:75], v[148:151], v[210:213], v[72:75]
	v_mfma_f32_16x16x32_bf16 v[124:127], v[132:135], v[186:189], v[124:127]
	v_mfma_f32_16x16x32_bf16 v[120:123], v[162:165], v[186:189], v[120:123]
	v_mfma_f32_16x16x32_bf16 v[108:111], v[132:135], v[194:197], v[108:111]
	v_mfma_f32_16x16x32_bf16 v[104:107], v[162:165], v[194:197], v[104:107]
	v_mfma_f32_16x16x32_bf16 v[92:95], v[132:135], v[206:209], v[92:95]
	v_mfma_f32_16x16x32_bf16 v[88:91], v[162:165], v[206:209], v[88:91]
	v_mfma_f32_16x16x32_bf16 v[76:79], v[132:135], v[214:217], v[76:79]
	v_mfma_f32_16x16x32_bf16 v[72:75], v[162:165], v[214:217], v[72:75]
	s_setprio 0
	s_setprio 1
	v_mfma_f32_16x16x32_bf16 v[116:119], v[166:169], v[182:185], v[116:119]
	v_mfma_f32_16x16x32_bf16 v[112:115], v[174:177], v[182:185], v[112:115]
	v_mfma_f32_16x16x32_bf16 v[100:103], v[166:169], v[190:193], v[100:103]
	v_mfma_f32_16x16x32_bf16 v[96:99], v[174:177], v[190:193], v[96:99]
	v_mfma_f32_16x16x32_bf16 v[84:87], v[166:169], v[202:205], v[84:87]
	v_mfma_f32_16x16x32_bf16 v[80:83], v[174:177], v[202:205], v[80:83]
	v_mfma_f32_16x16x32_bf16 v[68:71], v[166:169], v[210:213], v[68:71]
	v_mfma_f32_16x16x32_bf16 v[64:67], v[174:177], v[210:213], v[64:67]
	v_mfma_f32_16x16x32_bf16 v[116:119], v[170:173], v[186:189], v[116:119]
	v_mfma_f32_16x16x32_bf16 v[112:115], v[178:181], v[186:189], v[112:115]
	v_mfma_f32_16x16x32_bf16 v[100:103], v[170:173], v[194:197], v[100:103]
	v_mfma_f32_16x16x32_bf16 v[96:99], v[178:181], v[194:197], v[96:99]
	v_mfma_f32_16x16x32_bf16 v[84:87], v[170:173], v[206:209], v[84:87]
	v_mfma_f32_16x16x32_bf16 v[80:83], v[178:181], v[206:209], v[80:83]
	v_mfma_f32_16x16x32_bf16 v[68:71], v[170:173], v[214:217], v[68:71]
	v_mfma_f32_16x16x32_bf16 v[64:67], v[178:181], v[214:217], v[64:67]
	s_setprio 0
	s_barrier
	s_mov_b32 m0, s73
	v_lshl_add_u64 v[152:153], s[58:59], 0, v[138:139]
	s_add_u32 s86, s58, 0xb0000
	ds_read_b128 v[182:185], v158 offset:16384
	ds_read_b128 v[186:189], v158 offset:17408
	ds_read_b128 v[190:193], v158 offset:18432
	ds_read_b128 v[194:197], v158 offset:19456
	ds_read_b128 v[202:205], v158 offset:20480
	ds_read_b128 v[206:209], v158 offset:21504
	ds_read_b128 v[210:213], v158 offset:22528
	ds_read_b128 v[214:217], v158 offset:23552
	global_load_lds_dwordx4 v[152:153], off
	v_lshl_add_u64 v[198:199], s[58:59], 0, v[142:143]
	s_mov_b32 m0, s74
	s_addc_u32 s87, s59, 0
	global_load_lds_dwordx4 v[198:199], off
	v_lshl_add_u64 v[218:219], s[86:87], 0, v[138:139]
	s_mov_b32 m0, s75
	v_lshl_add_u64 v[220:221], s[60:61], 0, v[140:141]
	global_load_lds_dwordx4 v[218:219], off
	v_lshl_add_u64 v[218:219], s[86:87], 0, v[142:143]
	s_mov_b32 m0, s76
	s_nop 0
	global_load_lds_dwordx4 v[218:219], off
	v_lshl_add_u64 v[218:219], s[60:61], 0, v[136:137]
	s_mov_b32 m0, s28
	s_nop 0
	global_load_lds_dwordx4 v[218:219], off
	s_mov_b32 m0, s29
	s_nop 0
	global_load_lds_dwordx4 v[220:221], off
	s_waitcnt vmcnt(8)
	s_waitcnt lgkmcnt(0)
	s_barrier
; #define PG8_STAGE(bufoff, gbase, voff) do { _Pragma("unroll") for (int _i = 0; _i < 2; ++_i) \
;         __builtin_amdgcn_global_load_lds((const unsigned*)((const char*)(gbase) + (voff)[_i]), (PG8_LAS unsigned*)(lds + (bufoff) + ldsw + _i * 8192), 16, 0, 0); } while (0)
; #define PG8_LDA(dst, b, h) do { _Pragma("unroll") for (int m = 0; m < 4; ++m) _Pragma("unroll") for (int k = 0; k < 2; ++k) dst[m][k] = *(const PG8_LAS bf16x8*)(lds + PG8_SA(b, h) + aoff + m * 2048 + k * 1024); } while (0)
; #define PG8_LDB(dst, b, h) do { _Pragma("unroll") for (int n = 0; n < 2; ++n) _Pragma("unroll") for (int k = 0; k < 2; ++k) dst[n][k] = *(const PG8_LAS bf16x8*)(lds + PG8_SB(b, h) + boff + n * 2048 + k * 1024); } while (0)
; #define PG8_MMA(ai, bj, At, Bt) do { __builtin_amdgcn_s_setprio(1); _Pragma("unroll") for (int m = 0; m < 4; ++m) _Pragma("unroll") for (int n = 0; n < 2; ++n) _Pragma("unroll") for (int k = 0; k < 2; ++k) \
;         acc[ai][bj][m][n] = __builtin_amdgcn_mfma_f32_16x16x32_bf16(Bt[n][k], At[m][k], acc[ai][bj][m][n], 0, 0, 0); __builtin_amdgcn_s_setprio(0); } while (0)
; #define PG8_WAIT_V(n) asm volatile("s_waitcnt vmcnt(" #n ")" ::: "memory")
; #define PG8_WAIT_L(n) asm volatile("s_waitcnt lgkmcnt(" #n ")" ::: "memory")
; #define PG8_BAR __builtin_amdgcn_s_barrier()
; #define PG8_SCHED __builtin_amdgcn_sched_barrier(0)
; template <class Epi, class Sched, bool ALIGN_EPI = false, bool SP2 = false>
; __device__ __forceinline__ void gemm_phase(PG8_LAS unsigned char* lds, const Gemm g, const Sched& S, const Epi& E) {
;     ...
;             PG8_WAIT_V(8); PG8_WAIT_L(0); PG8_BAR; PG8_MMA(1, 0, At, B0); PG8_MMA(1, 1, At, B1); PG8_BAR; PG8_SCHED;
;             PG8_LDB(B0, 1, 0); PG8_LDB(B1, 1, 1); PG8_SCHED; PG8_LDA(At, 1, 0); PG8_STAGE(PG8_SA(0, 1), a2 + hstep, voffA);
;             PG8_WAIT_V(8); PG8_WAIT_L(0); PG8_BAR; PG8_MMA(0, 0, At, B0); PG8_MMA(0, 1, At, B1); PG8_BAR; PG8_SCHED;
	s_setprio 1
	s_waitcnt lgkmcnt(0)
	v_mfma_f32_16x16x32_bf16 v[60:63], v[128:131], v[182:185], v[60:63]
	v_mfma_f32_16x16x32_bf16 v[56:59], v[148:151], v[182:185], v[56:59]
	v_mfma_f32_16x16x32_bf16 v[44:47], v[128:131], v[190:193], v[44:47]
	v_mfma_f32_16x16x32_bf16 v[40:43], v[148:151], v[190:193], v[40:43]
	v_mfma_f32_16x16x32_bf16 v[32:35], v[128:131], v[202:205], v[32:35]
	v_mfma_f32_16x16x32_bf16 v[24:27], v[148:151], v[202:205], v[24:27]
	v_mfma_f32_16x16x32_bf16 v[16:19], v[128:131], v[210:213], v[16:19]
	v_mfma_f32_16x16x32_bf16 v[8:11], v[148:151], v[210:213], v[8:11]
	v_mfma_f32_16x16x32_bf16 v[60:63], v[132:135], v[186:189], v[60:63]
	v_mfma_f32_16x16x32_bf16 v[56:59], v[162:165], v[186:189], v[56:59]
	v_mfma_f32_16x16x32_bf16 v[44:47], v[132:135], v[194:197], v[44:47]
	v_mfma_f32_16x16x32_bf16 v[40:43], v[162:165], v[194:197], v[40:43]
	v_mfma_f32_16x16x32_bf16 v[32:35], v[132:135], v[206:209], v[32:35]
	v_mfma_f32_16x16x32_bf16 v[24:27], v[162:165], v[206:209], v[24:27]
	v_mfma_f32_16x16x32_bf16 v[16:19], v[132:135], v[214:217], v[16:19]
	v_mfma_f32_16x16x32_bf16 v[8:11], v[162:165], v[214:217], v[8:11]
	s_setprio 0
	s_setprio 1
	v_mfma_f32_16x16x32_bf16 v[52:55], v[166:169], v[182:185], v[52:55]
	v_mfma_f32_16x16x32_bf16 v[48:51], v[174:177], v[182:185], v[48:51]
	v_mfma_f32_16x16x32_bf16 v[36:39], v[166:169], v[190:193], v[36:39]
	v_mfma_f32_16x16x32_bf16 v[28:31], v[174:177], v[190:193], v[28:31]
	v_mfma_f32_16x16x32_bf16 v[20:23], v[166:169], v[202:205], v[20:23]
	v_mfma_f32_16x16x32_bf16 v[12:15], v[174:177], v[202:205], v[12:15]
	v_mfma_f32_16x16x32_bf16 v[4:7], v[166:169], v[210:213], v[4:7]
	v_mfma_f32_16x16x32_bf16 v[0:3], v[174:177], v[210:213], v[0:3]
	v_mfma_f32_16x16x32_bf16 v[52:55], v[170:173], v[186:189], v[52:55]
	v_mfma_f32_16x16x32_bf16 v[48:51], v[178:181], v[186:189], v[48:51]
	v_mfma_f32_16x16x32_bf16 v[36:39], v[170:173], v[194:197], v[36:39]
	v_mfma_f32_16x16x32_bf16 v[28:31], v[178:181], v[194:197], v[28:31]
	v_mfma_f32_16x16x32_bf16 v[20:23], v[170:173], v[206:209], v[20:23]
	v_mfma_f32_16x16x32_bf16 v[12:15], v[178:181], v[206:209], v[12:15]
	v_mfma_f32_16x16x32_bf16 v[4:7], v[170:173], v[214:217], v[4:7]
	v_mfma_f32_16x16x32_bf16 v[0:3], v[178:181], v[214:217], v[0:3]
	s_setprio 0
	s_barrier
	ds_read_b128 v[128:131], v160
	ds_read_b128 v[132:135], v160 offset:1024
	ds_read_b128 v[148:151], v160 offset:2048
	ds_read_b128 v[162:165], v160 offset:3072
	ds_read_b128 v[166:169], v161
	ds_read_b128 v[170:173], v161 offset:1024
	ds_read_b128 v[174:177], v161 offset:2048
	ds_read_b128 v[178:181], v161 offset:3072
	s_add_u32 s60, s60, 0xb0000
	s_addc_u32 s61, s61, 0
	s_mov_b32 m0, s30
	v_lshl_add_u64 v[222:223], s[60:61], 0, v[136:137]
	ds_read_b128 v[182:185], v158 offset:32768
	ds_read_b128 v[186:189], v158 offset:33792
	ds_read_b128 v[190:193], v158 offset:34816
	ds_read_b128 v[194:197], v158 offset:35840
	ds_read_b128 v[202:205], v158 offset:36864
	ds_read_b128 v[206:209], v158 offset:37888
	ds_read_b128 v[210:213], v158 offset:38912
	ds_read_b128 v[214:217], v158 offset:39936
	global_load_lds_dwordx4 v[222:223], off
	v_lshl_add_u64 v[222:223], s[60:61], 0, v[140:141]
	s_mov_b32 m0, s31
	s_nop 0
	global_load_lds_dwordx4 v[222:223], off
	s_waitcnt vmcnt(8)
	s_waitcnt lgkmcnt(0)
	s_barrier
	s_setprio 1
	s_waitcnt lgkmcnt(0)
	v_mfma_f32_16x16x32_bf16 v[124:127], v[128:131], v[182:185], v[124:127]
	v_mfma_f32_16x16x32_bf16 v[120:123], v[148:151], v[182:185], v[120:123]
	v_mfma_f32_16x16x32_bf16 v[108:111], v[128:131], v[190:193], v[108:111]
	v_mfma_f32_16x16x32_bf16 v[104:107], v[148:151], v[190:193], v[104:107]
	v_mfma_f32_16x16x32_bf16 v[92:95], v[128:131], v[202:205], v[92:95]
	v_mfma_f32_16x16x32_bf16 v[88:91], v[148:151], v[202:205], v[88:91]
	v_mfma_f32_16x16x32_bf16 v[76:79], v[128:131], v[210:213], v[76:79]
	v_mfma_f32_16x16x32_bf16 v[72:75], v[148:151], v[210:213], v[72:75]
	v_mfma_f32_16x16x32_bf16 v[124:127], v[132:135], v[186:189], v[124:127]
	v_mfma_f32_16x16x32_bf16 v[120:123], v[162:165], v[186:189], v[120:123]
	v_mfma_f32_16x16x32_bf16 v[108:111], v[132:135], v[194:197], v[108:111]
	v_mfma_f32_16x16x32_bf16 v[104:107], v[162:165], v[194:197], v[104:107]
	v_mfma_f32_16x16x32_bf16 v[92:95], v[132:135], v[206:209], v[92:95]
	v_mfma_f32_16x16x32_bf16 v[88:91], v[162:165], v[206:209], v[88:91]
	v_mfma_f32_16x16x32_bf16 v[76:79], v[132:135], v[214:217], v[76:79]
	v_mfma_f32_16x16x32_bf16 v[72:75], v[162:165], v[214:217], v[72:75]
	s_setprio 0
	s_setprio 1
	v_mfma_f32_16x16x32_bf16 v[116:119], v[166:169], v[182:185], v[116:119]
	v_mfma_f32_16x16x32_bf16 v[112:115], v[174:177], v[182:185], v[112:115]
	v_mfma_f32_16x16x32_bf16 v[100:103], v[166:169], v[190:193], v[100:103]
	v_mfma_f32_16x16x32_bf16 v[96:99], v[174:177], v[190:193], v[96:99]
	v_mfma_f32_16x16x32_bf16 v[84:87], v[166:169], v[202:205], v[84:87]
	v_mfma_f32_16x16x32_bf16 v[80:83], v[174:177], v[202:205], v[80:83]
	v_mfma_f32_16x16x32_bf16 v[68:71], v[166:169], v[210:213], v[68:71]
	v_mfma_f32_16x16x32_bf16 v[64:67], v[174:177], v[210:213], v[64:67]
	v_mfma_f32_16x16x32_bf16 v[116:119], v[170:173], v[186:189], v[116:119]
	v_mfma_f32_16x16x32_bf16 v[112:115], v[178:181], v[186:189], v[112:115]
	v_mfma_f32_16x16x32_bf16 v[100:103], v[170:173], v[194:197], v[100:103]
	v_mfma_f32_16x16x32_bf16 v[96:99], v[178:181], v[194:197], v[96:99]
	v_mfma_f32_16x16x32_bf16 v[84:87], v[170:173], v[206:209], v[84:87]
	v_mfma_f32_16x16x32_bf16 v[80:83], v[178:181], v[206:209], v[80:83]
	v_mfma_f32_16x16x32_bf16 v[68:71], v[170:173], v[214:217], v[68:71]
	v_mfma_f32_16x16x32_bf16 v[64:67], v[178:181], v[214:217], v[64:67]
	s_setprio 0
	s_barrier
; #define PG8_STAGE(bufoff, gbase, voff) do { _Pragma("unroll") for (int _i = 0; _i < 2; ++_i) \
;         __builtin_amdgcn_global_load_lds((const unsigned*)((const char*)(gbase) + (voff)[_i]), (PG8_LAS unsigned*)(lds + (bufoff) + ldsw + _i * 8192), 16, 0, 0); } while (0)
; #define PG8_LDA(dst, b, h) do { _Pragma("unroll") for (int m = 0; m < 4; ++m) _Pragma("unroll") for (int k = 0; k < 2; ++k) dst[m][k] = *(const PG8_LAS bf16x8*)(lds + PG8_SA(b, h) + aoff + m * 2048 + k * 1024); } while (0)
; #define PG8_MMA(ai, bj, At, Bt) do { __builtin_amdgcn_s_setprio(1); _Pragma("unroll") for (int m = 0; m < 4; ++m) _Pragma("unroll") for (int n = 0; n < 2; ++n) _Pragma("unroll") for (int k = 0; k < 2; ++k) \
;         acc[ai][bj][m][n] = __builtin_amdgcn_mfma_f32_16x16x32_bf16(Bt[n][k], At[m][k], acc[ai][bj][m][n], 0, 0, 0); __builtin_amdgcn_s_setprio(0); } while (0)
; #define PG8_WAIT_V(n) asm volatile("s_waitcnt vmcnt(" #n ")" ::: "memory")
; #define PG8_WAIT_L(n) asm volatile("s_waitcnt lgkmcnt(" #n ")" ::: "memory")
; #define PG8_BAR __builtin_amdgcn_s_barrier()
; #define PG8_SCHED __builtin_amdgcn_sched_barrier(0)
; template <class Epi, class Sched, bool ALIGN_EPI = false, bool SP2 = false>
; __device__ __forceinline__ void gemm_phase(PG8_LAS unsigned char* lds, const Gemm g, const Sched& S, const Epi& E) {
;     ...
;             PG8_LDA(At, 1, 1); PG8_STAGE(PG8_SB(1, 0), b3, voffB); PG8_STAGE(PG8_SB(1, 1), b3 + hstep, voffB); PG8_STAGE(PG8_SA(1, 0), a3, voffA);
;             PG8_WAIT_V(8); PG8_WAIT_L(0); PG8_BAR; PG8_MMA(1, 0, At, B0); PG8_MMA(1, 1, At, B1); PG8_BAR; PG8_SCHED;
	s_add_i32 s60, s77, s21
	v_lshl_add_u64 v[152:153], v[152:153], 0, s[40:41]
	s_mov_b32 m0, s60
	ds_read_b128 v[182:185], v158 offset:49152
	ds_read_b128 v[186:189], v158 offset:50176
	ds_read_b128 v[190:193], v158 offset:51200
	ds_read_b128 v[194:197], v158 offset:52224
	ds_read_b128 v[202:205], v158 offset:53248
	ds_read_b128 v[206:209], v158 offset:54272
	ds_read_b128 v[210:213], v158 offset:55296
	ds_read_b128 v[214:217], v158 offset:56320
	global_load_lds_dwordx4 v[152:153], off
	s_add_i32 m0, s60, 0x2000
	s_add_u32 s58, s58, 0xb0080
	v_lshl_add_u64 v[152:153], v[198:199], 0, s[40:41]
	s_addc_u32 s59, s59, 0
	s_add_i32 s60, s78, s21
	global_load_lds_dwordx4 v[152:153], off
	v_lshl_add_u64 v[152:153], s[58:59], 0, v[138:139]
	s_mov_b32 m0, s60
	s_nop 0
	global_load_lds_dwordx4 v[152:153], off
	v_lshl_add_u64 v[152:153], s[58:59], 0, v[142:143]
	s_add_i32 m0, s60, 0x2000
	s_nop 0
	global_load_lds_dwordx4 v[152:153], off
	v_lshl_add_u64 v[152:153], v[218:219], 0, s[40:41]
	s_mov_b32 m0, s64
	s_nop 0
	global_load_lds_dwordx4 v[152:153], off
	v_lshl_add_u64 v[152:153], v[220:221], 0, s[40:41]
	s_mov_b32 m0, s65
	s_nop 0
	global_load_lds_dwordx4 v[152:153], off
	s_waitcnt vmcnt(8)
	s_waitcnt lgkmcnt(0)
	s_barrier
	s_setprio 1
	s_waitcnt lgkmcnt(0)
	v_mfma_f32_16x16x32_bf16 v[60:63], v[128:131], v[182:185], v[60:63]
	v_mfma_f32_16x16x32_bf16 v[56:59], v[148:151], v[182:185], v[56:59]
	v_mfma_f32_16x16x32_bf16 v[44:47], v[128:131], v[190:193], v[44:47]
	v_mfma_f32_16x16x32_bf16 v[40:43], v[148:151], v[190:193], v[40:43]
	v_mfma_f32_16x16x32_bf16 v[32:35], v[128:131], v[202:205], v[32:35]
	v_mfma_f32_16x16x32_bf16 v[24:27], v[148:151], v[202:205], v[24:27]
	v_mfma_f32_16x16x32_bf16 v[16:19], v[128:131], v[210:213], v[16:19]
	v_mfma_f32_16x16x32_bf16 v[8:11], v[148:151], v[210:213], v[8:11]
	v_mfma_f32_16x16x32_bf16 v[60:63], v[132:135], v[186:189], v[60:63]
	v_mfma_f32_16x16x32_bf16 v[56:59], v[162:165], v[186:189], v[56:59]
	v_mfma_f32_16x16x32_bf16 v[44:47], v[132:135], v[194:197], v[44:47]
	v_mfma_f32_16x16x32_bf16 v[40:43], v[162:165], v[194:197], v[40:43]
	v_mfma_f32_16x16x32_bf16 v[32:35], v[132:135], v[206:209], v[32:35]
	v_mfma_f32_16x16x32_bf16 v[24:27], v[162:165], v[206:209], v[24:27]
	v_mfma_f32_16x16x32_bf16 v[16:19], v[132:135], v[214:217], v[16:19]
	v_mfma_f32_16x16x32_bf16 v[8:11], v[162:165], v[214:217], v[8:11]
	s_setprio 0
	s_setprio 1
	v_mfma_f32_16x16x32_bf16 v[52:55], v[166:169], v[182:185], v[52:55]
	v_mfma_f32_16x16x32_bf16 v[48:51], v[174:177], v[182:185], v[48:51]
	v_mfma_f32_16x16x32_bf16 v[36:39], v[166:169], v[190:193], v[36:39]
	v_mfma_f32_16x16x32_bf16 v[28:31], v[174:177], v[190:193], v[28:31]
	v_mfma_f32_16x16x32_bf16 v[20:23], v[166:169], v[202:205], v[20:23]
	v_mfma_f32_16x16x32_bf16 v[12:15], v[174:177], v[202:205], v[12:15]
	v_mfma_f32_16x16x32_bf16 v[4:7], v[166:169], v[210:213], v[4:7]
	v_mfma_f32_16x16x32_bf16 v[0:3], v[174:177], v[210:213], v[0:3]
	v_mfma_f32_16x16x32_bf16 v[52:55], v[170:173], v[186:189], v[52:55]
	v_mfma_f32_16x16x32_bf16 v[48:51], v[178:181], v[186:189], v[48:51]
	v_mfma_f32_16x16x32_bf16 v[36:39], v[170:173], v[194:197], v[36:39]
	v_mfma_f32_16x16x32_bf16 v[28:31], v[178:181], v[194:197], v[28:31]
	v_mfma_f32_16x16x32_bf16 v[20:23], v[170:173], v[206:209], v[20:23]
	v_mfma_f32_16x16x32_bf16 v[12:15], v[178:181], v[206:209], v[12:15]
	v_mfma_f32_16x16x32_bf16 v[4:7], v[170:173], v[214:217], v[4:7]
	v_mfma_f32_16x16x32_bf16 v[0:3], v[178:181], v[214:217], v[0:3]
	s_setprio 0
	s_add_i32 s85, s85, 2
	s_add_u32 s56, s56, 0x100
	s_addc_u32 s57, s57, 0
	s_add_u32 s83, s83, 0x100
	s_addc_u32 s84, s84, 0
	s_barrier
	s_cmp_gt_u32 s85, 41
	s_cbranch_scc0 .LBB0_245
	s_and_b64 vcc, exec, s[44:45]
	s_cbranch_vccz .LBB0_248
	s_barrier

; #define PG8_STAGE(bufoff, gbase, voff) do { _Pragma("unroll") for (int _i = 0; _i < 2; ++_i) \
;         __builtin_amdgcn_global_load_lds((const unsigned*)((const char*)(gbase) + (voff)[_i]), (PG8_LAS unsigned*)(lds + (bufoff) + ldsw + _i * 8192), 16, 0, 0); } while (0)
; #define PG8_LDA(dst, b, h) do { _Pragma("unroll") for (int m = 0; m < 4; ++m) _Pragma("unroll") for (int k = 0; k < 2; ++k) dst[m][k] = *(const PG8_LAS bf16x8*)(lds + PG8_SA(b, h) + aoff + m * 2048 + k * 1024); } while (0)
; #define PG8_LDB(dst, b, h) do { _Pragma("unroll") for (int n = 0; n < 2; ++n) _Pragma("unroll") for (int k = 0; k < 2; ++k) dst[n][k] = *(const PG8_LAS bf16x8*)(lds + PG8_SB(b, h) + boff + n * 2048 + k * 1024); } while (0)
; #define PG8_MMA(ai, bj, At, Bt) do { __builtin_amdgcn_s_setprio(1); _Pragma("unroll") for (int m = 0; m < 4; ++m) _Pragma("unroll") for (int n = 0; n < 2; ++n) _Pragma("unroll") for (int k = 0; k < 2; ++k) \
;         acc[ai][bj][m][n] = __builtin_amdgcn_mfma_f32_16x16x32_bf16(Bt[n][k], At[m][k], acc[ai][bj][m][n], 0, 0, 0); __builtin_amdgcn_s_setprio(0); } while (0)
; #define PG8_WAIT_V(n) asm volatile("s_waitcnt vmcnt(" #n ")" ::: "memory")
; #define PG8_WAIT_L(n) asm volatile("s_waitcnt lgkmcnt(" #n ")" ::: "memory")
; #define PG8_BAR __builtin_amdgcn_s_barrier()
; #define PG8_SCHED __builtin_amdgcn_sched_barrier(0)
; template <class Epi, class Sched, bool ALIGN_EPI = false, bool SP2 = false>
; __device__ __forceinline__ void gemm_phase(PG8_LAS unsigned char* lds, const Gemm g, const Sched& S, const Epi& E) {
;     ...
;             PG8_LDB(B0, 0, 0); PG8_LDB(B1, 0, 1); PG8_SCHED; PG8_LDA(At, 0, 0); PG8_STAGE(PG8_SA(1, 1), a1 + hstep, voffA);
;             PG8_WAIT_V(8); PG8_WAIT_L(0); PG8_BAR; PG8_MMA(0, 0, At, B0); PG8_MMA(0, 1, At, B1); PG8_BAR; PG8_SCHED;
;             PG8_LDA(At, 0, 1); PG8_STAGE(PG8_SB(0, 0), b2, voffB); PG8_STAGE(PG8_SB(0, 1), b2 + hstep, voffB); PG8_STAGE(PG8_SA(0, 0), a2, voffA);
;             PG8_WAIT_V(8); PG8_WAIT_L(0); PG8_BAR; PG8_MMA(1, 0, At, B0); PG8_MMA(1, 1, At, B1); PG8_BAR; PG8_SCHED;
.LBB0_325:
	ds_read_b128 v[140:143], v162
	ds_read_b128 v[144:147], v162 offset:1024
	ds_read_b128 v[148:151], v162 offset:2048
	ds_read_b128 v[152:155], v162 offset:3072
	ds_read_b128 v[168:171], v163
	ds_read_b128 v[172:175], v163 offset:1024
	ds_read_b128 v[176:179], v163 offset:2048
	ds_read_b128 v[180:183], v163 offset:3072
	s_add_u32 s74, s72, 0xfffc0080
	s_addc_u32 s75, s73, -1
	s_cmp_eq_u32 s84, 12
	s_cselect_b32 s77, s5, s75
	s_cselect_b32 s76, s61, s74
	s_cselect_b32 s75, s63, s83
	s_cselect_b32 s74, s71, s82
	v_lshl_add_u64 v[156:157], s[72:73], 0, v[136:137]
	s_add_i32 m0, s28, 0xc000
	ds_read_b128 v[184:187], v164
	ds_read_b128 v[188:191], v164 offset:1024
	ds_read_b128 v[192:195], v164 offset:2048
	ds_read_b128 v[196:199], v164 offset:3072
	ds_read_b128 v[202:205], v164 offset:4096
	ds_read_b128 v[206:209], v164 offset:5120
	ds_read_b128 v[210:213], v164 offset:6144
	ds_read_b128 v[214:217], v164 offset:7168
	global_load_lds_dwordx4 v[156:157], off
	v_lshl_add_u64 v[156:157], s[72:73], 0, v[138:139]
	s_add_i32 m0, s28, 0xe000
	s_nop 0
	global_load_lds_dwordx4 v[156:157], off
	s_waitcnt vmcnt(8)
	s_waitcnt lgkmcnt(0)
	s_barrier
	s_setprio 1
	s_waitcnt lgkmcnt(0)
	v_mfma_f32_16x16x32_bf16 v[124:127], v[140:143], v[184:187], v[124:127]
	v_mfma_f32_16x16x32_bf16 v[120:123], v[148:151], v[184:187], v[120:123]
	v_mfma_f32_16x16x32_bf16 v[108:111], v[140:143], v[192:195], v[108:111]
	v_mfma_f32_16x16x32_bf16 v[104:107], v[148:151], v[192:195], v[104:107]
	v_mfma_f32_16x16x32_bf16 v[92:95], v[140:143], v[202:205], v[92:95]
	v_mfma_f32_16x16x32_bf16 v[88:91], v[148:151], v[202:205], v[88:91]
	v_mfma_f32_16x16x32_bf16 v[76:79], v[140:143], v[210:213], v[76:79]
	v_mfma_f32_16x16x32_bf16 v[72:75], v[148:151], v[210:213], v[72:75]
	v_mfma_f32_16x16x32_bf16 v[124:127], v[144:147], v[188:191], v[124:127]
	v_mfma_f32_16x16x32_bf16 v[120:123], v[152:155], v[188:191], v[120:123]
	v_mfma_f32_16x16x32_bf16 v[108:111], v[144:147], v[196:199], v[108:111]
	v_mfma_f32_16x16x32_bf16 v[104:107], v[152:155], v[196:199], v[104:107]
	v_mfma_f32_16x16x32_bf16 v[92:95], v[144:147], v[206:209], v[92:95]
	v_mfma_f32_16x16x32_bf16 v[88:91], v[152:155], v[206:209], v[88:91]
	v_mfma_f32_16x16x32_bf16 v[76:79], v[144:147], v[214:217], v[76:79]
	v_mfma_f32_16x16x32_bf16 v[72:75], v[152:155], v[214:217], v[72:75]
	s_setprio 0
	s_setprio 1
	v_mfma_f32_16x16x32_bf16 v[116:119], v[168:171], v[184:187], v[116:119]
	v_mfma_f32_16x16x32_bf16 v[112:115], v[176:179], v[184:187], v[112:115]
	v_mfma_f32_16x16x32_bf16 v[100:103], v[168:171], v[192:195], v[100:103]
	v_mfma_f32_16x16x32_bf16 v[96:99], v[176:179], v[192:195], v[96:99]
	v_mfma_f32_16x16x32_bf16 v[84:87], v[168:171], v[202:205], v[84:87]
	v_mfma_f32_16x16x32_bf16 v[80:83], v[176:179], v[202:205], v[80:83]
	v_mfma_f32_16x16x32_bf16 v[68:71], v[168:171], v[210:213], v[68:71]
	v_mfma_f32_16x16x32_bf16 v[64:67], v[176:179], v[210:213], v[64:67]
	v_mfma_f32_16x16x32_bf16 v[116:119], v[172:175], v[188:191], v[116:119]
	v_mfma_f32_16x16x32_bf16 v[112:115], v[180:183], v[188:191], v[112:115]
	v_mfma_f32_16x16x32_bf16 v[100:103], v[172:175], v[196:199], v[100:103]
	v_mfma_f32_16x16x32_bf16 v[96:99], v[180:183], v[196:199], v[96:99]
	v_mfma_f32_16x16x32_bf16 v[84:87], v[172:175], v[206:209], v[84:87]
	v_mfma_f32_16x16x32_bf16 v[80:83], v[180:183], v[206:209], v[80:83]
	v_mfma_f32_16x16x32_bf16 v[68:71], v[172:175], v[214:217], v[68:71]
	v_mfma_f32_16x16x32_bf16 v[64:67], v[180:183], v[214:217], v[64:67]
	s_setprio 0
	s_barrier
	s_add_i32 s85, s79, s21
	v_lshl_add_u64 v[156:157], s[74:75], 0, v[130:131]
	s_mov_b32 m0, s85
	ds_read_b128 v[184:187], v164 offset:16384
	ds_read_b128 v[188:191], v164 offset:17408
	ds_read_b128 v[192:195], v164 offset:18432
	ds_read_b128 v[196:199], v164 offset:19456
	ds_read_b128 v[202:205], v164 offset:20480
	ds_read_b128 v[206:209], v164 offset:21504
	ds_read_b128 v[210:213], v164 offset:22528
	ds_read_b128 v[214:217], v164 offset:23552
	global_load_lds_dwordx4 v[156:157], off
	s_add_i32 m0, s85, 0x2000
	s_add_u32 s86, s74, 0x40000
	v_lshl_add_u64 v[218:219], s[74:75], 0, v[134:135]
	s_addc_u32 s87, s75, 0
	s_add_i32 s85, s80, s21
	global_load_lds_dwordx4 v[218:219], off
	v_lshl_add_u64 v[220:221], s[86:87], 0, v[130:131]
	s_mov_b32 m0, s85
	v_lshl_add_u64 v[222:223], s[76:77], 0, v[132:133]
	global_load_lds_dwordx4 v[220:221], off
	v_lshl_add_u64 v[220:221], s[86:87], 0, v[134:135]
	s_add_i32 m0, s85, 0x2000
	s_nop 0
	global_load_lds_dwordx4 v[220:221], off
	v_lshl_add_u64 v[220:221], s[76:77], 0, v[128:129]
	s_mov_b32 m0, s28
	s_nop 0
	global_load_lds_dwordx4 v[220:221], off
	s_mov_b32 m0, s29
	s_nop 0
	global_load_lds_dwordx4 v[222:223], off
	s_waitcnt vmcnt(8)
	s_waitcnt lgkmcnt(0)
	s_barrier
; #define PG8_STAGE(bufoff, gbase, voff) do { _Pragma("unroll") for (int _i = 0; _i < 2; ++_i) \
;         __builtin_amdgcn_global_load_lds((const unsigned*)((const char*)(gbase) + (voff)[_i]), (PG8_LAS unsigned*)(lds + (bufoff) + ldsw + _i * 8192), 16, 0, 0); } while (0)
; #define PG8_LDA(dst, b, h) do { _Pragma("unroll") for (int m = 0; m < 4; ++m) _Pragma("unroll") for (int k = 0; k < 2; ++k) dst[m][k] = *(const PG8_LAS bf16x8*)(lds + PG8_SA(b, h) + aoff + m * 2048 + k * 1024); } while (0)
; #define PG8_LDB(dst, b, h) do { _Pragma("unroll") for (int n = 0; n < 2; ++n) _Pragma("unroll") for (int k = 0; k < 2; ++k) dst[n][k] = *(const PG8_LAS bf16x8*)(lds + PG8_SB(b, h) + boff + n * 2048 + k * 1024); } while (0)
; #define PG8_MMA(ai, bj, At, Bt) do { __builtin_amdgcn_s_setprio(1); _Pragma("unroll") for (int m = 0; m < 4; ++m) _Pragma("unroll") for (int n = 0; n < 2; ++n) _Pragma("unroll") for (int k = 0; k < 2; ++k) \
;         acc[ai][bj][m][n] = __builtin_amdgcn_mfma_f32_16x16x32_bf16(Bt[n][k], At[m][k], acc[ai][bj][m][n], 0, 0, 0); __builtin_amdgcn_s_setprio(0); } while (0)
; #define PG8_WAIT_V(n) asm volatile("s_waitcnt vmcnt(" #n ")" ::: "memory")
; #define PG8_WAIT_L(n) asm volatile("s_waitcnt lgkmcnt(" #n ")" ::: "memory")
; #define PG8_BAR __builtin_amdgcn_s_barrier()
; #define PG8_SCHED __builtin_amdgcn_sched_barrier(0)
; template <class Epi, class Sched, bool ALIGN_EPI = false, bool SP2 = false>
; __device__ __forceinline__ void gemm_phase(PG8_LAS unsigned char* lds, const Gemm g, const Sched& S, const Epi& E) {
;     ...
;             PG8_WAIT_V(8); PG8_WAIT_L(0); PG8_BAR; PG8_MMA(1, 0, At, B0); PG8_MMA(1, 1, At, B1); PG8_BAR; PG8_SCHED;
;             PG8_LDB(B0, 1, 0); PG8_LDB(B1, 1, 1); PG8_SCHED; PG8_LDA(At, 1, 0); PG8_STAGE(PG8_SA(0, 1), a2 + hstep, voffA);
;             PG8_WAIT_V(8); PG8_WAIT_L(0); PG8_BAR; PG8_MMA(0, 0, At, B0); PG8_MMA(0, 1, At, B1); PG8_BAR; PG8_SCHED;
	s_setprio 1
	s_waitcnt lgkmcnt(0)
	v_mfma_f32_16x16x32_bf16 v[60:63], v[140:143], v[184:187], v[60:63]
	v_mfma_f32_16x16x32_bf16 v[56:59], v[148:151], v[184:187], v[56:59]
	v_mfma_f32_16x16x32_bf16 v[44:47], v[140:143], v[192:195], v[44:47]
	v_mfma_f32_16x16x32_bf16 v[40:43], v[148:151], v[192:195], v[40:43]
	v_mfma_f32_16x16x32_bf16 v[28:31], v[140:143], v[202:205], v[28:31]
	v_mfma_f32_16x16x32_bf16 v[24:27], v[148:151], v[202:205], v[24:27]
	v_mfma_f32_16x16x32_bf16 v[12:15], v[140:143], v[210:213], v[12:15]
	v_mfma_f32_16x16x32_bf16 v[8:11], v[148:151], v[210:213], v[8:11]
	v_mfma_f32_16x16x32_bf16 v[60:63], v[144:147], v[188:191], v[60:63]
	v_mfma_f32_16x16x32_bf16 v[56:59], v[152:155], v[188:191], v[56:59]
	v_mfma_f32_16x16x32_bf16 v[44:47], v[144:147], v[196:199], v[44:47]
	v_mfma_f32_16x16x32_bf16 v[40:43], v[152:155], v[196:199], v[40:43]
	v_mfma_f32_16x16x32_bf16 v[28:31], v[144:147], v[206:209], v[28:31]
	v_mfma_f32_16x16x32_bf16 v[24:27], v[152:155], v[206:209], v[24:27]
	v_mfma_f32_16x16x32_bf16 v[12:15], v[144:147], v[214:217], v[12:15]
	v_mfma_f32_16x16x32_bf16 v[8:11], v[152:155], v[214:217], v[8:11]
	s_setprio 0
	s_setprio 1
	v_mfma_f32_16x16x32_bf16 v[52:55], v[168:171], v[184:187], v[52:55]
	v_mfma_f32_16x16x32_bf16 v[48:51], v[176:179], v[184:187], v[48:51]
	v_mfma_f32_16x16x32_bf16 v[36:39], v[168:171], v[192:195], v[36:39]
	v_mfma_f32_16x16x32_bf16 v[32:35], v[176:179], v[192:195], v[32:35]
	v_mfma_f32_16x16x32_bf16 v[20:23], v[168:171], v[202:205], v[20:23]
	v_mfma_f32_16x16x32_bf16 v[16:19], v[176:179], v[202:205], v[16:19]
	v_mfma_f32_16x16x32_bf16 v[4:7], v[168:171], v[210:213], v[4:7]
	v_mfma_f32_16x16x32_bf16 v[0:3], v[176:179], v[210:213], v[0:3]
	v_mfma_f32_16x16x32_bf16 v[52:55], v[172:175], v[188:191], v[52:55]
	v_mfma_f32_16x16x32_bf16 v[48:51], v[180:183], v[188:191], v[48:51]
	v_mfma_f32_16x16x32_bf16 v[36:39], v[172:175], v[196:199], v[36:39]
	v_mfma_f32_16x16x32_bf16 v[32:35], v[180:183], v[196:199], v[32:35]
	v_mfma_f32_16x16x32_bf16 v[20:23], v[172:175], v[206:209], v[20:23]
	v_mfma_f32_16x16x32_bf16 v[16:19], v[180:183], v[206:209], v[16:19]
	v_mfma_f32_16x16x32_bf16 v[4:7], v[172:175], v[214:217], v[4:7]
	v_mfma_f32_16x16x32_bf16 v[0:3], v[180:183], v[214:217], v[0:3]
	s_setprio 0
	s_barrier
	s_add_i32 s85, 0, 0x18000
	s_add_i32 s86, 0, 0x1c000
	v_add_u32_e32 v152, s85, v160
	v_add_u32_e32 v167, s86, v160
	ds_read_b128 v[140:143], v152
	ds_read_b128 v[144:147], v152 offset:1024
	ds_read_b128 v[148:151], v152 offset:2048
	ds_read_b128 v[152:155], v152 offset:3072
	ds_read_b128 v[168:171], v167
	ds_read_b128 v[172:175], v167 offset:1024
	ds_read_b128 v[176:179], v167 offset:2048
	ds_read_b128 v[180:183], v167 offset:3072
	s_add_u32 s76, s76, 0x40000
	s_addc_u32 s77, s77, 0
	s_mov_b32 m0, s30
	v_lshl_add_u64 v[224:225], s[76:77], 0, v[128:129]
	ds_read_b128 v[184:187], v164 offset:32768
	ds_read_b128 v[188:191], v164 offset:33792
	ds_read_b128 v[192:195], v164 offset:34816
	ds_read_b128 v[196:199], v164 offset:35840
	ds_read_b128 v[202:205], v164 offset:36864
	ds_read_b128 v[206:209], v164 offset:37888
	ds_read_b128 v[210:213], v164 offset:38912
	ds_read_b128 v[214:217], v164 offset:39936
	global_load_lds_dwordx4 v[224:225], off
	v_lshl_add_u64 v[224:225], s[76:77], 0, v[132:133]
	s_mov_b32 m0, s31
	s_nop 0
	global_load_lds_dwordx4 v[224:225], off
	s_waitcnt vmcnt(8)
	s_waitcnt lgkmcnt(0)
	s_barrier
	s_setprio 1
	s_waitcnt lgkmcnt(0)
	v_mfma_f32_16x16x32_bf16 v[124:127], v[140:143], v[184:187], v[124:127]
	v_mfma_f32_16x16x32_bf16 v[120:123], v[148:151], v[184:187], v[120:123]
	v_mfma_f32_16x16x32_bf16 v[108:111], v[140:143], v[192:195], v[108:111]
	v_mfma_f32_16x16x32_bf16 v[104:107], v[148:151], v[192:195], v[104:107]
	v_mfma_f32_16x16x32_bf16 v[92:95], v[140:143], v[202:205], v[92:95]
	v_mfma_f32_16x16x32_bf16 v[88:91], v[148:151], v[202:205], v[88:91]
	v_mfma_f32_16x16x32_bf16 v[76:79], v[140:143], v[210:213], v[76:79]
	v_mfma_f32_16x16x32_bf16 v[72:75], v[148:151], v[210:213], v[72:75]
	v_mfma_f32_16x16x32_bf16 v[124:127], v[144:147], v[188:191], v[124:127]
	v_mfma_f32_16x16x32_bf16 v[120:123], v[152:155], v[188:191], v[120:123]
	v_mfma_f32_16x16x32_bf16 v[108:111], v[144:147], v[196:199], v[108:111]
	v_mfma_f32_16x16x32_bf16 v[104:107], v[152:155], v[196:199], v[104:107]
	v_mfma_f32_16x16x32_bf16 v[92:95], v[144:147], v[206:209], v[92:95]
	v_mfma_f32_16x16x32_bf16 v[88:91], v[152:155], v[206:209], v[88:91]
	v_mfma_f32_16x16x32_bf16 v[76:79], v[144:147], v[214:217], v[76:79]
	v_mfma_f32_16x16x32_bf16 v[72:75], v[152:155], v[214:217], v[72:75]
	s_setprio 0
	s_setprio 1
	v_mfma_f32_16x16x32_bf16 v[116:119], v[168:171], v[184:187], v[116:119]
	v_mfma_f32_16x16x32_bf16 v[112:115], v[176:179], v[184:187], v[112:115]
	v_mfma_f32_16x16x32_bf16 v[100:103], v[168:171], v[192:195], v[100:103]
	v_mfma_f32_16x16x32_bf16 v[96:99], v[176:179], v[192:195], v[96:99]
	v_mfma_f32_16x16x32_bf16 v[84:87], v[168:171], v[202:205], v[84:87]
	v_mfma_f32_16x16x32_bf16 v[80:83], v[176:179], v[202:205], v[80:83]
	v_mfma_f32_16x16x32_bf16 v[68:71], v[168:171], v[210:213], v[68:71]
	v_mfma_f32_16x16x32_bf16 v[64:67], v[176:179], v[210:213], v[64:67]
	v_mfma_f32_16x16x32_bf16 v[116:119], v[172:175], v[188:191], v[116:119]
	v_mfma_f32_16x16x32_bf16 v[112:115], v[180:183], v[188:191], v[112:115]
	v_mfma_f32_16x16x32_bf16 v[100:103], v[172:175], v[196:199], v[100:103]
	v_mfma_f32_16x16x32_bf16 v[96:99], v[180:183], v[196:199], v[96:99]
	v_mfma_f32_16x16x32_bf16 v[84:87], v[172:175], v[206:209], v[84:87]
	v_mfma_f32_16x16x32_bf16 v[80:83], v[180:183], v[206:209], v[80:83]
	v_mfma_f32_16x16x32_bf16 v[68:71], v[172:175], v[214:217], v[68:71]
	v_mfma_f32_16x16x32_bf16 v[64:67], v[180:183], v[214:217], v[64:67]
	s_setprio 0
	s_barrier
; #define PG8_STAGE(bufoff, gbase, voff) do { _Pragma("unroll") for (int _i = 0; _i < 2; ++_i) \
;         __builtin_amdgcn_global_load_lds((const unsigned*)((const char*)(gbase) + (voff)[_i]), (PG8_LAS unsigned*)(lds + (bufoff) + ldsw + _i * 8192), 16, 0, 0); } while (0)
; #define PG8_LDA(dst, b, h) do { _Pragma("unroll") for (int m = 0; m < 4; ++m) _Pragma("unroll") for (int k = 0; k < 2; ++k) dst[m][k] = *(const PG8_LAS bf16x8*)(lds + PG8_SA(b, h) + aoff + m * 2048 + k * 1024); } while (0)
; #define PG8_MMA(ai, bj, At, Bt) do { __builtin_amdgcn_s_setprio(1); _Pragma("unroll") for (int m = 0; m < 4; ++m) _Pragma("unroll") for (int n = 0; n < 2; ++n) _Pragma("unroll") for (int k = 0; k < 2; ++k) \
;         acc[ai][bj][m][n] = __builtin_amdgcn_mfma_f32_16x16x32_bf16(Bt[n][k], At[m][k], acc[ai][bj][m][n], 0, 0, 0); __builtin_amdgcn_s_setprio(0); } while (0)
; #define PG8_WAIT_V(n) asm volatile("s_waitcnt vmcnt(" #n ")" ::: "memory")
; #define PG8_WAIT_L(n) asm volatile("s_waitcnt lgkmcnt(" #n ")" ::: "memory")
; #define PG8_BAR __builtin_amdgcn_s_barrier()
; #define PG8_SCHED __builtin_amdgcn_sched_barrier(0)
; template <class Epi, class Sched, bool ALIGN_EPI = false, bool SP2 = false>
; __device__ __forceinline__ void gemm_phase(PG8_LAS unsigned char* lds, const Gemm g, const Sched& S, const Epi& E) {
;     ...
;             PG8_LDA(At, 1, 1); PG8_STAGE(PG8_SB(1, 0), b3, voffB); PG8_STAGE(PG8_SB(1, 1), b3 + hstep, voffB); PG8_STAGE(PG8_SA(1, 0), a3, voffA);
;             PG8_WAIT_V(8); PG8_WAIT_L(0); PG8_BAR; PG8_MMA(1, 0, At, B0); PG8_MMA(1, 1, At, B1); PG8_BAR; PG8_SCHED;
	s_add_i32 s76, s85, s21
	v_lshl_add_u64 v[156:157], v[156:157], 0, s[56:57]
	s_mov_b32 m0, s76
	ds_read_b128 v[184:187], v164 offset:49152
	ds_read_b128 v[188:191], v164 offset:50176
	ds_read_b128 v[192:195], v164 offset:51200
	ds_read_b128 v[196:199], v164 offset:52224
	ds_read_b128 v[202:205], v164 offset:53248
	ds_read_b128 v[206:209], v164 offset:54272
	ds_read_b128 v[210:213], v164 offset:55296
	ds_read_b128 v[214:217], v164 offset:56320
	global_load_lds_dwordx4 v[156:157], off
	s_add_i32 m0, s76, 0x2000
	s_add_u32 s74, s74, 0x40080
	v_lshl_add_u64 v[156:157], v[218:219], 0, s[56:57]
	s_addc_u32 s75, s75, 0
	s_add_i32 s76, s86, s21
	global_load_lds_dwordx4 v[156:157], off
	v_lshl_add_u64 v[156:157], s[74:75], 0, v[130:131]
	s_mov_b32 m0, s76
	s_nop 0
	global_load_lds_dwordx4 v[156:157], off
	v_lshl_add_u64 v[156:157], s[74:75], 0, v[134:135]
	s_add_i32 m0, s76, 0x2000
	s_nop 0
	global_load_lds_dwordx4 v[156:157], off
	v_lshl_add_u64 v[156:157], v[220:221], 0, s[56:57]
	s_mov_b32 m0, s39
	s_nop 0
	global_load_lds_dwordx4 v[156:157], off
	v_lshl_add_u64 v[156:157], v[222:223], 0, s[56:57]
	s_mov_b32 m0, s78
	s_nop 0
	global_load_lds_dwordx4 v[156:157], off
	s_waitcnt vmcnt(8)
	s_waitcnt lgkmcnt(0)
	s_barrier
	s_setprio 1
	s_waitcnt lgkmcnt(0)
	v_mfma_f32_16x16x32_bf16 v[60:63], v[140:143], v[184:187], v[60:63]
	v_mfma_f32_16x16x32_bf16 v[56:59], v[148:151], v[184:187], v[56:59]
	v_mfma_f32_16x16x32_bf16 v[44:47], v[140:143], v[192:195], v[44:47]
	v_mfma_f32_16x16x32_bf16 v[40:43], v[148:151], v[192:195], v[40:43]
	v_mfma_f32_16x16x32_bf16 v[28:31], v[140:143], v[202:205], v[28:31]
	v_mfma_f32_16x16x32_bf16 v[24:27], v[148:151], v[202:205], v[24:27]
	v_mfma_f32_16x16x32_bf16 v[12:15], v[140:143], v[210:213], v[12:15]
	v_mfma_f32_16x16x32_bf16 v[8:11], v[148:151], v[210:213], v[8:11]
	v_mfma_f32_16x16x32_bf16 v[60:63], v[144:147], v[188:191], v[60:63]
	v_mfma_f32_16x16x32_bf16 v[56:59], v[152:155], v[188:191], v[56:59]
	v_mfma_f32_16x16x32_bf16 v[44:47], v[144:147], v[196:199], v[44:47]
	v_mfma_f32_16x16x32_bf16 v[40:43], v[152:155], v[196:199], v[40:43]
	v_mfma_f32_16x16x32_bf16 v[28:31], v[144:147], v[206:209], v[28:31]
	v_mfma_f32_16x16x32_bf16 v[24:27], v[152:155], v[206:209], v[24:27]
	v_mfma_f32_16x16x32_bf16 v[12:15], v[144:147], v[214:217], v[12:15]
	v_mfma_f32_16x16x32_bf16 v[8:11], v[152:155], v[214:217], v[8:11]
	s_setprio 0
	s_setprio 1
	v_mfma_f32_16x16x32_bf16 v[52:55], v[168:171], v[184:187], v[52:55]
	v_mfma_f32_16x16x32_bf16 v[48:51], v[176:179], v[184:187], v[48:51]
	v_mfma_f32_16x16x32_bf16 v[36:39], v[168:171], v[192:195], v[36:39]
	v_mfma_f32_16x16x32_bf16 v[32:35], v[176:179], v[192:195], v[32:35]
	v_mfma_f32_16x16x32_bf16 v[20:23], v[168:171], v[202:205], v[20:23]
	v_mfma_f32_16x16x32_bf16 v[16:19], v[176:179], v[202:205], v[16:19]
	v_mfma_f32_16x16x32_bf16 v[4:7], v[168:171], v[210:213], v[4:7]
	v_mfma_f32_16x16x32_bf16 v[0:3], v[176:179], v[210:213], v[0:3]
	v_mfma_f32_16x16x32_bf16 v[52:55], v[172:175], v[188:191], v[52:55]
	v_mfma_f32_16x16x32_bf16 v[48:51], v[180:183], v[188:191], v[48:51]
	v_mfma_f32_16x16x32_bf16 v[36:39], v[172:175], v[196:199], v[36:39]
	v_mfma_f32_16x16x32_bf16 v[32:35], v[180:183], v[196:199], v[32:35]
	v_mfma_f32_16x16x32_bf16 v[20:23], v[172:175], v[206:209], v[20:23]
	v_mfma_f32_16x16x32_bf16 v[16:19], v[180:183], v[206:209], v[16:19]
	v_mfma_f32_16x16x32_bf16 v[4:7], v[172:175], v[214:217], v[4:7]
	v_mfma_f32_16x16x32_bf16 v[0:3], v[180:183], v[214:217], v[0:3]
	s_setprio 0
	s_add_i32 s84, s84, 2
	s_add_u32 s72, s72, 0x100
	s_addc_u32 s73, s73, 0
	s_add_u32 s82, s82, 0x100
	s_addc_u32 s83, s83, 0
	s_barrier
	s_cmp_gt_u32 s84, 13
	s_cbranch_scc0 .LBB0_325
	s_and_b64 vcc, exec, s[58:59]
	s_cbranch_vccz .LBB0_328
	s_barrier

; #define PG8_STAGE(bufoff, gbase, voff) do { _Pragma("unroll") for (int _i = 0; _i < 2; ++_i) \
;         __builtin_amdgcn_global_load_lds((const unsigned*)((const char*)(gbase) + (voff)[_i]), (PG8_LAS unsigned*)(lds + (bufoff) + ldsw + _i * 8192), 16, 0, 0); } while (0)
; #define PG8_LDA(dst, b, h) do { _Pragma("unroll") for (int m = 0; m < 4; ++m) _Pragma("unroll") for (int k = 0; k < 2; ++k) dst[m][k] = *(const PG8_LAS bf16x8*)(lds + PG8_SA(b, h) + aoff + m * 2048 + k * 1024); } while (0)
; #define PG8_LDB(dst, b, h) do { _Pragma("unroll") for (int n = 0; n < 2; ++n) _Pragma("unroll") for (int k = 0; k < 2; ++k) dst[n][k] = *(const PG8_LAS bf16x8*)(lds + PG8_SB(b, h) + boff + n * 2048 + k * 1024); } while (0)
; #define PG8_MMA(ai, bj, At, Bt) do { __builtin_amdgcn_s_setprio(1); _Pragma("unroll") for (int m = 0; m < 4; ++m) _Pragma("unroll") for (int n = 0; n < 2; ++n) _Pragma("unroll") for (int k = 0; k < 2; ++k) \
;         acc[ai][bj][m][n] = __builtin_amdgcn_mfma_f32_16x16x32_bf16(Bt[n][k], At[m][k], acc[ai][bj][m][n], 0, 0, 0); __builtin_amdgcn_s_setprio(0); } while (0)
; #define PG8_WAIT_V(n) asm volatile("s_waitcnt vmcnt(" #n ")" ::: "memory")
; #define PG8_WAIT_L(n) asm volatile("s_waitcnt lgkmcnt(" #n ")" ::: "memory")
; #define PG8_BAR __builtin_amdgcn_s_barrier()
; #define PG8_SCHED __builtin_amdgcn_sched_barrier(0)
; template <class Epi, class Sched, bool ALIGN_EPI = false, bool SP2 = false>
; __device__ __forceinline__ void gemm_phase(PG8_LAS unsigned char* lds, const Gemm g, const Sched& S, const Epi& E) {
;     ...
;             PG8_LDB(B0, 0, 0); PG8_LDB(B1, 0, 1); PG8_SCHED; PG8_LDA(At, 0, 0); PG8_STAGE(PG8_SA(1, 1), a1 + hstep, voffA);
;             PG8_WAIT_V(8); PG8_WAIT_L(0); PG8_BAR; PG8_MMA(0, 0, At, B0); PG8_MMA(0, 1, At, B1); PG8_BAR; PG8_SCHED;
;             PG8_LDA(At, 0, 1); PG8_STAGE(PG8_SB(0, 0), b2, voffB); PG8_STAGE(PG8_SB(0, 1), b2 + hstep, voffB); PG8_STAGE(PG8_SA(0, 0), a2, voffA);
;             PG8_WAIT_V(8); PG8_WAIT_L(0); PG8_BAR; PG8_MMA(1, 0, At, B0); PG8_MMA(1, 1, At, B1); PG8_BAR; PG8_SCHED;
.LBB0_582:
	ds_read_b128 v[128:131], v168
	ds_read_b128 v[132:135], v168 offset:1024
	ds_read_b128 v[136:139], v168 offset:2048
	ds_read_b128 v[140:143], v168 offset:3072
	ds_read_b128 v[158:161], v169
	ds_read_b128 v[162:165], v169 offset:1024
	ds_read_b128 v[172:175], v169 offset:2048
	ds_read_b128 v[176:179], v169 offset:3072
	s_add_u32 s58, s84, 0xfffc0080
	s_addc_u32 s59, s85, -1
	s_cmp_eq_u32 s91, 12
	s_cselect_b32 s89, s56, s59
	s_cselect_b32 s88, s57, s58
	s_cselect_b32 s87, s71, s90
	s_cselect_b32 s86, s73, s81
	v_lshl_add_u64 v[218:219], s[84:85], 0, v[154:155]
	s_add_i32 m0, s29, 0xc000
	ds_read_b128 v[180:183], v170
	ds_read_b128 v[184:187], v170 offset:1024
	ds_read_b128 v[188:191], v170 offset:2048
	ds_read_b128 v[192:195], v170 offset:3072
	ds_read_b128 v[196:199], v170 offset:4096
	ds_read_b128 v[206:209], v170 offset:5120
	ds_read_b128 v[210:213], v170 offset:6144
	ds_read_b128 v[214:217], v170 offset:7168
	global_load_lds_dwordx4 v[218:219], off
	v_lshl_add_u64 v[218:219], s[84:85], 0, v[156:157]
	s_add_i32 m0, s29, 0xe000
	s_nop 0
	global_load_lds_dwordx4 v[218:219], off
	s_waitcnt vmcnt(8)
	s_waitcnt lgkmcnt(0)
	s_barrier
	s_setprio 1
	s_waitcnt lgkmcnt(0)
	v_mfma_f32_16x16x32_bf16 v[124:127], v[128:131], v[180:183], v[124:127]
	v_mfma_f32_16x16x32_bf16 v[120:123], v[136:139], v[180:183], v[120:123]
	v_mfma_f32_16x16x32_bf16 v[108:111], v[128:131], v[188:191], v[108:111]
	v_mfma_f32_16x16x32_bf16 v[104:107], v[136:139], v[188:191], v[104:107]
	v_mfma_f32_16x16x32_bf16 v[96:99], v[128:131], v[196:199], v[96:99]
	v_mfma_f32_16x16x32_bf16 v[88:91], v[136:139], v[196:199], v[88:91]
	v_mfma_f32_16x16x32_bf16 v[80:83], v[128:131], v[210:213], v[80:83]
	v_mfma_f32_16x16x32_bf16 v[72:75], v[136:139], v[210:213], v[72:75]
	v_mfma_f32_16x16x32_bf16 v[124:127], v[132:135], v[184:187], v[124:127]
	v_mfma_f32_16x16x32_bf16 v[120:123], v[140:143], v[184:187], v[120:123]
	v_mfma_f32_16x16x32_bf16 v[108:111], v[132:135], v[192:195], v[108:111]
	v_mfma_f32_16x16x32_bf16 v[104:107], v[140:143], v[192:195], v[104:107]
	v_mfma_f32_16x16x32_bf16 v[96:99], v[132:135], v[206:209], v[96:99]
	v_mfma_f32_16x16x32_bf16 v[88:91], v[140:143], v[206:209], v[88:91]
	v_mfma_f32_16x16x32_bf16 v[80:83], v[132:135], v[214:217], v[80:83]
	v_mfma_f32_16x16x32_bf16 v[72:75], v[140:143], v[214:217], v[72:75]
	s_setprio 0
	s_setprio 1
	v_mfma_f32_16x16x32_bf16 v[116:119], v[158:161], v[180:183], v[116:119]
	v_mfma_f32_16x16x32_bf16 v[112:115], v[172:175], v[180:183], v[112:115]
	v_mfma_f32_16x16x32_bf16 v[100:103], v[158:161], v[188:191], v[100:103]
	v_mfma_f32_16x16x32_bf16 v[92:95], v[172:175], v[188:191], v[92:95]
	v_mfma_f32_16x16x32_bf16 v[84:87], v[158:161], v[196:199], v[84:87]
	v_mfma_f32_16x16x32_bf16 v[76:79], v[172:175], v[196:199], v[76:79]
	v_mfma_f32_16x16x32_bf16 v[68:71], v[158:161], v[210:213], v[68:71]
	v_mfma_f32_16x16x32_bf16 v[64:67], v[172:175], v[210:213], v[64:67]
	v_mfma_f32_16x16x32_bf16 v[116:119], v[162:165], v[184:187], v[116:119]
	v_mfma_f32_16x16x32_bf16 v[112:115], v[176:179], v[184:187], v[112:115]
	v_mfma_f32_16x16x32_bf16 v[100:103], v[162:165], v[192:195], v[100:103]
	v_mfma_f32_16x16x32_bf16 v[92:95], v[176:179], v[192:195], v[92:95]
	v_mfma_f32_16x16x32_bf16 v[84:87], v[162:165], v[206:209], v[84:87]
	v_mfma_f32_16x16x32_bf16 v[76:79], v[176:179], v[206:209], v[76:79]
	v_mfma_f32_16x16x32_bf16 v[68:71], v[162:165], v[214:217], v[68:71]
	v_mfma_f32_16x16x32_bf16 v[64:67], v[176:179], v[214:217], v[64:67]
	s_setprio 0
	s_barrier
	s_add_i32 s58, s11, s28
	v_lshl_add_u64 v[218:219], s[86:87], 0, v[148:149]
	s_mov_b32 m0, s58
	ds_read_b128 v[180:183], v170 offset:16384
	ds_read_b128 v[184:187], v170 offset:17408
	ds_read_b128 v[188:191], v170 offset:18432
	ds_read_b128 v[192:195], v170 offset:19456
	ds_read_b128 v[196:199], v170 offset:20480
	ds_read_b128 v[206:209], v170 offset:21504
	ds_read_b128 v[210:213], v170 offset:22528
	ds_read_b128 v[214:217], v170 offset:23552
	global_load_lds_dwordx4 v[218:219], off
	s_add_i32 m0, s58, 0x2000
	s_add_u32 s58, s86, 0x40000
	v_lshl_add_u64 v[220:221], s[86:87], 0, v[152:153]
	s_addc_u32 s59, s87, 0
	s_add_i32 s60, s83, s28
	global_load_lds_dwordx4 v[220:221], off
	v_lshl_add_u64 v[222:223], s[58:59], 0, v[148:149]
	s_mov_b32 m0, s60
	v_lshl_add_u64 v[224:225], s[88:89], 0, v[150:151]
	global_load_lds_dwordx4 v[222:223], off
	v_lshl_add_u64 v[222:223], s[58:59], 0, v[152:153]
	s_add_i32 m0, s60, 0x2000
	s_nop 0
	global_load_lds_dwordx4 v[222:223], off
	v_lshl_add_u64 v[222:223], s[88:89], 0, v[146:147]
	s_mov_b32 m0, s29
	s_nop 0
	global_load_lds_dwordx4 v[222:223], off
	s_mov_b32 m0, s30
	s_nop 0
	global_load_lds_dwordx4 v[224:225], off
	s_waitcnt vmcnt(8)
	s_waitcnt lgkmcnt(0)
	s_barrier
; #define PG8_STAGE(bufoff, gbase, voff) do { _Pragma("unroll") for (int _i = 0; _i < 2; ++_i) \
;         __builtin_amdgcn_global_load_lds((const unsigned*)((const char*)(gbase) + (voff)[_i]), (PG8_LAS unsigned*)(lds + (bufoff) + ldsw + _i * 8192), 16, 0, 0); } while (0)
; #define PG8_LDA(dst, b, h) do { _Pragma("unroll") for (int m = 0; m < 4; ++m) _Pragma("unroll") for (int k = 0; k < 2; ++k) dst[m][k] = *(const PG8_LAS bf16x8*)(lds + PG8_SA(b, h) + aoff + m * 2048 + k * 1024); } while (0)
; #define PG8_LDB(dst, b, h) do { _Pragma("unroll") for (int n = 0; n < 2; ++n) _Pragma("unroll") for (int k = 0; k < 2; ++k) dst[n][k] = *(const PG8_LAS bf16x8*)(lds + PG8_SB(b, h) + boff + n * 2048 + k * 1024); } while (0)
; #define PG8_MMA(ai, bj, At, Bt) do { __builtin_amdgcn_s_setprio(1); _Pragma("unroll") for (int m = 0; m < 4; ++m) _Pragma("unroll") for (int n = 0; n < 2; ++n) _Pragma("unroll") for (int k = 0; k < 2; ++k) \
;         acc[ai][bj][m][n] = __builtin_amdgcn_mfma_f32_16x16x32_bf16(Bt[n][k], At[m][k], acc[ai][bj][m][n], 0, 0, 0); __builtin_amdgcn_s_setprio(0); } while (0)
; #define PG8_WAIT_V(n) asm volatile("s_waitcnt vmcnt(" #n ")" ::: "memory")
; #define PG8_WAIT_L(n) asm volatile("s_waitcnt lgkmcnt(" #n ")" ::: "memory")
; #define PG8_BAR __builtin_amdgcn_s_barrier()
; #define PG8_SCHED __builtin_amdgcn_sched_barrier(0)
; template <class Epi, class Sched, bool ALIGN_EPI = false, bool SP2 = false>
; __device__ __forceinline__ void gemm_phase(PG8_LAS unsigned char* lds, const Gemm g, const Sched& S, const Epi& E) {
;     ...
;             PG8_WAIT_V(8); PG8_WAIT_L(0); PG8_BAR; PG8_MMA(1, 0, At, B0); PG8_MMA(1, 1, At, B1); PG8_BAR; PG8_SCHED;
;             PG8_LDB(B0, 1, 0); PG8_LDB(B1, 1, 1); PG8_SCHED; PG8_LDA(At, 1, 0); PG8_STAGE(PG8_SA(0, 1), a2 + hstep, voffA);
;             PG8_WAIT_V(8); PG8_WAIT_L(0); PG8_BAR; PG8_MMA(0, 0, At, B0); PG8_MMA(0, 1, At, B1); PG8_BAR; PG8_SCHED;
	s_setprio 1
	s_waitcnt lgkmcnt(0)
	v_mfma_f32_16x16x32_bf16 v[60:63], v[128:131], v[180:183], v[60:63]
	v_mfma_f32_16x16x32_bf16 v[56:59], v[136:139], v[180:183], v[56:59]
	v_mfma_f32_16x16x32_bf16 v[48:51], v[128:131], v[188:191], v[48:51]
	v_mfma_f32_16x16x32_bf16 v[40:43], v[136:139], v[188:191], v[40:43]
	v_mfma_f32_16x16x32_bf16 v[32:35], v[128:131], v[196:199], v[32:35]
	v_mfma_f32_16x16x32_bf16 v[24:27], v[136:139], v[196:199], v[24:27]
	v_mfma_f32_16x16x32_bf16 v[16:19], v[128:131], v[210:213], v[16:19]
	v_mfma_f32_16x16x32_bf16 v[8:11], v[136:139], v[210:213], v[8:11]
	v_mfma_f32_16x16x32_bf16 v[60:63], v[132:135], v[184:187], v[60:63]
	v_mfma_f32_16x16x32_bf16 v[56:59], v[140:143], v[184:187], v[56:59]
	v_mfma_f32_16x16x32_bf16 v[48:51], v[132:135], v[192:195], v[48:51]
	v_mfma_f32_16x16x32_bf16 v[40:43], v[140:143], v[192:195], v[40:43]
	v_mfma_f32_16x16x32_bf16 v[32:35], v[132:135], v[206:209], v[32:35]
	v_mfma_f32_16x16x32_bf16 v[24:27], v[140:143], v[206:209], v[24:27]
	v_mfma_f32_16x16x32_bf16 v[16:19], v[132:135], v[214:217], v[16:19]
	v_mfma_f32_16x16x32_bf16 v[8:11], v[140:143], v[214:217], v[8:11]
	s_setprio 0
	s_setprio 1
	v_mfma_f32_16x16x32_bf16 v[52:55], v[158:161], v[180:183], v[52:55]
	v_mfma_f32_16x16x32_bf16 v[44:47], v[172:175], v[180:183], v[44:47]
	v_mfma_f32_16x16x32_bf16 v[36:39], v[158:161], v[188:191], v[36:39]
	v_mfma_f32_16x16x32_bf16 v[28:31], v[172:175], v[188:191], v[28:31]
	v_mfma_f32_16x16x32_bf16 v[20:23], v[158:161], v[196:199], v[20:23]
	v_mfma_f32_16x16x32_bf16 v[12:15], v[172:175], v[196:199], v[12:15]
	v_mfma_f32_16x16x32_bf16 v[4:7], v[158:161], v[210:213], v[4:7]
	v_mfma_f32_16x16x32_bf16 v[0:3], v[172:175], v[210:213], v[0:3]
	v_mfma_f32_16x16x32_bf16 v[52:55], v[162:165], v[184:187], v[52:55]
	v_mfma_f32_16x16x32_bf16 v[44:47], v[176:179], v[184:187], v[44:47]
	v_mfma_f32_16x16x32_bf16 v[36:39], v[162:165], v[192:195], v[36:39]
	v_mfma_f32_16x16x32_bf16 v[28:31], v[176:179], v[192:195], v[28:31]
	v_mfma_f32_16x16x32_bf16 v[20:23], v[162:165], v[206:209], v[20:23]
	v_mfma_f32_16x16x32_bf16 v[12:15], v[176:179], v[206:209], v[12:15]
	v_mfma_f32_16x16x32_bf16 v[4:7], v[162:165], v[214:217], v[4:7]
	v_mfma_f32_16x16x32_bf16 v[0:3], v[176:179], v[214:217], v[0:3]
	s_setprio 0
	s_barrier
	s_add_i32 s60, 0, 0x18000
	s_add_i32 s61, 0, 0x1c000
	v_add_u32_e32 v140, s60, v166
	v_add_u32_e32 v176, s61, v166
	ds_read_b128 v[128:131], v140
	ds_read_b128 v[132:135], v140 offset:1024
	ds_read_b128 v[136:139], v140 offset:2048
	ds_read_b128 v[140:143], v140 offset:3072
	ds_read_b128 v[158:161], v176
	ds_read_b128 v[162:165], v176 offset:1024
	ds_read_b128 v[172:175], v176 offset:2048
	ds_read_b128 v[176:179], v176 offset:3072
	s_add_u32 s58, s88, 0x40000
	s_addc_u32 s59, s89, 0
	s_mov_b32 m0, s31
	v_lshl_add_u64 v[226:227], s[58:59], 0, v[146:147]
	ds_read_b128 v[180:183], v170 offset:32768
	ds_read_b128 v[184:187], v170 offset:33792
	ds_read_b128 v[188:191], v170 offset:34816
	ds_read_b128 v[192:195], v170 offset:35840
	ds_read_b128 v[196:199], v170 offset:36864
	ds_read_b128 v[206:209], v170 offset:37888
	ds_read_b128 v[210:213], v170 offset:38912
	ds_read_b128 v[214:217], v170 offset:39936
	global_load_lds_dwordx4 v[226:227], off
	v_lshl_add_u64 v[226:227], s[58:59], 0, v[150:151]
	s_mov_b32 m0, s37
	s_nop 0
	global_load_lds_dwordx4 v[226:227], off
	s_waitcnt vmcnt(8)
	s_waitcnt lgkmcnt(0)
	s_barrier
	s_setprio 1
	s_waitcnt lgkmcnt(0)
	v_mfma_f32_16x16x32_bf16 v[124:127], v[128:131], v[180:183], v[124:127]
	v_mfma_f32_16x16x32_bf16 v[120:123], v[136:139], v[180:183], v[120:123]
	v_mfma_f32_16x16x32_bf16 v[108:111], v[128:131], v[188:191], v[108:111]
	v_mfma_f32_16x16x32_bf16 v[104:107], v[136:139], v[188:191], v[104:107]
	v_mfma_f32_16x16x32_bf16 v[96:99], v[128:131], v[196:199], v[96:99]
	v_mfma_f32_16x16x32_bf16 v[88:91], v[136:139], v[196:199], v[88:91]
	v_mfma_f32_16x16x32_bf16 v[80:83], v[128:131], v[210:213], v[80:83]
	v_mfma_f32_16x16x32_bf16 v[72:75], v[136:139], v[210:213], v[72:75]
	v_mfma_f32_16x16x32_bf16 v[124:127], v[132:135], v[184:187], v[124:127]
	v_mfma_f32_16x16x32_bf16 v[120:123], v[140:143], v[184:187], v[120:123]
	v_mfma_f32_16x16x32_bf16 v[108:111], v[132:135], v[192:195], v[108:111]
	v_mfma_f32_16x16x32_bf16 v[104:107], v[140:143], v[192:195], v[104:107]
	v_mfma_f32_16x16x32_bf16 v[96:99], v[132:135], v[206:209], v[96:99]
	v_mfma_f32_16x16x32_bf16 v[88:91], v[140:143], v[206:209], v[88:91]
	v_mfma_f32_16x16x32_bf16 v[80:83], v[132:135], v[214:217], v[80:83]
	v_mfma_f32_16x16x32_bf16 v[72:75], v[140:143], v[214:217], v[72:75]
	s_setprio 0
	s_setprio 1
	v_mfma_f32_16x16x32_bf16 v[116:119], v[158:161], v[180:183], v[116:119]
	v_mfma_f32_16x16x32_bf16 v[112:115], v[172:175], v[180:183], v[112:115]
	v_mfma_f32_16x16x32_bf16 v[100:103], v[158:161], v[188:191], v[100:103]
	v_mfma_f32_16x16x32_bf16 v[92:95], v[172:175], v[188:191], v[92:95]
	v_mfma_f32_16x16x32_bf16 v[84:87], v[158:161], v[196:199], v[84:87]
	v_mfma_f32_16x16x32_bf16 v[76:79], v[172:175], v[196:199], v[76:79]
	v_mfma_f32_16x16x32_bf16 v[68:71], v[158:161], v[210:213], v[68:71]
	v_mfma_f32_16x16x32_bf16 v[64:67], v[172:175], v[210:213], v[64:67]
	v_mfma_f32_16x16x32_bf16 v[116:119], v[162:165], v[184:187], v[116:119]
	v_mfma_f32_16x16x32_bf16 v[112:115], v[176:179], v[184:187], v[112:115]
	v_mfma_f32_16x16x32_bf16 v[100:103], v[162:165], v[192:195], v[100:103]
	v_mfma_f32_16x16x32_bf16 v[92:95], v[176:179], v[192:195], v[92:95]
	v_mfma_f32_16x16x32_bf16 v[84:87], v[162:165], v[206:209], v[84:87]
	v_mfma_f32_16x16x32_bf16 v[76:79], v[176:179], v[206:209], v[76:79]
	v_mfma_f32_16x16x32_bf16 v[68:71], v[162:165], v[214:217], v[68:71]
	v_mfma_f32_16x16x32_bf16 v[64:67], v[176:179], v[214:217], v[64:67]
	s_setprio 0
	s_barrier
; #define PG8_STAGE(bufoff, gbase, voff) do { _Pragma("unroll") for (int _i = 0; _i < 2; ++_i) \
;         __builtin_amdgcn_global_load_lds((const unsigned*)((const char*)(gbase) + (voff)[_i]), (PG8_LAS unsigned*)(lds + (bufoff) + ldsw + _i * 8192), 16, 0, 0); } while (0)
; #define PG8_LDA(dst, b, h) do { _Pragma("unroll") for (int m = 0; m < 4; ++m) _Pragma("unroll") for (int k = 0; k < 2; ++k) dst[m][k] = *(const PG8_LAS bf16x8*)(lds + PG8_SA(b, h) + aoff + m * 2048 + k * 1024); } while (0)
; #define PG8_MMA(ai, bj, At, Bt) do { __builtin_amdgcn_s_setprio(1); _Pragma("unroll") for (int m = 0; m < 4; ++m) _Pragma("unroll") for (int n = 0; n < 2; ++n) _Pragma("unroll") for (int k = 0; k < 2; ++k) \
;         acc[ai][bj][m][n] = __builtin_amdgcn_mfma_f32_16x16x32_bf16(Bt[n][k], At[m][k], acc[ai][bj][m][n], 0, 0, 0); __builtin_amdgcn_s_setprio(0); } while (0)
; #define PG8_WAIT_V(n) asm volatile("s_waitcnt vmcnt(" #n ")" ::: "memory")
; #define PG8_WAIT_L(n) asm volatile("s_waitcnt lgkmcnt(" #n ")" ::: "memory")
; #define PG8_BAR __builtin_amdgcn_s_barrier()
; #define PG8_SCHED __builtin_amdgcn_sched_barrier(0)
; template <class Epi, class Sched, bool ALIGN_EPI = false, bool SP2 = false>
; __device__ __forceinline__ void gemm_phase(PG8_LAS unsigned char* lds, const Gemm g, const Sched& S, const Epi& E) {
;     ...
;             PG8_LDA(At, 1, 1); PG8_STAGE(PG8_SB(1, 0), b3, voffB); PG8_STAGE(PG8_SB(1, 1), b3 + hstep, voffB); PG8_STAGE(PG8_SA(1, 0), a3, voffA);
;             PG8_WAIT_V(8); PG8_WAIT_L(0); PG8_BAR; PG8_MMA(1, 0, At, B0); PG8_MMA(1, 1, At, B1); PG8_BAR; PG8_SCHED;
	s_add_i32 s58, s60, s28
	v_lshl_add_u64 v[218:219], v[218:219], 0, s[66:67]
	s_mov_b32 m0, s58
	ds_read_b128 v[180:183], v170 offset:49152
	ds_read_b128 v[184:187], v170 offset:50176
	ds_read_b128 v[188:191], v170 offset:51200
	ds_read_b128 v[192:195], v170 offset:52224
	ds_read_b128 v[196:199], v170 offset:53248
	ds_read_b128 v[206:209], v170 offset:54272
	ds_read_b128 v[210:213], v170 offset:55296
	ds_read_b128 v[214:217], v170 offset:56320
	global_load_lds_dwordx4 v[218:219], off
	s_add_i32 m0, s58, 0x2000
	s_add_u32 s58, s86, 0x40080
	v_lshl_add_u64 v[218:219], v[220:221], 0, s[66:67]
	s_addc_u32 s59, s87, 0
	s_add_i32 s60, s61, s28
	global_load_lds_dwordx4 v[218:219], off
	v_lshl_add_u64 v[218:219], s[58:59], 0, v[148:149]
	s_mov_b32 m0, s60
	s_nop 0
	global_load_lds_dwordx4 v[218:219], off
	v_lshl_add_u64 v[218:219], s[58:59], 0, v[152:153]
	s_add_i32 m0, s60, 0x2000
	s_nop 0
	global_load_lds_dwordx4 v[218:219], off
	v_lshl_add_u64 v[218:219], v[222:223], 0, s[66:67]
	s_mov_b32 m0, s2
	s_nop 0
	global_load_lds_dwordx4 v[218:219], off
	v_lshl_add_u64 v[218:219], v[224:225], 0, s[66:67]
	s_mov_b32 m0, s3
	s_nop 0
	global_load_lds_dwordx4 v[218:219], off
	s_waitcnt vmcnt(8)
	s_waitcnt lgkmcnt(0)
	s_barrier
	s_setprio 1
	s_waitcnt lgkmcnt(0)
	v_mfma_f32_16x16x32_bf16 v[60:63], v[128:131], v[180:183], v[60:63]
	v_mfma_f32_16x16x32_bf16 v[56:59], v[136:139], v[180:183], v[56:59]
	v_mfma_f32_16x16x32_bf16 v[48:51], v[128:131], v[188:191], v[48:51]
	v_mfma_f32_16x16x32_bf16 v[40:43], v[136:139], v[188:191], v[40:43]
	v_mfma_f32_16x16x32_bf16 v[32:35], v[128:131], v[196:199], v[32:35]
	v_mfma_f32_16x16x32_bf16 v[24:27], v[136:139], v[196:199], v[24:27]
	v_mfma_f32_16x16x32_bf16 v[16:19], v[128:131], v[210:213], v[16:19]
	v_mfma_f32_16x16x32_bf16 v[8:11], v[136:139], v[210:213], v[8:11]
	v_mfma_f32_16x16x32_bf16 v[60:63], v[132:135], v[184:187], v[60:63]
	v_mfma_f32_16x16x32_bf16 v[56:59], v[140:143], v[184:187], v[56:59]
	v_mfma_f32_16x16x32_bf16 v[48:51], v[132:135], v[192:195], v[48:51]
	v_mfma_f32_16x16x32_bf16 v[40:43], v[140:143], v[192:195], v[40:43]
	v_mfma_f32_16x16x32_bf16 v[32:35], v[132:135], v[206:209], v[32:35]
	v_mfma_f32_16x16x32_bf16 v[24:27], v[140:143], v[206:209], v[24:27]
	v_mfma_f32_16x16x32_bf16 v[16:19], v[132:135], v[214:217], v[16:19]
	v_mfma_f32_16x16x32_bf16 v[8:11], v[140:143], v[214:217], v[8:11]
	s_setprio 0
	s_setprio 1
	v_mfma_f32_16x16x32_bf16 v[52:55], v[158:161], v[180:183], v[52:55]
	v_mfma_f32_16x16x32_bf16 v[44:47], v[172:175], v[180:183], v[44:47]
	v_mfma_f32_16x16x32_bf16 v[36:39], v[158:161], v[188:191], v[36:39]
	v_mfma_f32_16x16x32_bf16 v[28:31], v[172:175], v[188:191], v[28:31]
	v_mfma_f32_16x16x32_bf16 v[20:23], v[158:161], v[196:199], v[20:23]
	v_mfma_f32_16x16x32_bf16 v[12:15], v[172:175], v[196:199], v[12:15]
	v_mfma_f32_16x16x32_bf16 v[4:7], v[158:161], v[210:213], v[4:7]
	v_mfma_f32_16x16x32_bf16 v[0:3], v[172:175], v[210:213], v[0:3]
	v_mfma_f32_16x16x32_bf16 v[52:55], v[162:165], v[184:187], v[52:55]
	v_mfma_f32_16x16x32_bf16 v[44:47], v[176:179], v[184:187], v[44:47]
	v_mfma_f32_16x16x32_bf16 v[36:39], v[162:165], v[192:195], v[36:39]
	v_mfma_f32_16x16x32_bf16 v[28:31], v[176:179], v[192:195], v[28:31]
	v_mfma_f32_16x16x32_bf16 v[20:23], v[162:165], v[206:209], v[20:23]
	v_mfma_f32_16x16x32_bf16 v[12:15], v[176:179], v[206:209], v[12:15]
	v_mfma_f32_16x16x32_bf16 v[4:7], v[162:165], v[214:217], v[4:7]
	v_mfma_f32_16x16x32_bf16 v[0:3], v[176:179], v[214:217], v[0:3]
	s_setprio 0
	s_add_i32 s91, s91, 2
	s_add_u32 s84, s84, 0x100
	s_addc_u32 s85, s85, 0
	s_add_u32 s81, s81, 0x100
	s_addc_u32 s90, s90, 0
	s_barrier
	s_cmp_gt_u32 s91, 13
	s_cbranch_scc0 .LBB0_582
	s_and_b64 vcc, exec, s[68:69]
	s_cbranch_vccz .LBB0_585
	s_barrier

; #define PG8_STAGE(bufoff, gbase, voff) do { _Pragma("unroll") for (int _i = 0; _i < 2; ++_i) \
;         __builtin_amdgcn_global_load_lds((const unsigned*)((const char*)(gbase) + (voff)[_i]), (PG8_LAS unsigned*)(lds + (bufoff) + ldsw + _i * 8192), 16, 0, 0); } while (0)
; #define PG8_LDA(dst, b, h) do { _Pragma("unroll") for (int m = 0; m < 4; ++m) _Pragma("unroll") for (int k = 0; k < 2; ++k) dst[m][k] = *(const PG8_LAS bf16x8*)(lds + PG8_SA(b, h) + aoff + m * 2048 + k * 1024); } while (0)
; #define PG8_LDB(dst, b, h) do { _Pragma("unroll") for (int n = 0; n < 2; ++n) _Pragma("unroll") for (int k = 0; k < 2; ++k) dst[n][k] = *(const PG8_LAS bf16x8*)(lds + PG8_SB(b, h) + boff + n * 2048 + k * 1024); } while (0)
; #define PG8_MMA(ai, bj, At, Bt) do { __builtin_amdgcn_s_setprio(1); _Pragma("unroll") for (int m = 0; m < 4; ++m) _Pragma("unroll") for (int n = 0; n < 2; ++n) _Pragma("unroll") for (int k = 0; k < 2; ++k) \
;         acc[ai][bj][m][n] = __builtin_amdgcn_mfma_f32_16x16x32_bf16(Bt[n][k], At[m][k], acc[ai][bj][m][n], 0, 0, 0); __builtin_amdgcn_s_setprio(0); } while (0)
; #define PG8_WAIT_V(n) asm volatile("s_waitcnt vmcnt(" #n ")" ::: "memory")
; #define PG8_WAIT_L(n) asm volatile("s_waitcnt lgkmcnt(" #n ")" ::: "memory")
; #define PG8_BAR __builtin_amdgcn_s_barrier()
; #define PG8_SCHED __builtin_amdgcn_sched_barrier(0)
; template <class Epi, class Sched, bool ALIGN_EPI = false, bool SP2 = false>
; __device__ __forceinline__ void gemm_phase(PG8_LAS unsigned char* lds, const Gemm g, const Sched& S, const Epi& E) {
;     ...
;             PG8_LDB(B0, 0, 0); PG8_LDB(B1, 0, 1); PG8_SCHED; PG8_LDA(At, 0, 0); PG8_STAGE(PG8_SA(1, 1), a1 + hstep, voffA);
;             PG8_WAIT_V(8); PG8_WAIT_L(0); PG8_BAR; PG8_MMA(0, 0, At, B0); PG8_MMA(0, 1, At, B1); PG8_BAR; PG8_SCHED;
;             PG8_LDA(At, 0, 1); PG8_STAGE(PG8_SB(0, 0), b2, voffB); PG8_STAGE(PG8_SB(0, 1), b2 + hstep, voffB); PG8_STAGE(PG8_SA(0, 0), a2, voffA);
;             PG8_WAIT_V(8); PG8_WAIT_L(0); PG8_BAR; PG8_MMA(1, 0, At, B0); PG8_MMA(1, 1, At, B1); PG8_BAR; PG8_SCHED;
.LBB0_660:
	ds_read_b128 v[140:143], v190
	ds_read_b128 v[146:149], v190 offset:1024
	ds_read_b128 v[150:153], v190 offset:2048
	ds_read_b128 v[154:157], v190 offset:3072
	ds_read_b128 v[158:161], v191
	ds_read_b128 v[162:165], v191 offset:1024
	ds_read_b128 v[166:169], v191 offset:2048
	ds_read_b128 v[170:173], v191 offset:3072
	s_add_u32 s58, s80, 0xfffc0080
	s_addc_u32 s59, s81, -1
	s_cmp_eq_u32 s90, 12
	s_cselect_b32 s85, s5, s59
	s_cselect_b32 s84, s71, s58
	s_cselect_b32 s83, s73, s89
	s_cselect_b32 s82, s87, s88
	v_lshl_add_u64 v[186:187], s[80:81], 0, v[136:137]
	s_add_i32 m0, s20, 0xc000
	ds_read_b128 v[174:177], v192
	ds_read_b128 v[178:181], v192 offset:1024
	ds_read_b128 v[182:185], v192 offset:2048
	ds_read_b128 v[194:197], v192 offset:3072
	ds_read_b128 v[206:209], v192 offset:4096
	ds_read_b128 v[210:213], v192 offset:5120
	ds_read_b128 v[214:217], v192 offset:6144
	ds_read_b128 v[218:221], v192 offset:7168
	global_load_lds_dwordx4 v[186:187], off
	v_lshl_add_u64 v[186:187], s[80:81], 0, v[138:139]
	s_add_i32 m0, s20, 0xe000
	s_nop 0
	global_load_lds_dwordx4 v[186:187], off
	s_waitcnt vmcnt(8)
	s_waitcnt lgkmcnt(0)
	s_barrier
	s_setprio 1
	s_waitcnt lgkmcnt(0)
	v_mfma_f32_16x16x32_bf16 v[124:127], v[140:143], v[174:177], v[124:127]
	v_mfma_f32_16x16x32_bf16 v[120:123], v[150:153], v[174:177], v[120:123]
	v_mfma_f32_16x16x32_bf16 v[108:111], v[140:143], v[182:185], v[108:111]
	v_mfma_f32_16x16x32_bf16 v[104:107], v[150:153], v[182:185], v[104:107]
	v_mfma_f32_16x16x32_bf16 v[92:95], v[140:143], v[206:209], v[92:95]
	v_mfma_f32_16x16x32_bf16 v[88:91], v[150:153], v[206:209], v[88:91]
	v_mfma_f32_16x16x32_bf16 v[76:79], v[140:143], v[214:217], v[76:79]
	v_mfma_f32_16x16x32_bf16 v[72:75], v[150:153], v[214:217], v[72:75]
	v_mfma_f32_16x16x32_bf16 v[124:127], v[146:149], v[178:181], v[124:127]
	v_mfma_f32_16x16x32_bf16 v[120:123], v[154:157], v[178:181], v[120:123]
	v_mfma_f32_16x16x32_bf16 v[108:111], v[146:149], v[194:197], v[108:111]
	v_mfma_f32_16x16x32_bf16 v[104:107], v[154:157], v[194:197], v[104:107]
	v_mfma_f32_16x16x32_bf16 v[92:95], v[146:149], v[210:213], v[92:95]
	v_mfma_f32_16x16x32_bf16 v[88:91], v[154:157], v[210:213], v[88:91]
	v_mfma_f32_16x16x32_bf16 v[76:79], v[146:149], v[218:221], v[76:79]
	v_mfma_f32_16x16x32_bf16 v[72:75], v[154:157], v[218:221], v[72:75]
	s_setprio 0
	s_setprio 1
	v_mfma_f32_16x16x32_bf16 v[116:119], v[158:161], v[174:177], v[116:119]
	v_mfma_f32_16x16x32_bf16 v[112:115], v[166:169], v[174:177], v[112:115]
	v_mfma_f32_16x16x32_bf16 v[100:103], v[158:161], v[182:185], v[100:103]
	v_mfma_f32_16x16x32_bf16 v[96:99], v[166:169], v[182:185], v[96:99]
	v_mfma_f32_16x16x32_bf16 v[84:87], v[158:161], v[206:209], v[84:87]
	v_mfma_f32_16x16x32_bf16 v[80:83], v[166:169], v[206:209], v[80:83]
	v_mfma_f32_16x16x32_bf16 v[68:71], v[158:161], v[214:217], v[68:71]
	v_mfma_f32_16x16x32_bf16 v[64:67], v[166:169], v[214:217], v[64:67]
	v_mfma_f32_16x16x32_bf16 v[116:119], v[162:165], v[178:181], v[116:119]
	v_mfma_f32_16x16x32_bf16 v[112:115], v[170:173], v[178:181], v[112:115]
	v_mfma_f32_16x16x32_bf16 v[100:103], v[162:165], v[194:197], v[100:103]
	v_mfma_f32_16x16x32_bf16 v[96:99], v[170:173], v[194:197], v[96:99]
	v_mfma_f32_16x16x32_bf16 v[84:87], v[162:165], v[210:213], v[84:87]
	v_mfma_f32_16x16x32_bf16 v[80:83], v[170:173], v[210:213], v[80:83]
	v_mfma_f32_16x16x32_bf16 v[68:71], v[162:165], v[218:221], v[68:71]
	v_mfma_f32_16x16x32_bf16 v[64:67], v[170:173], v[218:221], v[64:67]
	s_setprio 0
	s_barrier
	s_add_i32 s58, s39, s11
	v_lshl_add_u64 v[186:187], s[82:83], 0, v[132:133]
	s_mov_b32 m0, s58
	ds_read_b128 v[174:177], v192 offset:16384
	ds_read_b128 v[178:181], v192 offset:17408
	ds_read_b128 v[182:185], v192 offset:18432
	ds_read_b128 v[194:197], v192 offset:19456
	ds_read_b128 v[206:209], v192 offset:20480
	ds_read_b128 v[210:213], v192 offset:21504
	ds_read_b128 v[214:217], v192 offset:22528
	ds_read_b128 v[218:221], v192 offset:23552
	global_load_lds_dwordx4 v[186:187], off
	s_add_i32 m0, s58, 0x2000
	s_add_u32 s58, s82, 0x40000
	v_lshl_add_u64 v[198:199], s[82:83], 0, v[128:129]
	s_addc_u32 s59, s83, 0
	s_add_i32 s60, s56, s11
	global_load_lds_dwordx4 v[198:199], off
	v_lshl_add_u64 v[222:223], s[58:59], 0, v[132:133]
	s_mov_b32 m0, s60
	v_lshl_add_u64 v[224:225], s[84:85], 0, v[130:131]
	global_load_lds_dwordx4 v[222:223], off
	v_lshl_add_u64 v[222:223], s[58:59], 0, v[128:129]
	s_add_i32 m0, s60, 0x2000
	s_nop 0
	global_load_lds_dwordx4 v[222:223], off
	v_lshl_add_u64 v[222:223], s[84:85], 0, v[134:135]
	s_mov_b32 m0, s20
	s_nop 0
	global_load_lds_dwordx4 v[222:223], off
	s_mov_b32 m0, s21
	s_nop 0
	global_load_lds_dwordx4 v[224:225], off
	s_waitcnt vmcnt(8)
	s_waitcnt lgkmcnt(0)
	s_barrier
; #define PG8_STAGE(bufoff, gbase, voff) do { _Pragma("unroll") for (int _i = 0; _i < 2; ++_i) \
;         __builtin_amdgcn_global_load_lds((const unsigned*)((const char*)(gbase) + (voff)[_i]), (PG8_LAS unsigned*)(lds + (bufoff) + ldsw + _i * 8192), 16, 0, 0); } while (0)
; #define PG8_LDA(dst, b, h) do { _Pragma("unroll") for (int m = 0; m < 4; ++m) _Pragma("unroll") for (int k = 0; k < 2; ++k) dst[m][k] = *(const PG8_LAS bf16x8*)(lds + PG8_SA(b, h) + aoff + m * 2048 + k * 1024); } while (0)
; #define PG8_LDB(dst, b, h) do { _Pragma("unroll") for (int n = 0; n < 2; ++n) _Pragma("unroll") for (int k = 0; k < 2; ++k) dst[n][k] = *(const PG8_LAS bf16x8*)(lds + PG8_SB(b, h) + boff + n * 2048 + k * 1024); } while (0)
; #define PG8_MMA(ai, bj, At, Bt) do { __builtin_amdgcn_s_setprio(1); _Pragma("unroll") for (int m = 0; m < 4; ++m) _Pragma("unroll") for (int n = 0; n < 2; ++n) _Pragma("unroll") for (int k = 0; k < 2; ++k) \
;         acc[ai][bj][m][n] = __builtin_amdgcn_mfma_f32_16x16x32_bf16(Bt[n][k], At[m][k], acc[ai][bj][m][n], 0, 0, 0); __builtin_amdgcn_s_setprio(0); } while (0)
; #define PG8_WAIT_V(n) asm volatile("s_waitcnt vmcnt(" #n ")" ::: "memory")
; #define PG8_WAIT_L(n) asm volatile("s_waitcnt lgkmcnt(" #n ")" ::: "memory")
; #define PG8_BAR __builtin_amdgcn_s_barrier()
; #define PG8_SCHED __builtin_amdgcn_sched_barrier(0)
; template <class Epi, class Sched, bool ALIGN_EPI = false, bool SP2 = false>
; __device__ __forceinline__ void gemm_phase(PG8_LAS unsigned char* lds, const Gemm g, const Sched& S, const Epi& E) {
;     ...
;             PG8_WAIT_V(8); PG8_WAIT_L(0); PG8_BAR; PG8_MMA(1, 0, At, B0); PG8_MMA(1, 1, At, B1); PG8_BAR; PG8_SCHED;
;             PG8_LDB(B0, 1, 0); PG8_LDB(B1, 1, 1); PG8_SCHED; PG8_LDA(At, 1, 0); PG8_STAGE(PG8_SA(0, 1), a2 + hstep, voffA);
;             PG8_WAIT_V(8); PG8_WAIT_L(0); PG8_BAR; PG8_MMA(0, 0, At, B0); PG8_MMA(0, 1, At, B1); PG8_BAR; PG8_SCHED;
	s_setprio 1
	s_waitcnt lgkmcnt(0)
	v_mfma_f32_16x16x32_bf16 v[60:63], v[140:143], v[174:177], v[60:63]
	v_mfma_f32_16x16x32_bf16 v[56:59], v[150:153], v[174:177], v[56:59]
	v_mfma_f32_16x16x32_bf16 v[44:47], v[140:143], v[182:185], v[44:47]
	v_mfma_f32_16x16x32_bf16 v[40:43], v[150:153], v[182:185], v[40:43]
	v_mfma_f32_16x16x32_bf16 v[28:31], v[140:143], v[206:209], v[28:31]
	v_mfma_f32_16x16x32_bf16 v[24:27], v[150:153], v[206:209], v[24:27]
	v_mfma_f32_16x16x32_bf16 v[12:15], v[140:143], v[214:217], v[12:15]
	v_mfma_f32_16x16x32_bf16 v[8:11], v[150:153], v[214:217], v[8:11]
	v_mfma_f32_16x16x32_bf16 v[60:63], v[146:149], v[178:181], v[60:63]
	v_mfma_f32_16x16x32_bf16 v[56:59], v[154:157], v[178:181], v[56:59]
	v_mfma_f32_16x16x32_bf16 v[44:47], v[146:149], v[194:197], v[44:47]
	v_mfma_f32_16x16x32_bf16 v[40:43], v[154:157], v[194:197], v[40:43]
	v_mfma_f32_16x16x32_bf16 v[28:31], v[146:149], v[210:213], v[28:31]
	v_mfma_f32_16x16x32_bf16 v[24:27], v[154:157], v[210:213], v[24:27]
	v_mfma_f32_16x16x32_bf16 v[12:15], v[146:149], v[218:221], v[12:15]
	v_mfma_f32_16x16x32_bf16 v[8:11], v[154:157], v[218:221], v[8:11]
	s_setprio 0
	s_setprio 1
	v_mfma_f32_16x16x32_bf16 v[52:55], v[158:161], v[174:177], v[52:55]
	v_mfma_f32_16x16x32_bf16 v[48:51], v[166:169], v[174:177], v[48:51]
	v_mfma_f32_16x16x32_bf16 v[36:39], v[158:161], v[182:185], v[36:39]
	v_mfma_f32_16x16x32_bf16 v[32:35], v[166:169], v[182:185], v[32:35]
	v_mfma_f32_16x16x32_bf16 v[20:23], v[158:161], v[206:209], v[20:23]
	v_mfma_f32_16x16x32_bf16 v[16:19], v[166:169], v[206:209], v[16:19]
	v_mfma_f32_16x16x32_bf16 v[4:7], v[158:161], v[214:217], v[4:7]
	v_mfma_f32_16x16x32_bf16 v[0:3], v[166:169], v[214:217], v[0:3]
	v_mfma_f32_16x16x32_bf16 v[52:55], v[162:165], v[178:181], v[52:55]
	v_mfma_f32_16x16x32_bf16 v[48:51], v[170:173], v[178:181], v[48:51]
	v_mfma_f32_16x16x32_bf16 v[36:39], v[162:165], v[194:197], v[36:39]
	v_mfma_f32_16x16x32_bf16 v[32:35], v[170:173], v[194:197], v[32:35]
	v_mfma_f32_16x16x32_bf16 v[20:23], v[162:165], v[210:213], v[20:23]
	v_mfma_f32_16x16x32_bf16 v[16:19], v[170:173], v[210:213], v[16:19]
	v_mfma_f32_16x16x32_bf16 v[4:7], v[162:165], v[218:221], v[4:7]
	v_mfma_f32_16x16x32_bf16 v[0:3], v[170:173], v[218:221], v[0:3]
	s_setprio 0
	s_barrier
	s_add_i32 s60, 0, 0x18000
	s_add_i32 s61, 0, 0x1c000
	v_add_u32_e32 v154, s60, v188
	v_add_u32_e32 v170, s61, v188
	ds_read_b128 v[140:143], v154
	ds_read_b128 v[146:149], v154 offset:1024
	ds_read_b128 v[150:153], v154 offset:2048
	ds_read_b128 v[154:157], v154 offset:3072
	ds_read_b128 v[158:161], v170
	ds_read_b128 v[162:165], v170 offset:1024
	ds_read_b128 v[166:169], v170 offset:2048
	ds_read_b128 v[170:173], v170 offset:3072
	s_add_u32 s58, s84, 0x40000
	s_addc_u32 s59, s85, 0
	s_mov_b32 m0, s28
	v_lshl_add_u64 v[226:227], s[58:59], 0, v[134:135]
	ds_read_b128 v[174:177], v192 offset:32768
	ds_read_b128 v[178:181], v192 offset:33792
	ds_read_b128 v[182:185], v192 offset:34816
	ds_read_b128 v[194:197], v192 offset:35840
	ds_read_b128 v[206:209], v192 offset:36864
	ds_read_b128 v[210:213], v192 offset:37888
	ds_read_b128 v[214:217], v192 offset:38912
	ds_read_b128 v[218:221], v192 offset:39936
	global_load_lds_dwordx4 v[226:227], off
	v_lshl_add_u64 v[226:227], s[58:59], 0, v[130:131]
	s_mov_b32 m0, s29
	s_nop 0
	global_load_lds_dwordx4 v[226:227], off
	s_waitcnt vmcnt(8)
	s_waitcnt lgkmcnt(0)
	s_barrier
	s_setprio 1
	s_waitcnt lgkmcnt(0)
	v_mfma_f32_16x16x32_bf16 v[124:127], v[140:143], v[174:177], v[124:127]
	v_mfma_f32_16x16x32_bf16 v[120:123], v[150:153], v[174:177], v[120:123]
	v_mfma_f32_16x16x32_bf16 v[108:111], v[140:143], v[182:185], v[108:111]
	v_mfma_f32_16x16x32_bf16 v[104:107], v[150:153], v[182:185], v[104:107]
	v_mfma_f32_16x16x32_bf16 v[92:95], v[140:143], v[206:209], v[92:95]
	v_mfma_f32_16x16x32_bf16 v[88:91], v[150:153], v[206:209], v[88:91]
	v_mfma_f32_16x16x32_bf16 v[76:79], v[140:143], v[214:217], v[76:79]
	v_mfma_f32_16x16x32_bf16 v[72:75], v[150:153], v[214:217], v[72:75]
	v_mfma_f32_16x16x32_bf16 v[124:127], v[146:149], v[178:181], v[124:127]
	v_mfma_f32_16x16x32_bf16 v[120:123], v[154:157], v[178:181], v[120:123]
	v_mfma_f32_16x16x32_bf16 v[108:111], v[146:149], v[194:197], v[108:111]
	v_mfma_f32_16x16x32_bf16 v[104:107], v[154:157], v[194:197], v[104:107]
	v_mfma_f32_16x16x32_bf16 v[92:95], v[146:149], v[210:213], v[92:95]
	v_mfma_f32_16x16x32_bf16 v[88:91], v[154:157], v[210:213], v[88:91]
	v_mfma_f32_16x16x32_bf16 v[76:79], v[146:149], v[218:221], v[76:79]
	v_mfma_f32_16x16x32_bf16 v[72:75], v[154:157], v[218:221], v[72:75]
	s_setprio 0
	s_setprio 1
	v_mfma_f32_16x16x32_bf16 v[116:119], v[158:161], v[174:177], v[116:119]
	v_mfma_f32_16x16x32_bf16 v[112:115], v[166:169], v[174:177], v[112:115]
	v_mfma_f32_16x16x32_bf16 v[100:103], v[158:161], v[182:185], v[100:103]
	v_mfma_f32_16x16x32_bf16 v[96:99], v[166:169], v[182:185], v[96:99]
	v_mfma_f32_16x16x32_bf16 v[84:87], v[158:161], v[206:209], v[84:87]
	v_mfma_f32_16x16x32_bf16 v[80:83], v[166:169], v[206:209], v[80:83]
	v_mfma_f32_16x16x32_bf16 v[68:71], v[158:161], v[214:217], v[68:71]
	v_mfma_f32_16x16x32_bf16 v[64:67], v[166:169], v[214:217], v[64:67]
	v_mfma_f32_16x16x32_bf16 v[116:119], v[162:165], v[178:181], v[116:119]
	v_mfma_f32_16x16x32_bf16 v[112:115], v[170:173], v[178:181], v[112:115]
	v_mfma_f32_16x16x32_bf16 v[100:103], v[162:165], v[194:197], v[100:103]
	v_mfma_f32_16x16x32_bf16 v[96:99], v[170:173], v[194:197], v[96:99]
	v_mfma_f32_16x16x32_bf16 v[84:87], v[162:165], v[210:213], v[84:87]
	v_mfma_f32_16x16x32_bf16 v[80:83], v[170:173], v[210:213], v[80:83]
	v_mfma_f32_16x16x32_bf16 v[68:71], v[162:165], v[218:221], v[68:71]
	v_mfma_f32_16x16x32_bf16 v[64:67], v[170:173], v[218:221], v[64:67]
	s_setprio 0
	s_barrier
; #define PG8_STAGE(bufoff, gbase, voff) do { _Pragma("unroll") for (int _i = 0; _i < 2; ++_i) \
;         __builtin_amdgcn_global_load_lds((const unsigned*)((const char*)(gbase) + (voff)[_i]), (PG8_LAS unsigned*)(lds + (bufoff) + ldsw + _i * 8192), 16, 0, 0); } while (0)
; #define PG8_LDA(dst, b, h) do { _Pragma("unroll") for (int m = 0; m < 4; ++m) _Pragma("unroll") for (int k = 0; k < 2; ++k) dst[m][k] = *(const PG8_LAS bf16x8*)(lds + PG8_SA(b, h) + aoff + m * 2048 + k * 1024); } while (0)
; #define PG8_MMA(ai, bj, At, Bt) do { __builtin_amdgcn_s_setprio(1); _Pragma("unroll") for (int m = 0; m < 4; ++m) _Pragma("unroll") for (int n = 0; n < 2; ++n) _Pragma("unroll") for (int k = 0; k < 2; ++k) \
;         acc[ai][bj][m][n] = __builtin_amdgcn_mfma_f32_16x16x32_bf16(Bt[n][k], At[m][k], acc[ai][bj][m][n], 0, 0, 0); __builtin_amdgcn_s_setprio(0); } while (0)
; #define PG8_WAIT_V(n) asm volatile("s_waitcnt vmcnt(" #n ")" ::: "memory")
; #define PG8_WAIT_L(n) asm volatile("s_waitcnt lgkmcnt(" #n ")" ::: "memory")
; #define PG8_BAR __builtin_amdgcn_s_barrier()
; #define PG8_SCHED __builtin_amdgcn_sched_barrier(0)
; template <class Epi, class Sched, bool ALIGN_EPI = false, bool SP2 = false>
; __device__ __forceinline__ void gemm_phase(PG8_LAS unsigned char* lds, const Gemm g, const Sched& S, const Epi& E) {
;     ...
;         for (int t = 0; t < nt; t += 2) {
;     ...
;             PG8_LDA(At, 1, 1); PG8_STAGE(PG8_SB(1, 0), b3, voffB); PG8_STAGE(PG8_SB(1, 1), b3 + hstep, voffB); PG8_STAGE(PG8_SA(1, 0), a3, voffA);
;             PG8_WAIT_V(8); PG8_WAIT_L(0); PG8_BAR; PG8_MMA(1, 0, At, B0); PG8_MMA(1, 1, At, B1); PG8_BAR; PG8_SCHED;
	s_add_i32 s58, s60, s11
	v_lshl_add_u64 v[186:187], v[186:187], 0, s[66:67]
	s_mov_b32 m0, s58
	ds_read_b128 v[174:177], v192 offset:49152
	ds_read_b128 v[178:181], v192 offset:50176
	ds_read_b128 v[182:185], v192 offset:51200
	ds_read_b128 v[194:197], v192 offset:52224
	ds_read_b128 v[206:209], v192 offset:53248
	ds_read_b128 v[210:213], v192 offset:54272
	ds_read_b128 v[214:217], v192 offset:55296
	ds_read_b128 v[218:221], v192 offset:56320
	global_load_lds_dwordx4 v[186:187], off
	s_add_i32 m0, s58, 0x2000
	s_add_u32 s58, s82, 0x40080
	v_lshl_add_u64 v[186:187], v[198:199], 0, s[66:67]
	s_addc_u32 s59, s83, 0
	s_add_i32 s60, s61, s11
	global_load_lds_dwordx4 v[186:187], off
	v_lshl_add_u64 v[186:187], s[58:59], 0, v[132:133]
	s_mov_b32 m0, s60
	s_nop 0
	global_load_lds_dwordx4 v[186:187], off
	v_lshl_add_u64 v[186:187], s[58:59], 0, v[128:129]
	s_add_i32 m0, s60, 0x2000
	s_nop 0
	global_load_lds_dwordx4 v[186:187], off
	v_lshl_add_u64 v[186:187], v[222:223], 0, s[66:67]
	s_mov_b32 m0, s31
	s_nop 0
	global_load_lds_dwordx4 v[186:187], off
	v_lshl_add_u64 v[186:187], v[224:225], 0, s[66:67]
	s_mov_b32 m0, s37
	s_nop 0
	global_load_lds_dwordx4 v[186:187], off
	s_waitcnt vmcnt(8)
	s_waitcnt lgkmcnt(0)
	s_barrier
	s_setprio 1
	s_waitcnt lgkmcnt(0)
	v_mfma_f32_16x16x32_bf16 v[60:63], v[140:143], v[174:177], v[60:63]
	v_mfma_f32_16x16x32_bf16 v[56:59], v[150:153], v[174:177], v[56:59]
	v_mfma_f32_16x16x32_bf16 v[44:47], v[140:143], v[182:185], v[44:47]
	v_mfma_f32_16x16x32_bf16 v[40:43], v[150:153], v[182:185], v[40:43]
	v_mfma_f32_16x16x32_bf16 v[28:31], v[140:143], v[206:209], v[28:31]
	v_mfma_f32_16x16x32_bf16 v[24:27], v[150:153], v[206:209], v[24:27]
	v_mfma_f32_16x16x32_bf16 v[12:15], v[140:143], v[214:217], v[12:15]
	v_mfma_f32_16x16x32_bf16 v[8:11], v[150:153], v[214:217], v[8:11]
	v_mfma_f32_16x16x32_bf16 v[60:63], v[146:149], v[178:181], v[60:63]
	v_mfma_f32_16x16x32_bf16 v[56:59], v[154:157], v[178:181], v[56:59]
	v_mfma_f32_16x16x32_bf16 v[44:47], v[146:149], v[194:197], v[44:47]
	v_mfma_f32_16x16x32_bf16 v[40:43], v[154:157], v[194:197], v[40:43]
	v_mfma_f32_16x16x32_bf16 v[28:31], v[146:149], v[210:213], v[28:31]
	v_mfma_f32_16x16x32_bf16 v[24:27], v[154:157], v[210:213], v[24:27]
	v_mfma_f32_16x16x32_bf16 v[12:15], v[146:149], v[218:221], v[12:15]
	v_mfma_f32_16x16x32_bf16 v[8:11], v[154:157], v[218:221], v[8:11]
	s_setprio 0
	s_setprio 1
	v_mfma_f32_16x16x32_bf16 v[52:55], v[158:161], v[174:177], v[52:55]
	v_mfma_f32_16x16x32_bf16 v[48:51], v[166:169], v[174:177], v[48:51]
	v_mfma_f32_16x16x32_bf16 v[36:39], v[158:161], v[182:185], v[36:39]
	v_mfma_f32_16x16x32_bf16 v[32:35], v[166:169], v[182:185], v[32:35]
	v_mfma_f32_16x16x32_bf16 v[20:23], v[158:161], v[206:209], v[20:23]
	v_mfma_f32_16x16x32_bf16 v[16:19], v[166:169], v[206:209], v[16:19]
	v_mfma_f32_16x16x32_bf16 v[4:7], v[158:161], v[214:217], v[4:7]
	v_mfma_f32_16x16x32_bf16 v[0:3], v[166:169], v[214:217], v[0:3]
	v_mfma_f32_16x16x32_bf16 v[52:55], v[162:165], v[178:181], v[52:55]
	v_mfma_f32_16x16x32_bf16 v[48:51], v[170:173], v[178:181], v[48:51]
	v_mfma_f32_16x16x32_bf16 v[36:39], v[162:165], v[194:197], v[36:39]
	v_mfma_f32_16x16x32_bf16 v[32:35], v[170:173], v[194:197], v[32:35]
	v_mfma_f32_16x16x32_bf16 v[20:23], v[162:165], v[210:213], v[20:23]
	v_mfma_f32_16x16x32_bf16 v[16:19], v[170:173], v[210:213], v[16:19]
	v_mfma_f32_16x16x32_bf16 v[4:7], v[162:165], v[218:221], v[4:7]
	v_mfma_f32_16x16x32_bf16 v[0:3], v[170:173], v[218:221], v[0:3]
	s_setprio 0
	s_add_i32 s90, s90, 2
	s_add_u32 s80, s80, 0x100
	s_addc_u32 s81, s81, 0
	s_add_u32 s88, s88, 0x100
	s_addc_u32 s89, s89, 0
	s_barrier
	s_cmp_gt_u32 s90, 13
	s_cbranch_scc0 .LBB0_660
	s_and_b64 vcc, exec, s[68:69]
	s_cbranch_vccz .LBB0_663
	s_barrier

; #define PG8_STAGE(bufoff, gbase, voff) do { _Pragma("unroll") for (int _i = 0; _i < 2; ++_i) \
;         __builtin_amdgcn_global_load_lds((const unsigned*)((const char*)(gbase) + (voff)[_i]), (PG8_LAS unsigned*)(lds + (bufoff) + ldsw + _i * 8192), 16, 0, 0); } while (0)
; #define PG8_LDA(dst, b, h) do { _Pragma("unroll") for (int m = 0; m < 4; ++m) _Pragma("unroll") for (int k = 0; k < 2; ++k) dst[m][k] = *(const PG8_LAS bf16x8*)(lds + PG8_SA(b, h) + aoff + m * 2048 + k * 1024); } while (0)
; #define PG8_LDB(dst, b, h) do { _Pragma("unroll") for (int n = 0; n < 2; ++n) _Pragma("unroll") for (int k = 0; k < 2; ++k) dst[n][k] = *(const PG8_LAS bf16x8*)(lds + PG8_SB(b, h) + boff + n * 2048 + k * 1024); } while (0)
; #define PG8_MMA(ai, bj, At, Bt) do { __builtin_amdgcn_s_setprio(1); _Pragma("unroll") for (int m = 0; m < 4; ++m) _Pragma("unroll") for (int n = 0; n < 2; ++n) _Pragma("unroll") for (int k = 0; k < 2; ++k) \
;         acc[ai][bj][m][n] = __builtin_amdgcn_mfma_f32_16x16x32_bf16(Bt[n][k], At[m][k], acc[ai][bj][m][n], 0, 0, 0); __builtin_amdgcn_s_setprio(0); } while (0)
; #define PG8_WAIT_V(n) asm volatile("s_waitcnt vmcnt(" #n ")" ::: "memory")
; #define PG8_WAIT_L(n) asm volatile("s_waitcnt lgkmcnt(" #n ")" ::: "memory")
; template <class Epi, class Sched, bool ALIGN_EPI = false, bool SP2 = false>
; __device__ __forceinline__ void gemm_phase(PG8_LAS unsigned char* lds, const Gemm g, const Sched& S, const Epi& E) {
;     ...
;             const bool last = (t == nt - 2);
;             const char* a1 = cA + (size_t)(t + 1) * kstep;
;             const char* a2 = last ? nA : cA + (size_t)(t + 2) * kstep; const char* b2 = last ? nB : cB + (size_t)(t + 2) * kstep;
;             const char* a3 = a2 + kstep; const char* b3 = b2 + kstep;
;             if (last && has_next) S.a_ready(nxt);
;             if constexpr (SP2) {
;             PG8_LDB(B0, 0, 0); PG8_LDB(B1, 0, 1); PG8_SCHED; PG8_LDA(At, 0, 0); PG8_STAGE(PG8_SA(1, 1), a1 + hstep, voffA);
;             PG8_WAIT_V(8); PG8_WAIT_L(0); PG8_BAR; PG8_MMA(0, 0, At, B0); PG8_MMA(0, 1, At, B1); PG8_BAR; PG8_SCHED;
;             PG8_LDA(At, 0, 1); PG8_STAGE(PG8_SB(0, 0), b2, voffB); PG8_STAGE(PG8_SB(0, 1), b2 + hstep, voffB); PG8_STAGE(PG8_SA(0, 0), a2, voffA);
;             PG8_WAIT_V(8); PG8_WAIT_L(0); PG8_BAR; PG8_MMA(1, 0, At, B0); PG8_MMA(1, 1, At, B1); PG8_BAR; PG8_SCHED;
.LBB0_730:
	ds_read_b128 v[128:131], v167
	ds_read_b128 v[132:135], v167 offset:1024
	ds_read_b128 v[136:139], v167 offset:2048
	ds_read_b128 v[140:143], v167 offset:3072
	ds_read_b128 v[158:161], v168
	ds_read_b128 v[162:165], v168 offset:1024
	ds_read_b128 v[174:177], v168 offset:2048
	ds_read_b128 v[178:181], v168 offset:3072
	s_add_u32 s60, s76, 0xfff50080
	s_addc_u32 s61, s77, -1
	s_cmp_eq_u32 s59, 40
	s_cselect_b32 s81, s73, s61
	s_cselect_b32 s80, s72, s60
	s_cselect_b32 s79, s75, s58
	s_cselect_b32 s78, s74, s57
	s_mov_b32 m0, s84
	v_lshl_add_u64 v[198:199], s[76:77], 0, v[154:155]
	ds_read_b128 v[182:185], v169
	ds_read_b128 v[186:189], v169 offset:1024
	ds_read_b128 v[190:193], v169 offset:2048
	ds_read_b128 v[194:197], v169 offset:3072
	ds_read_b128 v[206:209], v169 offset:4096
	ds_read_b128 v[210:213], v169 offset:5120
	ds_read_b128 v[214:217], v169 offset:6144
	ds_read_b128 v[218:221], v169 offset:7168
	global_load_lds_dwordx4 v[198:199], off
	v_lshl_add_u64 v[198:199], s[76:77], 0, v[156:157]
	s_mov_b32 m0, s85
	s_nop 0
	global_load_lds_dwordx4 v[198:199], off
	s_waitcnt vmcnt(8)
	s_waitcnt lgkmcnt(0)
	s_barrier
	s_setprio 1
	s_waitcnt lgkmcnt(0)
	v_mfma_f32_16x16x32_bf16 v[124:127], v[128:131], v[182:185], v[124:127]
	v_mfma_f32_16x16x32_bf16 v[120:123], v[136:139], v[182:185], v[120:123]
	v_mfma_f32_16x16x32_bf16 v[108:111], v[128:131], v[190:193], v[108:111]
	v_mfma_f32_16x16x32_bf16 v[104:107], v[136:139], v[190:193], v[104:107]
	v_mfma_f32_16x16x32_bf16 v[92:95], v[128:131], v[206:209], v[92:95]
	v_mfma_f32_16x16x32_bf16 v[88:91], v[136:139], v[206:209], v[88:91]
	v_mfma_f32_16x16x32_bf16 v[76:79], v[128:131], v[214:217], v[76:79]
	v_mfma_f32_16x16x32_bf16 v[72:75], v[136:139], v[214:217], v[72:75]
	v_mfma_f32_16x16x32_bf16 v[124:127], v[132:135], v[186:189], v[124:127]
	v_mfma_f32_16x16x32_bf16 v[120:123], v[140:143], v[186:189], v[120:123]
	v_mfma_f32_16x16x32_bf16 v[108:111], v[132:135], v[194:197], v[108:111]
	v_mfma_f32_16x16x32_bf16 v[104:107], v[140:143], v[194:197], v[104:107]
	v_mfma_f32_16x16x32_bf16 v[92:95], v[132:135], v[210:213], v[92:95]
	v_mfma_f32_16x16x32_bf16 v[88:91], v[140:143], v[210:213], v[88:91]
	v_mfma_f32_16x16x32_bf16 v[76:79], v[132:135], v[218:221], v[76:79]
	v_mfma_f32_16x16x32_bf16 v[72:75], v[140:143], v[218:221], v[72:75]
	s_setprio 0
	s_setprio 1
	v_mfma_f32_16x16x32_bf16 v[116:119], v[158:161], v[182:185], v[116:119]
	v_mfma_f32_16x16x32_bf16 v[112:115], v[174:177], v[182:185], v[112:115]
	v_mfma_f32_16x16x32_bf16 v[100:103], v[158:161], v[190:193], v[100:103]
	v_mfma_f32_16x16x32_bf16 v[96:99], v[174:177], v[190:193], v[96:99]
	v_mfma_f32_16x16x32_bf16 v[84:87], v[158:161], v[206:209], v[84:87]
	v_mfma_f32_16x16x32_bf16 v[80:83], v[174:177], v[206:209], v[80:83]
	v_mfma_f32_16x16x32_bf16 v[68:71], v[158:161], v[214:217], v[68:71]
	v_mfma_f32_16x16x32_bf16 v[64:67], v[174:177], v[214:217], v[64:67]
	v_mfma_f32_16x16x32_bf16 v[116:119], v[162:165], v[186:189], v[116:119]
	v_mfma_f32_16x16x32_bf16 v[112:115], v[178:181], v[186:189], v[112:115]
	v_mfma_f32_16x16x32_bf16 v[100:103], v[162:165], v[194:197], v[100:103]
	v_mfma_f32_16x16x32_bf16 v[96:99], v[178:181], v[194:197], v[96:99]
	v_mfma_f32_16x16x32_bf16 v[84:87], v[162:165], v[210:213], v[84:87]
	v_mfma_f32_16x16x32_bf16 v[80:83], v[178:181], v[210:213], v[80:83]
	v_mfma_f32_16x16x32_bf16 v[68:71], v[162:165], v[218:221], v[68:71]
	v_mfma_f32_16x16x32_bf16 v[64:67], v[178:181], v[218:221], v[64:67]
	s_setprio 0
	s_barrier
	s_mov_b32 m0, s86
	v_lshl_add_u64 v[198:199], s[78:79], 0, v[148:149]
	s_add_u32 vcc_lo, s78, 0xb0000
	ds_read_b128 v[182:185], v169 offset:16384
	ds_read_b128 v[186:189], v169 offset:17408
	ds_read_b128 v[190:193], v169 offset:18432
	ds_read_b128 v[194:197], v169 offset:19456
	ds_read_b128 v[206:209], v169 offset:20480
	ds_read_b128 v[210:213], v169 offset:21504
	ds_read_b128 v[214:217], v169 offset:22528
	ds_read_b128 v[218:221], v169 offset:23552
	global_load_lds_dwordx4 v[198:199], off
	v_lshl_add_u64 v[222:223], s[78:79], 0, v[152:153]
	s_mov_b32 m0, s87
	s_addc_u32 vcc_hi, s79, 0
	global_load_lds_dwordx4 v[222:223], off
	v_lshl_add_u64 v[224:225], vcc, 0, v[148:149]
	s_mov_b32 m0, s88
	v_lshl_add_u64 v[226:227], s[80:81], 0, v[150:151]
	global_load_lds_dwordx4 v[224:225], off
	v_lshl_add_u64 v[224:225], vcc, 0, v[152:153]
	s_mov_b32 m0, s89
	s_nop 0
	global_load_lds_dwordx4 v[224:225], off
	v_lshl_add_u64 v[224:225], s[80:81], 0, v[146:147]
	s_mov_b32 m0, s29
	s_nop 0
	global_load_lds_dwordx4 v[224:225], off
	s_mov_b32 m0, s30
	s_nop 0
	global_load_lds_dwordx4 v[226:227], off
	s_waitcnt vmcnt(8)
	s_waitcnt lgkmcnt(0)
	s_barrier
; #define PG8_STAGE(bufoff, gbase, voff) do { _Pragma("unroll") for (int _i = 0; _i < 2; ++_i) \
;         __builtin_amdgcn_global_load_lds((const unsigned*)((const char*)(gbase) + (voff)[_i]), (PG8_LAS unsigned*)(lds + (bufoff) + ldsw + _i * 8192), 16, 0, 0); } while (0)
; #define PG8_LDA(dst, b, h) do { _Pragma("unroll") for (int m = 0; m < 4; ++m) _Pragma("unroll") for (int k = 0; k < 2; ++k) dst[m][k] = *(const PG8_LAS bf16x8*)(lds + PG8_SA(b, h) + aoff + m * 2048 + k * 1024); } while (0)
; #define PG8_LDB(dst, b, h) do { _Pragma("unroll") for (int n = 0; n < 2; ++n) _Pragma("unroll") for (int k = 0; k < 2; ++k) dst[n][k] = *(const PG8_LAS bf16x8*)(lds + PG8_SB(b, h) + boff + n * 2048 + k * 1024); } while (0)
; #define PG8_MMA(ai, bj, At, Bt) do { __builtin_amdgcn_s_setprio(1); _Pragma("unroll") for (int m = 0; m < 4; ++m) _Pragma("unroll") for (int n = 0; n < 2; ++n) _Pragma("unroll") for (int k = 0; k < 2; ++k) \
;         acc[ai][bj][m][n] = __builtin_amdgcn_mfma_f32_16x16x32_bf16(Bt[n][k], At[m][k], acc[ai][bj][m][n], 0, 0, 0); __builtin_amdgcn_s_setprio(0); } while (0)
; #define PG8_WAIT_V(n) asm volatile("s_waitcnt vmcnt(" #n ")" ::: "memory")
; #define PG8_WAIT_L(n) asm volatile("s_waitcnt lgkmcnt(" #n ")" ::: "memory")
; #define PG8_BAR __builtin_amdgcn_s_barrier()
; #define PG8_SCHED __builtin_amdgcn_sched_barrier(0)
; template <class Epi, class Sched, bool ALIGN_EPI = false, bool SP2 = false>
; __device__ __forceinline__ void gemm_phase(PG8_LAS unsigned char* lds, const Gemm g, const Sched& S, const Epi& E) {
;     ...
;             PG8_WAIT_V(8); PG8_WAIT_L(0); PG8_BAR; PG8_MMA(1, 0, At, B0); PG8_MMA(1, 1, At, B1); PG8_BAR; PG8_SCHED;
;             PG8_LDB(B0, 1, 0); PG8_LDB(B1, 1, 1); PG8_SCHED; PG8_LDA(At, 1, 0); PG8_STAGE(PG8_SA(0, 1), a2 + hstep, voffA);
;             PG8_WAIT_V(8); PG8_WAIT_L(0); PG8_BAR; PG8_MMA(0, 0, At, B0); PG8_MMA(0, 1, At, B1); PG8_BAR; PG8_SCHED;
	s_setprio 1
	s_waitcnt lgkmcnt(0)
	v_mfma_f32_16x16x32_bf16 v[60:63], v[128:131], v[182:185], v[60:63]
	v_mfma_f32_16x16x32_bf16 v[56:59], v[136:139], v[182:185], v[56:59]
	v_mfma_f32_16x16x32_bf16 v[44:47], v[128:131], v[190:193], v[44:47]
	v_mfma_f32_16x16x32_bf16 v[40:43], v[136:139], v[190:193], v[40:43]
	v_mfma_f32_16x16x32_bf16 v[32:35], v[128:131], v[206:209], v[32:35]
	v_mfma_f32_16x16x32_bf16 v[24:27], v[136:139], v[206:209], v[24:27]
	v_mfma_f32_16x16x32_bf16 v[16:19], v[128:131], v[214:217], v[16:19]
	v_mfma_f32_16x16x32_bf16 v[8:11], v[136:139], v[214:217], v[8:11]
	v_mfma_f32_16x16x32_bf16 v[60:63], v[132:135], v[186:189], v[60:63]
	v_mfma_f32_16x16x32_bf16 v[56:59], v[140:143], v[186:189], v[56:59]
	v_mfma_f32_16x16x32_bf16 v[44:47], v[132:135], v[194:197], v[44:47]
	v_mfma_f32_16x16x32_bf16 v[40:43], v[140:143], v[194:197], v[40:43]
	v_mfma_f32_16x16x32_bf16 v[32:35], v[132:135], v[210:213], v[32:35]
	v_mfma_f32_16x16x32_bf16 v[24:27], v[140:143], v[210:213], v[24:27]
	v_mfma_f32_16x16x32_bf16 v[16:19], v[132:135], v[218:221], v[16:19]
	v_mfma_f32_16x16x32_bf16 v[8:11], v[140:143], v[218:221], v[8:11]
	s_setprio 0
	s_setprio 1
	v_mfma_f32_16x16x32_bf16 v[52:55], v[158:161], v[182:185], v[52:55]
	v_mfma_f32_16x16x32_bf16 v[48:51], v[174:177], v[182:185], v[48:51]
	v_mfma_f32_16x16x32_bf16 v[36:39], v[158:161], v[190:193], v[36:39]
	v_mfma_f32_16x16x32_bf16 v[28:31], v[174:177], v[190:193], v[28:31]
	v_mfma_f32_16x16x32_bf16 v[20:23], v[158:161], v[206:209], v[20:23]
	v_mfma_f32_16x16x32_bf16 v[12:15], v[174:177], v[206:209], v[12:15]
	v_mfma_f32_16x16x32_bf16 v[4:7], v[158:161], v[214:217], v[4:7]
	v_mfma_f32_16x16x32_bf16 v[0:3], v[174:177], v[214:217], v[0:3]
	v_mfma_f32_16x16x32_bf16 v[52:55], v[162:165], v[186:189], v[52:55]
	v_mfma_f32_16x16x32_bf16 v[48:51], v[178:181], v[186:189], v[48:51]
	v_mfma_f32_16x16x32_bf16 v[36:39], v[162:165], v[194:197], v[36:39]
	v_mfma_f32_16x16x32_bf16 v[28:31], v[178:181], v[194:197], v[28:31]
	v_mfma_f32_16x16x32_bf16 v[20:23], v[162:165], v[210:213], v[20:23]
	v_mfma_f32_16x16x32_bf16 v[12:15], v[178:181], v[210:213], v[12:15]
	v_mfma_f32_16x16x32_bf16 v[4:7], v[162:165], v[218:221], v[4:7]
	v_mfma_f32_16x16x32_bf16 v[0:3], v[178:181], v[218:221], v[0:3]
	s_setprio 0
	s_barrier
	ds_read_b128 v[128:131], v171
	ds_read_b128 v[132:135], v171 offset:1024
	ds_read_b128 v[136:139], v171 offset:2048
	ds_read_b128 v[140:143], v171 offset:3072
	ds_read_b128 v[158:161], v172
	ds_read_b128 v[162:165], v172 offset:1024
	ds_read_b128 v[174:177], v172 offset:2048
	ds_read_b128 v[178:181], v172 offset:3072
	s_add_u32 s80, s80, 0xb0000
	s_addc_u32 s81, s81, 0
	s_mov_b32 m0, s31
	v_lshl_add_u64 v[228:229], s[80:81], 0, v[146:147]
	ds_read_b128 v[182:185], v169 offset:32768
	ds_read_b128 v[186:189], v169 offset:33792
	ds_read_b128 v[190:193], v169 offset:34816
	ds_read_b128 v[194:197], v169 offset:35840
	ds_read_b128 v[206:209], v169 offset:36864
	ds_read_b128 v[210:213], v169 offset:37888
	ds_read_b128 v[214:217], v169 offset:38912
	ds_read_b128 v[218:221], v169 offset:39936
	global_load_lds_dwordx4 v[228:229], off
	v_lshl_add_u64 v[228:229], s[80:81], 0, v[150:151]
	s_mov_b32 m0, s37
	s_nop 0
	global_load_lds_dwordx4 v[228:229], off
	s_waitcnt vmcnt(8)
	s_waitcnt lgkmcnt(0)
	s_barrier
	s_setprio 1
	s_waitcnt lgkmcnt(0)
	v_mfma_f32_16x16x32_bf16 v[124:127], v[128:131], v[182:185], v[124:127]
	v_mfma_f32_16x16x32_bf16 v[120:123], v[136:139], v[182:185], v[120:123]
	v_mfma_f32_16x16x32_bf16 v[108:111], v[128:131], v[190:193], v[108:111]
	v_mfma_f32_16x16x32_bf16 v[104:107], v[136:139], v[190:193], v[104:107]
	v_mfma_f32_16x16x32_bf16 v[92:95], v[128:131], v[206:209], v[92:95]
	v_mfma_f32_16x16x32_bf16 v[88:91], v[136:139], v[206:209], v[88:91]
	v_mfma_f32_16x16x32_bf16 v[76:79], v[128:131], v[214:217], v[76:79]
	v_mfma_f32_16x16x32_bf16 v[72:75], v[136:139], v[214:217], v[72:75]
	v_mfma_f32_16x16x32_bf16 v[124:127], v[132:135], v[186:189], v[124:127]
	v_mfma_f32_16x16x32_bf16 v[120:123], v[140:143], v[186:189], v[120:123]
	v_mfma_f32_16x16x32_bf16 v[108:111], v[132:135], v[194:197], v[108:111]
	v_mfma_f32_16x16x32_bf16 v[104:107], v[140:143], v[194:197], v[104:107]
	v_mfma_f32_16x16x32_bf16 v[92:95], v[132:135], v[210:213], v[92:95]
	v_mfma_f32_16x16x32_bf16 v[88:91], v[140:143], v[210:213], v[88:91]
	v_mfma_f32_16x16x32_bf16 v[76:79], v[132:135], v[218:221], v[76:79]
	v_mfma_f32_16x16x32_bf16 v[72:75], v[140:143], v[218:221], v[72:75]
	s_setprio 0
	s_setprio 1
	v_mfma_f32_16x16x32_bf16 v[116:119], v[158:161], v[182:185], v[116:119]
	v_mfma_f32_16x16x32_bf16 v[112:115], v[174:177], v[182:185], v[112:115]
	v_mfma_f32_16x16x32_bf16 v[100:103], v[158:161], v[190:193], v[100:103]
	v_mfma_f32_16x16x32_bf16 v[96:99], v[174:177], v[190:193], v[96:99]
	v_mfma_f32_16x16x32_bf16 v[84:87], v[158:161], v[206:209], v[84:87]
	v_mfma_f32_16x16x32_bf16 v[80:83], v[174:177], v[206:209], v[80:83]
	v_mfma_f32_16x16x32_bf16 v[68:71], v[158:161], v[214:217], v[68:71]
	v_mfma_f32_16x16x32_bf16 v[64:67], v[174:177], v[214:217], v[64:67]
	v_mfma_f32_16x16x32_bf16 v[116:119], v[162:165], v[186:189], v[116:119]
	v_mfma_f32_16x16x32_bf16 v[112:115], v[178:181], v[186:189], v[112:115]
	v_mfma_f32_16x16x32_bf16 v[100:103], v[162:165], v[194:197], v[100:103]
	v_mfma_f32_16x16x32_bf16 v[96:99], v[178:181], v[194:197], v[96:99]
	v_mfma_f32_16x16x32_bf16 v[84:87], v[162:165], v[210:213], v[84:87]
	v_mfma_f32_16x16x32_bf16 v[80:83], v[178:181], v[210:213], v[80:83]
	v_mfma_f32_16x16x32_bf16 v[68:71], v[162:165], v[218:221], v[68:71]
	v_mfma_f32_16x16x32_bf16 v[64:67], v[178:181], v[218:221], v[64:67]
	s_setprio 0
	s_barrier
; #define PG8_STAGE(bufoff, gbase, voff) do { _Pragma("unroll") for (int _i = 0; _i < 2; ++_i) \
;         __builtin_amdgcn_global_load_lds((const unsigned*)((const char*)(gbase) + (voff)[_i]), (PG8_LAS unsigned*)(lds + (bufoff) + ldsw + _i * 8192), 16, 0, 0); } while (0)
; #define PG8_LDA(dst, b, h) do { _Pragma("unroll") for (int m = 0; m < 4; ++m) _Pragma("unroll") for (int k = 0; k < 2; ++k) dst[m][k] = *(const PG8_LAS bf16x8*)(lds + PG8_SA(b, h) + aoff + m * 2048 + k * 1024); } while (0)
; #define PG8_MMA(ai, bj, At, Bt) do { __builtin_amdgcn_s_setprio(1); _Pragma("unroll") for (int m = 0; m < 4; ++m) _Pragma("unroll") for (int n = 0; n < 2; ++n) _Pragma("unroll") for (int k = 0; k < 2; ++k) \
;         acc[ai][bj][m][n] = __builtin_amdgcn_mfma_f32_16x16x32_bf16(Bt[n][k], At[m][k], acc[ai][bj][m][n], 0, 0, 0); __builtin_amdgcn_s_setprio(0); } while (0)
; #define PG8_WAIT_V(n) asm volatile("s_waitcnt vmcnt(" #n ")" ::: "memory")
; #define PG8_WAIT_L(n) asm volatile("s_waitcnt lgkmcnt(" #n ")" ::: "memory")
; #define PG8_BAR __builtin_amdgcn_s_barrier()
; #define PG8_SCHED __builtin_amdgcn_sched_barrier(0)
; template <class Epi, class Sched, bool ALIGN_EPI = false, bool SP2 = false>
; __device__ __forceinline__ void gemm_phase(PG8_LAS unsigned char* lds, const Gemm g, const Sched& S, const Epi& E) {
;     ...
;         for (int t = 0; t < nt; t += 2) {
;     ...
;             PG8_LDA(At, 1, 1); PG8_STAGE(PG8_SB(1, 0), b3, voffB); PG8_STAGE(PG8_SB(1, 1), b3 + hstep, voffB); PG8_STAGE(PG8_SA(1, 0), a3, voffA);
;             PG8_WAIT_V(8); PG8_WAIT_L(0); PG8_BAR; PG8_MMA(1, 0, At, B0); PG8_MMA(1, 1, At, B1); PG8_BAR; PG8_SCHED;
	s_add_i32 s60, s90, s28
	v_lshl_add_u64 v[198:199], v[198:199], 0, s[68:69]
	s_mov_b32 m0, s60
	ds_read_b128 v[182:185], v169 offset:49152
	ds_read_b128 v[186:189], v169 offset:50176
	ds_read_b128 v[190:193], v169 offset:51200
	ds_read_b128 v[194:197], v169 offset:52224
	ds_read_b128 v[206:209], v169 offset:53248
	ds_read_b128 v[210:213], v169 offset:54272
	ds_read_b128 v[214:217], v169 offset:55296
	ds_read_b128 v[218:221], v169 offset:56320
	global_load_lds_dwordx4 v[198:199], off
	s_add_i32 m0, s60, 0x2000
	s_add_u32 s78, s78, 0xb0080
	v_lshl_add_u64 v[198:199], v[222:223], 0, s[68:69]
	s_addc_u32 s79, s79, 0
	s_add_i32 s60, s91, s28
	global_load_lds_dwordx4 v[198:199], off
	v_lshl_add_u64 v[198:199], s[78:79], 0, v[148:149]
	s_mov_b32 m0, s60
	s_nop 0
	global_load_lds_dwordx4 v[198:199], off
	v_lshl_add_u64 v[198:199], s[78:79], 0, v[152:153]
	s_add_i32 m0, s60, 0x2000
	s_nop 0
	global_load_lds_dwordx4 v[198:199], off
	v_lshl_add_u64 v[198:199], v[224:225], 0, s[68:69]
	s_mov_b32 m0, s82
	s_nop 0
	global_load_lds_dwordx4 v[198:199], off
	v_lshl_add_u64 v[198:199], v[226:227], 0, s[68:69]
	s_mov_b32 m0, s83
	s_nop 0
	global_load_lds_dwordx4 v[198:199], off
	s_waitcnt vmcnt(8)
	s_waitcnt lgkmcnt(0)
	s_barrier
	s_setprio 1
	s_waitcnt lgkmcnt(0)
	v_mfma_f32_16x16x32_bf16 v[60:63], v[128:131], v[182:185], v[60:63]
	v_mfma_f32_16x16x32_bf16 v[56:59], v[136:139], v[182:185], v[56:59]
	v_mfma_f32_16x16x32_bf16 v[44:47], v[128:131], v[190:193], v[44:47]
	v_mfma_f32_16x16x32_bf16 v[40:43], v[136:139], v[190:193], v[40:43]
	v_mfma_f32_16x16x32_bf16 v[32:35], v[128:131], v[206:209], v[32:35]
	v_mfma_f32_16x16x32_bf16 v[24:27], v[136:139], v[206:209], v[24:27]
	v_mfma_f32_16x16x32_bf16 v[16:19], v[128:131], v[214:217], v[16:19]
	v_mfma_f32_16x16x32_bf16 v[8:11], v[136:139], v[214:217], v[8:11]
	v_mfma_f32_16x16x32_bf16 v[60:63], v[132:135], v[186:189], v[60:63]
	v_mfma_f32_16x16x32_bf16 v[56:59], v[140:143], v[186:189], v[56:59]
	v_mfma_f32_16x16x32_bf16 v[44:47], v[132:135], v[194:197], v[44:47]
	v_mfma_f32_16x16x32_bf16 v[40:43], v[140:143], v[194:197], v[40:43]
	v_mfma_f32_16x16x32_bf16 v[32:35], v[132:135], v[210:213], v[32:35]
	v_mfma_f32_16x16x32_bf16 v[24:27], v[140:143], v[210:213], v[24:27]
	v_mfma_f32_16x16x32_bf16 v[16:19], v[132:135], v[218:221], v[16:19]
	v_mfma_f32_16x16x32_bf16 v[8:11], v[140:143], v[218:221], v[8:11]
	s_setprio 0
	s_setprio 1
	v_mfma_f32_16x16x32_bf16 v[52:55], v[158:161], v[182:185], v[52:55]
	v_mfma_f32_16x16x32_bf16 v[48:51], v[174:177], v[182:185], v[48:51]
	v_mfma_f32_16x16x32_bf16 v[36:39], v[158:161], v[190:193], v[36:39]
	v_mfma_f32_16x16x32_bf16 v[28:31], v[174:177], v[190:193], v[28:31]
	v_mfma_f32_16x16x32_bf16 v[20:23], v[158:161], v[206:209], v[20:23]
	v_mfma_f32_16x16x32_bf16 v[12:15], v[174:177], v[206:209], v[12:15]
	v_mfma_f32_16x16x32_bf16 v[4:7], v[158:161], v[214:217], v[4:7]
	v_mfma_f32_16x16x32_bf16 v[0:3], v[174:177], v[214:217], v[0:3]
	v_mfma_f32_16x16x32_bf16 v[52:55], v[162:165], v[186:189], v[52:55]
	v_mfma_f32_16x16x32_bf16 v[48:51], v[178:181], v[186:189], v[48:51]
	v_mfma_f32_16x16x32_bf16 v[36:39], v[162:165], v[194:197], v[36:39]
	v_mfma_f32_16x16x32_bf16 v[28:31], v[178:181], v[194:197], v[28:31]
	v_mfma_f32_16x16x32_bf16 v[20:23], v[162:165], v[210:213], v[20:23]
	v_mfma_f32_16x16x32_bf16 v[12:15], v[178:181], v[210:213], v[12:15]
	v_mfma_f32_16x16x32_bf16 v[4:7], v[162:165], v[218:221], v[4:7]
	v_mfma_f32_16x16x32_bf16 v[0:3], v[178:181], v[218:221], v[0:3]
	s_setprio 0
	s_add_i32 s59, s59, 2
	s_add_u32 s76, s76, 0x100
	s_addc_u32 s77, s77, 0
	s_add_u32 s57, s57, 0x100
	s_addc_u32 s58, s58, 0
	s_barrier
	s_cmp_gt_u32 s59, 41
	s_cbranch_scc0 .LBB0_730
	s_and_b64 vcc, exec, s[70:71]
	s_cbranch_vccz .LBB0_733
	s_barrier

; #define PG8_STAGE(bufoff, gbase, voff) do { _Pragma("unroll") for (int _i = 0; _i < 2; ++_i) \
;         __builtin_amdgcn_global_load_lds((const unsigned*)((const char*)(gbase) + (voff)[_i]), (PG8_LAS unsigned*)(lds + (bufoff) + ldsw + _i * 8192), 16, 0, 0); } while (0)
; #define PG8_LDA(dst, b, h) do { _Pragma("unroll") for (int m = 0; m < 4; ++m) _Pragma("unroll") for (int k = 0; k < 2; ++k) dst[m][k] = *(const PG8_LAS bf16x8*)(lds + PG8_SA(b, h) + aoff + m * 2048 + k * 1024); } while (0)
; #define PG8_LDB(dst, b, h) do { _Pragma("unroll") for (int n = 0; n < 2; ++n) _Pragma("unroll") for (int k = 0; k < 2; ++k) dst[n][k] = *(const PG8_LAS bf16x8*)(lds + PG8_SB(b, h) + boff + n * 2048 + k * 1024); } while (0)
; #define PG8_MMA(ai, bj, At, Bt) do { __builtin_amdgcn_s_setprio(1); _Pragma("unroll") for (int m = 0; m < 4; ++m) _Pragma("unroll") for (int n = 0; n < 2; ++n) _Pragma("unroll") for (int k = 0; k < 2; ++k) \
;         acc[ai][bj][m][n] = __builtin_amdgcn_mfma_f32_16x16x32_bf16(Bt[n][k], At[m][k], acc[ai][bj][m][n], 0, 0, 0); __builtin_amdgcn_s_setprio(0); } while (0)
; #define PG8_WAIT_V(n) asm volatile("s_waitcnt vmcnt(" #n ")" ::: "memory")
; #define PG8_WAIT_L(n) asm volatile("s_waitcnt lgkmcnt(" #n ")" ::: "memory")
; template <class Epi, class Sched, bool ALIGN_EPI = false, bool SP2 = false>
; __device__ __forceinline__ void gemm_phase(PG8_LAS unsigned char* lds, const Gemm g, const Sched& S, const Epi& E) {
;     ...
;             const bool last = (t == nt - 2);
;             const char* a1 = cA + (size_t)(t + 1) * kstep;
;             const char* a2 = last ? nA : cA + (size_t)(t + 2) * kstep; const char* b2 = last ? nB : cB + (size_t)(t + 2) * kstep;
;             const char* a3 = a2 + kstep; const char* b3 = b2 + kstep;
;             if (last && has_next) S.a_ready(nxt);
;             if constexpr (SP2) {
;             PG8_LDB(B0, 0, 0); PG8_LDB(B1, 0, 1); PG8_SCHED; PG8_LDA(At, 0, 0); PG8_STAGE(PG8_SA(1, 1), a1 + hstep, voffA);
;             PG8_WAIT_V(8); PG8_WAIT_L(0); PG8_BAR; PG8_MMA(0, 0, At, B0); PG8_MMA(0, 1, At, B1); PG8_BAR; PG8_SCHED;
;             PG8_LDA(At, 0, 1); PG8_STAGE(PG8_SB(0, 0), b2, voffB); PG8_STAGE(PG8_SB(0, 1), b2 + hstep, voffB); PG8_STAGE(PG8_SA(0, 0), a2, voffA);
;             PG8_WAIT_V(8); PG8_WAIT_L(0); PG8_BAR; PG8_MMA(1, 0, At, B0); PG8_MMA(1, 1, At, B1); PG8_BAR; PG8_SCHED;
.LBB0_958:
	ds_read_b128 v[140:143], v163
	ds_read_b128 v[146:149], v163 offset:1024
	ds_read_b128 v[150:153], v163 offset:2048
	ds_read_b128 v[154:157], v163 offset:3072
	ds_read_b128 v[168:171], v164
	ds_read_b128 v[172:175], v164 offset:1024
	ds_read_b128 v[176:179], v164 offset:2048
	ds_read_b128 v[180:183], v164 offset:3072
	s_add_u32 s59, s86, 0xfffc0080
	s_addc_u32 s60, s87, -1
	s_cmp_eq_u32 s58, 12
	s_cselect_b32 s91, s7, s60
	s_cselect_b32 s90, s75, s59
	s_cselect_b32 s89, s77, vcc_hi
	s_cselect_b32 s88, s85, vcc_lo
	v_lshl_add_u64 v[158:159], s[86:87], 0, v[136:137]
	s_add_i32 m0, s20, 0xc000
	ds_read_b128 v[184:187], v165
	ds_read_b128 v[188:191], v165 offset:1024
	ds_read_b128 v[192:195], v165 offset:2048
	ds_read_b128 v[196:199], v165 offset:3072
	ds_read_b128 v[206:209], v165 offset:4096
	ds_read_b128 v[210:213], v165 offset:5120
	ds_read_b128 v[214:217], v165 offset:6144
	ds_read_b128 v[218:221], v165 offset:7168
	global_load_lds_dwordx4 v[158:159], off
	v_lshl_add_u64 v[158:159], s[86:87], 0, v[138:139]
	s_add_i32 m0, s20, 0xe000
	s_nop 0
	global_load_lds_dwordx4 v[158:159], off
	s_waitcnt vmcnt(8)
	s_waitcnt lgkmcnt(0)
	s_barrier
	s_setprio 1
	s_waitcnt lgkmcnt(0)
	v_mfma_f32_16x16x32_bf16 v[124:127], v[140:143], v[184:187], v[124:127]
	v_mfma_f32_16x16x32_bf16 v[120:123], v[150:153], v[184:187], v[120:123]
	v_mfma_f32_16x16x32_bf16 v[108:111], v[140:143], v[192:195], v[108:111]
	v_mfma_f32_16x16x32_bf16 v[104:107], v[150:153], v[192:195], v[104:107]
	v_mfma_f32_16x16x32_bf16 v[92:95], v[140:143], v[206:209], v[92:95]
	v_mfma_f32_16x16x32_bf16 v[88:91], v[150:153], v[206:209], v[88:91]
	v_mfma_f32_16x16x32_bf16 v[76:79], v[140:143], v[214:217], v[76:79]
	v_mfma_f32_16x16x32_bf16 v[72:75], v[150:153], v[214:217], v[72:75]
	v_mfma_f32_16x16x32_bf16 v[124:127], v[146:149], v[188:191], v[124:127]
	v_mfma_f32_16x16x32_bf16 v[120:123], v[154:157], v[188:191], v[120:123]
	v_mfma_f32_16x16x32_bf16 v[108:111], v[146:149], v[196:199], v[108:111]
	v_mfma_f32_16x16x32_bf16 v[104:107], v[154:157], v[196:199], v[104:107]
	v_mfma_f32_16x16x32_bf16 v[92:95], v[146:149], v[210:213], v[92:95]
	v_mfma_f32_16x16x32_bf16 v[88:91], v[154:157], v[210:213], v[88:91]
	v_mfma_f32_16x16x32_bf16 v[76:79], v[146:149], v[218:221], v[76:79]
	v_mfma_f32_16x16x32_bf16 v[72:75], v[154:157], v[218:221], v[72:75]
	s_setprio 0
	s_setprio 1
	v_mfma_f32_16x16x32_bf16 v[116:119], v[168:171], v[184:187], v[116:119]
	v_mfma_f32_16x16x32_bf16 v[112:115], v[176:179], v[184:187], v[112:115]
	v_mfma_f32_16x16x32_bf16 v[100:103], v[168:171], v[192:195], v[100:103]
	v_mfma_f32_16x16x32_bf16 v[96:99], v[176:179], v[192:195], v[96:99]
	v_mfma_f32_16x16x32_bf16 v[84:87], v[168:171], v[206:209], v[84:87]
	v_mfma_f32_16x16x32_bf16 v[80:83], v[176:179], v[206:209], v[80:83]
	v_mfma_f32_16x16x32_bf16 v[68:71], v[168:171], v[214:217], v[68:71]
	v_mfma_f32_16x16x32_bf16 v[64:67], v[176:179], v[214:217], v[64:67]
	v_mfma_f32_16x16x32_bf16 v[116:119], v[172:175], v[188:191], v[116:119]
	v_mfma_f32_16x16x32_bf16 v[112:115], v[180:183], v[188:191], v[112:115]
	v_mfma_f32_16x16x32_bf16 v[100:103], v[172:175], v[196:199], v[100:103]
	v_mfma_f32_16x16x32_bf16 v[96:99], v[180:183], v[196:199], v[96:99]
	v_mfma_f32_16x16x32_bf16 v[84:87], v[172:175], v[210:213], v[84:87]
	v_mfma_f32_16x16x32_bf16 v[80:83], v[180:183], v[210:213], v[80:83]
	v_mfma_f32_16x16x32_bf16 v[68:71], v[172:175], v[218:221], v[68:71]
	v_mfma_f32_16x16x32_bf16 v[64:67], v[180:183], v[218:221], v[64:67]
	s_setprio 0
	s_barrier
	s_add_i32 s59, s39, s11
	v_lshl_add_u64 v[158:159], s[88:89], 0, v[130:131]
	s_mov_b32 m0, s59
	ds_read_b128 v[184:187], v165 offset:16384
	ds_read_b128 v[188:191], v165 offset:17408
	ds_read_b128 v[192:195], v165 offset:18432
	ds_read_b128 v[196:199], v165 offset:19456
	ds_read_b128 v[206:209], v165 offset:20480
	ds_read_b128 v[210:213], v165 offset:21504
	ds_read_b128 v[214:217], v165 offset:22528
	ds_read_b128 v[218:221], v165 offset:23552
	global_load_lds_dwordx4 v[158:159], off
	s_add_i32 m0, s59, 0x2000
	s_add_u32 s60, s88, 0x40000
	v_lshl_add_u64 v[222:223], s[88:89], 0, v[134:135]
	s_addc_u32 s61, s89, 0
	s_add_i32 s59, s56, s11
	global_load_lds_dwordx4 v[222:223], off
	v_lshl_add_u64 v[224:225], s[60:61], 0, v[130:131]
	s_mov_b32 m0, s59
	v_lshl_add_u64 v[226:227], s[90:91], 0, v[132:133]
	global_load_lds_dwordx4 v[224:225], off
	v_lshl_add_u64 v[224:225], s[60:61], 0, v[134:135]
	s_add_i32 m0, s59, 0x2000
	s_nop 0
	global_load_lds_dwordx4 v[224:225], off
	v_lshl_add_u64 v[224:225], s[90:91], 0, v[128:129]
	s_mov_b32 m0, s20
	s_nop 0
	global_load_lds_dwordx4 v[224:225], off
	s_mov_b32 m0, s21
	s_nop 0
	global_load_lds_dwordx4 v[226:227], off
	s_waitcnt vmcnt(8)
	s_waitcnt lgkmcnt(0)
	s_barrier
; #define PG8_STAGE(bufoff, gbase, voff) do { _Pragma("unroll") for (int _i = 0; _i < 2; ++_i) \
;         __builtin_amdgcn_global_load_lds((const unsigned*)((const char*)(gbase) + (voff)[_i]), (PG8_LAS unsigned*)(lds + (bufoff) + ldsw + _i * 8192), 16, 0, 0); } while (0)
; #define PG8_LDA(dst, b, h) do { _Pragma("unroll") for (int m = 0; m < 4; ++m) _Pragma("unroll") for (int k = 0; k < 2; ++k) dst[m][k] = *(const PG8_LAS bf16x8*)(lds + PG8_SA(b, h) + aoff + m * 2048 + k * 1024); } while (0)
; #define PG8_LDB(dst, b, h) do { _Pragma("unroll") for (int n = 0; n < 2; ++n) _Pragma("unroll") for (int k = 0; k < 2; ++k) dst[n][k] = *(const PG8_LAS bf16x8*)(lds + PG8_SB(b, h) + boff + n * 2048 + k * 1024); } while (0)
; #define PG8_MMA(ai, bj, At, Bt) do { __builtin_amdgcn_s_setprio(1); _Pragma("unroll") for (int m = 0; m < 4; ++m) _Pragma("unroll") for (int n = 0; n < 2; ++n) _Pragma("unroll") for (int k = 0; k < 2; ++k) \
;         acc[ai][bj][m][n] = __builtin_amdgcn_mfma_f32_16x16x32_bf16(Bt[n][k], At[m][k], acc[ai][bj][m][n], 0, 0, 0); __builtin_amdgcn_s_setprio(0); } while (0)
; #define PG8_WAIT_V(n) asm volatile("s_waitcnt vmcnt(" #n ")" ::: "memory")
; #define PG8_WAIT_L(n) asm volatile("s_waitcnt lgkmcnt(" #n ")" ::: "memory")
; #define PG8_BAR __builtin_amdgcn_s_barrier()
; #define PG8_SCHED __builtin_amdgcn_sched_barrier(0)
; template <class Epi, class Sched, bool ALIGN_EPI = false, bool SP2 = false>
; __device__ __forceinline__ void gemm_phase(PG8_LAS unsigned char* lds, const Gemm g, const Sched& S, const Epi& E) {
;     ...
;             PG8_WAIT_V(8); PG8_WAIT_L(0); PG8_BAR; PG8_MMA(1, 0, At, B0); PG8_MMA(1, 1, At, B1); PG8_BAR; PG8_SCHED;
;             PG8_LDB(B0, 1, 0); PG8_LDB(B1, 1, 1); PG8_SCHED; PG8_LDA(At, 1, 0); PG8_STAGE(PG8_SA(0, 1), a2 + hstep, voffA);
;             PG8_WAIT_V(8); PG8_WAIT_L(0); PG8_BAR; PG8_MMA(0, 0, At, B0); PG8_MMA(0, 1, At, B1); PG8_BAR; PG8_SCHED;
	s_setprio 1
	s_waitcnt lgkmcnt(0)
	v_mfma_f32_16x16x32_bf16 v[60:63], v[140:143], v[184:187], v[60:63]
	v_mfma_f32_16x16x32_bf16 v[56:59], v[150:153], v[184:187], v[56:59]
	v_mfma_f32_16x16x32_bf16 v[44:47], v[140:143], v[192:195], v[44:47]
	v_mfma_f32_16x16x32_bf16 v[40:43], v[150:153], v[192:195], v[40:43]
	v_mfma_f32_16x16x32_bf16 v[28:31], v[140:143], v[206:209], v[28:31]
	v_mfma_f32_16x16x32_bf16 v[24:27], v[150:153], v[206:209], v[24:27]
	v_mfma_f32_16x16x32_bf16 v[12:15], v[140:143], v[214:217], v[12:15]
	v_mfma_f32_16x16x32_bf16 v[8:11], v[150:153], v[214:217], v[8:11]
	v_mfma_f32_16x16x32_bf16 v[60:63], v[146:149], v[188:191], v[60:63]
	v_mfma_f32_16x16x32_bf16 v[56:59], v[154:157], v[188:191], v[56:59]
	v_mfma_f32_16x16x32_bf16 v[44:47], v[146:149], v[196:199], v[44:47]
	v_mfma_f32_16x16x32_bf16 v[40:43], v[154:157], v[196:199], v[40:43]
	v_mfma_f32_16x16x32_bf16 v[28:31], v[146:149], v[210:213], v[28:31]
	v_mfma_f32_16x16x32_bf16 v[24:27], v[154:157], v[210:213], v[24:27]
	v_mfma_f32_16x16x32_bf16 v[12:15], v[146:149], v[218:221], v[12:15]
	v_mfma_f32_16x16x32_bf16 v[8:11], v[154:157], v[218:221], v[8:11]
	s_setprio 0
	s_setprio 1
	v_mfma_f32_16x16x32_bf16 v[52:55], v[168:171], v[184:187], v[52:55]
	v_mfma_f32_16x16x32_bf16 v[48:51], v[176:179], v[184:187], v[48:51]
	v_mfma_f32_16x16x32_bf16 v[36:39], v[168:171], v[192:195], v[36:39]
	v_mfma_f32_16x16x32_bf16 v[32:35], v[176:179], v[192:195], v[32:35]
	v_mfma_f32_16x16x32_bf16 v[20:23], v[168:171], v[206:209], v[20:23]
	v_mfma_f32_16x16x32_bf16 v[16:19], v[176:179], v[206:209], v[16:19]
	v_mfma_f32_16x16x32_bf16 v[4:7], v[168:171], v[214:217], v[4:7]
	v_mfma_f32_16x16x32_bf16 v[0:3], v[176:179], v[214:217], v[0:3]
	v_mfma_f32_16x16x32_bf16 v[52:55], v[172:175], v[188:191], v[52:55]
	v_mfma_f32_16x16x32_bf16 v[48:51], v[180:183], v[188:191], v[48:51]
	v_mfma_f32_16x16x32_bf16 v[36:39], v[172:175], v[196:199], v[36:39]
	v_mfma_f32_16x16x32_bf16 v[32:35], v[180:183], v[196:199], v[32:35]
	v_mfma_f32_16x16x32_bf16 v[20:23], v[172:175], v[210:213], v[20:23]
	v_mfma_f32_16x16x32_bf16 v[16:19], v[180:183], v[210:213], v[16:19]
	v_mfma_f32_16x16x32_bf16 v[4:7], v[172:175], v[218:221], v[4:7]
	v_mfma_f32_16x16x32_bf16 v[0:3], v[180:183], v[218:221], v[0:3]
	s_setprio 0
	s_barrier
	s_add_i32 s59, 0, 0x18000
	s_add_i32 s96, 0, 0x1c000
	v_add_u32_e32 v154, s59, v161
	v_add_u32_e32 v180, s96, v161
	ds_read_b128 v[140:143], v154
	ds_read_b128 v[146:149], v154 offset:1024
	ds_read_b128 v[150:153], v154 offset:2048
	ds_read_b128 v[154:157], v154 offset:3072
	ds_read_b128 v[168:171], v180
	ds_read_b128 v[172:175], v180 offset:1024
	ds_read_b128 v[176:179], v180 offset:2048
	ds_read_b128 v[180:183], v180 offset:3072
	s_add_u32 s60, s90, 0x40000
	s_addc_u32 s61, s91, 0
	s_mov_b32 m0, s28
	v_lshl_add_u64 v[228:229], s[60:61], 0, v[128:129]
	ds_read_b128 v[184:187], v165 offset:32768
	ds_read_b128 v[188:191], v165 offset:33792
	ds_read_b128 v[192:195], v165 offset:34816
	ds_read_b128 v[196:199], v165 offset:35840
	ds_read_b128 v[206:209], v165 offset:36864
	ds_read_b128 v[210:213], v165 offset:37888
	ds_read_b128 v[214:217], v165 offset:38912
	ds_read_b128 v[218:221], v165 offset:39936
	global_load_lds_dwordx4 v[228:229], off
	v_lshl_add_u64 v[228:229], s[60:61], 0, v[132:133]
	s_mov_b32 m0, s29
	s_nop 0
	global_load_lds_dwordx4 v[228:229], off
	s_waitcnt vmcnt(8)
	s_waitcnt lgkmcnt(0)
	s_barrier
	s_setprio 1
	s_waitcnt lgkmcnt(0)
	v_mfma_f32_16x16x32_bf16 v[124:127], v[140:143], v[184:187], v[124:127]
	v_mfma_f32_16x16x32_bf16 v[120:123], v[150:153], v[184:187], v[120:123]
	v_mfma_f32_16x16x32_bf16 v[108:111], v[140:143], v[192:195], v[108:111]
	v_mfma_f32_16x16x32_bf16 v[104:107], v[150:153], v[192:195], v[104:107]
	v_mfma_f32_16x16x32_bf16 v[92:95], v[140:143], v[206:209], v[92:95]
	v_mfma_f32_16x16x32_bf16 v[88:91], v[150:153], v[206:209], v[88:91]
	v_mfma_f32_16x16x32_bf16 v[76:79], v[140:143], v[214:217], v[76:79]
	v_mfma_f32_16x16x32_bf16 v[72:75], v[150:153], v[214:217], v[72:75]
	v_mfma_f32_16x16x32_bf16 v[124:127], v[146:149], v[188:191], v[124:127]
	v_mfma_f32_16x16x32_bf16 v[120:123], v[154:157], v[188:191], v[120:123]
	v_mfma_f32_16x16x32_bf16 v[108:111], v[146:149], v[196:199], v[108:111]
	v_mfma_f32_16x16x32_bf16 v[104:107], v[154:157], v[196:199], v[104:107]
	v_mfma_f32_16x16x32_bf16 v[92:95], v[146:149], v[210:213], v[92:95]
	v_mfma_f32_16x16x32_bf16 v[88:91], v[154:157], v[210:213], v[88:91]
	v_mfma_f32_16x16x32_bf16 v[76:79], v[146:149], v[218:221], v[76:79]
	v_mfma_f32_16x16x32_bf16 v[72:75], v[154:157], v[218:221], v[72:75]
	s_setprio 0
	s_setprio 1
	v_mfma_f32_16x16x32_bf16 v[116:119], v[168:171], v[184:187], v[116:119]
	v_mfma_f32_16x16x32_bf16 v[112:115], v[176:179], v[184:187], v[112:115]
	v_mfma_f32_16x16x32_bf16 v[100:103], v[168:171], v[192:195], v[100:103]
	v_mfma_f32_16x16x32_bf16 v[96:99], v[176:179], v[192:195], v[96:99]
	v_mfma_f32_16x16x32_bf16 v[84:87], v[168:171], v[206:209], v[84:87]
	v_mfma_f32_16x16x32_bf16 v[80:83], v[176:179], v[206:209], v[80:83]
	v_mfma_f32_16x16x32_bf16 v[68:71], v[168:171], v[214:217], v[68:71]
	v_mfma_f32_16x16x32_bf16 v[64:67], v[176:179], v[214:217], v[64:67]
	v_mfma_f32_16x16x32_bf16 v[116:119], v[172:175], v[188:191], v[116:119]
	v_mfma_f32_16x16x32_bf16 v[112:115], v[180:183], v[188:191], v[112:115]
	v_mfma_f32_16x16x32_bf16 v[100:103], v[172:175], v[196:199], v[100:103]
	v_mfma_f32_16x16x32_bf16 v[96:99], v[180:183], v[196:199], v[96:99]
	v_mfma_f32_16x16x32_bf16 v[84:87], v[172:175], v[210:213], v[84:87]
	v_mfma_f32_16x16x32_bf16 v[80:83], v[180:183], v[210:213], v[80:83]
	v_mfma_f32_16x16x32_bf16 v[68:71], v[172:175], v[218:221], v[68:71]
	v_mfma_f32_16x16x32_bf16 v[64:67], v[180:183], v[218:221], v[64:67]
	s_setprio 0
	s_barrier
; #define PG8_STAGE(bufoff, gbase, voff) do { _Pragma("unroll") for (int _i = 0; _i < 2; ++_i) \
;         __builtin_amdgcn_global_load_lds((const unsigned*)((const char*)(gbase) + (voff)[_i]), (PG8_LAS unsigned*)(lds + (bufoff) + ldsw + _i * 8192), 16, 0, 0); } while (0)
; #define PG8_LDA(dst, b, h) do { _Pragma("unroll") for (int m = 0; m < 4; ++m) _Pragma("unroll") for (int k = 0; k < 2; ++k) dst[m][k] = *(const PG8_LAS bf16x8*)(lds + PG8_SA(b, h) + aoff + m * 2048 + k * 1024); } while (0)
; #define PG8_MMA(ai, bj, At, Bt) do { __builtin_amdgcn_s_setprio(1); _Pragma("unroll") for (int m = 0; m < 4; ++m) _Pragma("unroll") for (int n = 0; n < 2; ++n) _Pragma("unroll") for (int k = 0; k < 2; ++k) \
;         acc[ai][bj][m][n] = __builtin_amdgcn_mfma_f32_16x16x32_bf16(Bt[n][k], At[m][k], acc[ai][bj][m][n], 0, 0, 0); __builtin_amdgcn_s_setprio(0); } while (0)
; #define PG8_WAIT_V(n) asm volatile("s_waitcnt vmcnt(" #n ")" ::: "memory")
; #define PG8_WAIT_L(n) asm volatile("s_waitcnt lgkmcnt(" #n ")" ::: "memory")
; #define PG8_BAR __builtin_amdgcn_s_barrier()
; #define PG8_SCHED __builtin_amdgcn_sched_barrier(0)
; template <class Epi, class Sched, bool ALIGN_EPI = false, bool SP2 = false>
; __device__ __forceinline__ void gemm_phase(PG8_LAS unsigned char* lds, const Gemm g, const Sched& S, const Epi& E) {
;     ...
;         for (int t = 0; t < nt; t += 2) {
;     ...
;             PG8_LDA(At, 1, 1); PG8_STAGE(PG8_SB(1, 0), b3, voffB); PG8_STAGE(PG8_SB(1, 1), b3 + hstep, voffB); PG8_STAGE(PG8_SA(1, 0), a3, voffA);
;             PG8_WAIT_V(8); PG8_WAIT_L(0); PG8_BAR; PG8_MMA(1, 0, At, B0); PG8_MMA(1, 1, At, B1); PG8_BAR; PG8_SCHED;
	s_add_i32 s59, s59, s11
	v_lshl_add_u64 v[158:159], v[158:159], 0, s[70:71]
	s_mov_b32 m0, s59
	ds_read_b128 v[184:187], v165 offset:49152
	ds_read_b128 v[188:191], v165 offset:50176
	ds_read_b128 v[192:195], v165 offset:51200
	ds_read_b128 v[196:199], v165 offset:52224
	ds_read_b128 v[206:209], v165 offset:53248
	ds_read_b128 v[210:213], v165 offset:54272
	ds_read_b128 v[214:217], v165 offset:55296
	ds_read_b128 v[218:221], v165 offset:56320
	global_load_lds_dwordx4 v[158:159], off
	s_add_i32 m0, s59, 0x2000
	s_add_u32 s60, s88, 0x40080
	v_lshl_add_u64 v[158:159], v[222:223], 0, s[70:71]
	s_addc_u32 s61, s89, 0
	s_add_i32 s59, s96, s11
	global_load_lds_dwordx4 v[158:159], off
	v_lshl_add_u64 v[158:159], s[60:61], 0, v[130:131]
	s_mov_b32 m0, s59
	s_nop 0
	global_load_lds_dwordx4 v[158:159], off
	v_lshl_add_u64 v[158:159], s[60:61], 0, v[134:135]
	s_add_i32 m0, s59, 0x2000
	s_nop 0
	global_load_lds_dwordx4 v[158:159], off
	v_lshl_add_u64 v[158:159], v[224:225], 0, s[70:71]
	s_mov_b32 m0, s31
	s_nop 0
	global_load_lds_dwordx4 v[158:159], off
	v_lshl_add_u64 v[158:159], v[226:227], 0, s[70:71]
	s_mov_b32 m0, s37
	s_nop 0
	global_load_lds_dwordx4 v[158:159], off
	s_waitcnt vmcnt(8)
	s_waitcnt lgkmcnt(0)
	s_barrier
	s_setprio 1
	s_waitcnt lgkmcnt(0)
	v_mfma_f32_16x16x32_bf16 v[60:63], v[140:143], v[184:187], v[60:63]
	v_mfma_f32_16x16x32_bf16 v[56:59], v[150:153], v[184:187], v[56:59]
	v_mfma_f32_16x16x32_bf16 v[44:47], v[140:143], v[192:195], v[44:47]
	v_mfma_f32_16x16x32_bf16 v[40:43], v[150:153], v[192:195], v[40:43]
	v_mfma_f32_16x16x32_bf16 v[28:31], v[140:143], v[206:209], v[28:31]
	v_mfma_f32_16x16x32_bf16 v[24:27], v[150:153], v[206:209], v[24:27]
	v_mfma_f32_16x16x32_bf16 v[12:15], v[140:143], v[214:217], v[12:15]
	v_mfma_f32_16x16x32_bf16 v[8:11], v[150:153], v[214:217], v[8:11]
	v_mfma_f32_16x16x32_bf16 v[60:63], v[146:149], v[188:191], v[60:63]
	v_mfma_f32_16x16x32_bf16 v[56:59], v[154:157], v[188:191], v[56:59]
	v_mfma_f32_16x16x32_bf16 v[44:47], v[146:149], v[196:199], v[44:47]
	v_mfma_f32_16x16x32_bf16 v[40:43], v[154:157], v[196:199], v[40:43]
	v_mfma_f32_16x16x32_bf16 v[28:31], v[146:149], v[210:213], v[28:31]
	v_mfma_f32_16x16x32_bf16 v[24:27], v[154:157], v[210:213], v[24:27]
	v_mfma_f32_16x16x32_bf16 v[12:15], v[146:149], v[218:221], v[12:15]
	v_mfma_f32_16x16x32_bf16 v[8:11], v[154:157], v[218:221], v[8:11]
	s_setprio 0
	s_setprio 1
	v_mfma_f32_16x16x32_bf16 v[52:55], v[168:171], v[184:187], v[52:55]
	v_mfma_f32_16x16x32_bf16 v[48:51], v[176:179], v[184:187], v[48:51]
	v_mfma_f32_16x16x32_bf16 v[36:39], v[168:171], v[192:195], v[36:39]
	v_mfma_f32_16x16x32_bf16 v[32:35], v[176:179], v[192:195], v[32:35]
	v_mfma_f32_16x16x32_bf16 v[20:23], v[168:171], v[206:209], v[20:23]
	v_mfma_f32_16x16x32_bf16 v[16:19], v[176:179], v[206:209], v[16:19]
	v_mfma_f32_16x16x32_bf16 v[4:7], v[168:171], v[214:217], v[4:7]
	v_mfma_f32_16x16x32_bf16 v[0:3], v[176:179], v[214:217], v[0:3]
	v_mfma_f32_16x16x32_bf16 v[52:55], v[172:175], v[188:191], v[52:55]
	v_mfma_f32_16x16x32_bf16 v[48:51], v[180:183], v[188:191], v[48:51]
	v_mfma_f32_16x16x32_bf16 v[36:39], v[172:175], v[196:199], v[36:39]
	v_mfma_f32_16x16x32_bf16 v[32:35], v[180:183], v[196:199], v[32:35]
	v_mfma_f32_16x16x32_bf16 v[20:23], v[172:175], v[210:213], v[20:23]
	v_mfma_f32_16x16x32_bf16 v[16:19], v[180:183], v[210:213], v[16:19]
	v_mfma_f32_16x16x32_bf16 v[4:7], v[172:175], v[218:221], v[4:7]
	v_mfma_f32_16x16x32_bf16 v[0:3], v[180:183], v[218:221], v[0:3]
	s_setprio 0
	s_add_i32 s58, s58, 2
	s_add_u32 s86, s86, 0x100
	s_addc_u32 s87, s87, 0
	s_add_u32 vcc_lo, vcc_lo, 0x100
	s_addc_u32 vcc_hi, vcc_hi, 0
	s_barrier
	s_cmp_gt_u32 s58, 13
	s_cbranch_scc0 .LBB0_958
	s_and_b64 vcc, exec, s[72:73]
	s_cbranch_vccz .LBB0_961
	s_barrier

; #define PG8_STAGE(bufoff, gbase, voff) do { _Pragma("unroll") for (int _i = 0; _i < 2; ++_i) \
;         __builtin_amdgcn_global_load_lds((const unsigned*)((const char*)(gbase) + (voff)[_i]), (PG8_LAS unsigned*)(lds + (bufoff) + ldsw + _i * 8192), 16, 0, 0); } while (0)
; #define PG8_LDA(dst, b, h) do { _Pragma("unroll") for (int m = 0; m < 4; ++m) _Pragma("unroll") for (int k = 0; k < 2; ++k) dst[m][k] = *(const PG8_LAS bf16x8*)(lds + PG8_SA(b, h) + aoff + m * 2048 + k * 1024); } while (0)
; #define PG8_LDB(dst, b, h) do { _Pragma("unroll") for (int n = 0; n < 2; ++n) _Pragma("unroll") for (int k = 0; k < 2; ++k) dst[n][k] = *(const PG8_LAS bf16x8*)(lds + PG8_SB(b, h) + boff + n * 2048 + k * 1024); } while (0)
; #define PG8_MMA(ai, bj, At, Bt) do { __builtin_amdgcn_s_setprio(1); _Pragma("unroll") for (int m = 0; m < 4; ++m) _Pragma("unroll") for (int n = 0; n < 2; ++n) _Pragma("unroll") for (int k = 0; k < 2; ++k) \
;         acc[ai][bj][m][n] = __builtin_amdgcn_mfma_f32_16x16x32_bf16(Bt[n][k], At[m][k], acc[ai][bj][m][n], 0, 0, 0); __builtin_amdgcn_s_setprio(0); } while (0)
; #define PG8_WAIT_V(n) asm volatile("s_waitcnt vmcnt(" #n ")" ::: "memory")
; #define PG8_WAIT_L(n) asm volatile("s_waitcnt lgkmcnt(" #n ")" ::: "memory")
; template <class Epi, class Sched, bool ALIGN_EPI = false, bool SP2 = false>
; __device__ __forceinline__ void gemm_phase(PG8_LAS unsigned char* lds, const Gemm g, const Sched& S, const Epi& E) {
;     ...
;             const bool last = (t == nt - 2);
;             const char* a1 = cA + (size_t)(t + 1) * kstep;
;             const char* a2 = last ? nA : cA + (size_t)(t + 2) * kstep; const char* b2 = last ? nB : cB + (size_t)(t + 2) * kstep;
;             const char* a3 = a2 + kstep; const char* b3 = b2 + kstep;
;             if (last && has_next) S.a_ready(nxt);
;             if constexpr (SP2) {
;             PG8_LDB(B0, 0, 0); PG8_LDB(B1, 0, 1); PG8_SCHED; PG8_LDA(At, 0, 0); PG8_STAGE(PG8_SA(1, 1), a1 + hstep, voffA);
;             PG8_WAIT_V(8); PG8_WAIT_L(0); PG8_BAR; PG8_MMA(0, 0, At, B0); PG8_MMA(0, 1, At, B1); PG8_BAR; PG8_SCHED;
;             PG8_LDA(At, 0, 1); PG8_STAGE(PG8_SB(0, 0), b2, voffB); PG8_STAGE(PG8_SB(0, 1), b2 + hstep, voffB); PG8_STAGE(PG8_SA(0, 0), a2, voffA);
;             PG8_WAIT_V(8); PG8_WAIT_L(0); PG8_BAR; PG8_MMA(1, 0, At, B0); PG8_MMA(1, 1, At, B1); PG8_BAR; PG8_SCHED;
.LBB0_1215:
	ds_read_b128 v[140:143], v149
	ds_read_b128 v[154:157], v149 offset:1024
	ds_read_b128 v[158:161], v149 offset:2048
	ds_read_b128 v[162:165], v149 offset:3072
	ds_read_b128 v[166:169], v150
	ds_read_b128 v[170:173], v150 offset:1024
	ds_read_b128 v[174:177], v150 offset:2048
	ds_read_b128 v[178:181], v150 offset:3072
	s_add_u32 s60, s58, 0xfffc0080
	s_addc_u32 s61, s59, -1
	s_cmp_eq_u32 s75, 12
	s_cselect_b32 s63, s17, s61
	s_cselect_b32 s62, s51, s60
	s_cselect_b32 s61, s19, s74
	s_cselect_b32 s60, s72, s73
	v_lshl_add_u64 v[144:145], s[58:59], 0, v[136:137]
	s_add_i32 m0, s28, 0xc000
	ds_read_b128 v[182:185], v151
	ds_read_b128 v[186:189], v151 offset:1024
	ds_read_b128 v[190:193], v151 offset:2048
	ds_read_b128 v[194:197], v151 offset:3072
	ds_read_b128 v[202:205], v151 offset:4096
	ds_read_b128 v[206:209], v151 offset:5120
	ds_read_b128 v[210:213], v151 offset:6144
	ds_read_b128 v[214:217], v151 offset:7168
	global_load_lds_dwordx4 v[144:145], off
	v_lshl_add_u64 v[144:145], s[58:59], 0, v[138:139]
	s_add_i32 m0, s28, 0xe000
	s_nop 0
	global_load_lds_dwordx4 v[144:145], off
	s_waitcnt vmcnt(8)
	s_waitcnt lgkmcnt(0)
	s_barrier
	s_setprio 1
	s_waitcnt lgkmcnt(0)
	v_mfma_f32_16x16x32_bf16 v[124:127], v[140:143], v[182:185], v[124:127]
	v_mfma_f32_16x16x32_bf16 v[120:123], v[158:161], v[182:185], v[120:123]
	v_mfma_f32_16x16x32_bf16 v[108:111], v[140:143], v[190:193], v[108:111]
	v_mfma_f32_16x16x32_bf16 v[104:107], v[158:161], v[190:193], v[104:107]
	v_mfma_f32_16x16x32_bf16 v[96:99], v[140:143], v[202:205], v[96:99]
	v_mfma_f32_16x16x32_bf16 v[88:91], v[158:161], v[202:205], v[88:91]
	v_mfma_f32_16x16x32_bf16 v[80:83], v[140:143], v[210:213], v[80:83]
	v_mfma_f32_16x16x32_bf16 v[72:75], v[158:161], v[210:213], v[72:75]
	v_mfma_f32_16x16x32_bf16 v[124:127], v[154:157], v[186:189], v[124:127]
	v_mfma_f32_16x16x32_bf16 v[120:123], v[162:165], v[186:189], v[120:123]
	v_mfma_f32_16x16x32_bf16 v[108:111], v[154:157], v[194:197], v[108:111]
	v_mfma_f32_16x16x32_bf16 v[104:107], v[162:165], v[194:197], v[104:107]
	v_mfma_f32_16x16x32_bf16 v[96:99], v[154:157], v[206:209], v[96:99]
	v_mfma_f32_16x16x32_bf16 v[88:91], v[162:165], v[206:209], v[88:91]
	v_mfma_f32_16x16x32_bf16 v[80:83], v[154:157], v[214:217], v[80:83]
	v_mfma_f32_16x16x32_bf16 v[72:75], v[162:165], v[214:217], v[72:75]
	s_setprio 0
	s_setprio 1
	v_mfma_f32_16x16x32_bf16 v[116:119], v[166:169], v[182:185], v[116:119]
	v_mfma_f32_16x16x32_bf16 v[112:115], v[174:177], v[182:185], v[112:115]
	v_mfma_f32_16x16x32_bf16 v[100:103], v[166:169], v[190:193], v[100:103]
	v_mfma_f32_16x16x32_bf16 v[92:95], v[174:177], v[190:193], v[92:95]
	v_mfma_f32_16x16x32_bf16 v[84:87], v[166:169], v[202:205], v[84:87]
	v_mfma_f32_16x16x32_bf16 v[76:79], v[174:177], v[202:205], v[76:79]
	v_mfma_f32_16x16x32_bf16 v[68:71], v[166:169], v[210:213], v[68:71]
	v_mfma_f32_16x16x32_bf16 v[64:67], v[174:177], v[210:213], v[64:67]
	v_mfma_f32_16x16x32_bf16 v[116:119], v[170:173], v[186:189], v[116:119]
	v_mfma_f32_16x16x32_bf16 v[112:115], v[178:181], v[186:189], v[112:115]
	v_mfma_f32_16x16x32_bf16 v[100:103], v[170:173], v[194:197], v[100:103]
	v_mfma_f32_16x16x32_bf16 v[92:95], v[178:181], v[194:197], v[92:95]
	v_mfma_f32_16x16x32_bf16 v[84:87], v[170:173], v[206:209], v[84:87]
	v_mfma_f32_16x16x32_bf16 v[76:79], v[178:181], v[206:209], v[76:79]
	v_mfma_f32_16x16x32_bf16 v[68:71], v[170:173], v[214:217], v[68:71]
	v_mfma_f32_16x16x32_bf16 v[64:67], v[178:181], v[214:217], v[64:67]
	s_setprio 0
	s_barrier
	s_add_i32 s76, s66, s21
	v_lshl_add_u64 v[144:145], s[60:61], 0, v[130:131]
	s_mov_b32 m0, s76
	ds_read_b128 v[182:185], v151 offset:16384
	ds_read_b128 v[186:189], v151 offset:17408
	ds_read_b128 v[190:193], v151 offset:18432
	ds_read_b128 v[194:197], v151 offset:19456
	ds_read_b128 v[202:205], v151 offset:20480
	ds_read_b128 v[206:209], v151 offset:21504
	ds_read_b128 v[210:213], v151 offset:22528
	ds_read_b128 v[214:217], v151 offset:23552
	global_load_lds_dwordx4 v[144:145], off
	s_add_i32 m0, s76, 0x2000
	s_add_u32 s76, s60, 0x40000
	v_lshl_add_u64 v[198:199], s[60:61], 0, v[134:135]
	s_addc_u32 s77, s61, 0
	s_add_i32 s78, s67, s21
	global_load_lds_dwordx4 v[198:199], off
	v_lshl_add_u64 v[218:219], s[76:77], 0, v[130:131]
	s_mov_b32 m0, s78
	v_lshl_add_u64 v[220:221], s[62:63], 0, v[132:133]
	global_load_lds_dwordx4 v[218:219], off
	v_lshl_add_u64 v[218:219], s[76:77], 0, v[134:135]
	s_add_i32 m0, s78, 0x2000
	s_nop 0
	global_load_lds_dwordx4 v[218:219], off
	v_lshl_add_u64 v[218:219], s[62:63], 0, v[128:129]
	s_mov_b32 m0, s28
	s_nop 0
	global_load_lds_dwordx4 v[218:219], off
	s_mov_b32 m0, s29
	s_nop 0
	global_load_lds_dwordx4 v[220:221], off
	s_waitcnt vmcnt(8)
	s_waitcnt lgkmcnt(0)
	s_barrier
; #define PG8_STAGE(bufoff, gbase, voff) do { _Pragma("unroll") for (int _i = 0; _i < 2; ++_i) \
;         __builtin_amdgcn_global_load_lds((const unsigned*)((const char*)(gbase) + (voff)[_i]), (PG8_LAS unsigned*)(lds + (bufoff) + ldsw + _i * 8192), 16, 0, 0); } while (0)
; #define PG8_LDA(dst, b, h) do { _Pragma("unroll") for (int m = 0; m < 4; ++m) _Pragma("unroll") for (int k = 0; k < 2; ++k) dst[m][k] = *(const PG8_LAS bf16x8*)(lds + PG8_SA(b, h) + aoff + m * 2048 + k * 1024); } while (0)
; #define PG8_LDB(dst, b, h) do { _Pragma("unroll") for (int n = 0; n < 2; ++n) _Pragma("unroll") for (int k = 0; k < 2; ++k) dst[n][k] = *(const PG8_LAS bf16x8*)(lds + PG8_SB(b, h) + boff + n * 2048 + k * 1024); } while (0)
; #define PG8_MMA(ai, bj, At, Bt) do { __builtin_amdgcn_s_setprio(1); _Pragma("unroll") for (int m = 0; m < 4; ++m) _Pragma("unroll") for (int n = 0; n < 2; ++n) _Pragma("unroll") for (int k = 0; k < 2; ++k) \
;         acc[ai][bj][m][n] = __builtin_amdgcn_mfma_f32_16x16x32_bf16(Bt[n][k], At[m][k], acc[ai][bj][m][n], 0, 0, 0); __builtin_amdgcn_s_setprio(0); } while (0)
; #define PG8_WAIT_V(n) asm volatile("s_waitcnt vmcnt(" #n ")" ::: "memory")
; #define PG8_WAIT_L(n) asm volatile("s_waitcnt lgkmcnt(" #n ")" ::: "memory")
; #define PG8_BAR __builtin_amdgcn_s_barrier()
; #define PG8_SCHED __builtin_amdgcn_sched_barrier(0)
; template <class Epi, class Sched, bool ALIGN_EPI = false, bool SP2 = false>
; __device__ __forceinline__ void gemm_phase(PG8_LAS unsigned char* lds, const Gemm g, const Sched& S, const Epi& E) {
;     ...
;             PG8_WAIT_V(8); PG8_WAIT_L(0); PG8_BAR; PG8_MMA(1, 0, At, B0); PG8_MMA(1, 1, At, B1); PG8_BAR; PG8_SCHED;
;             PG8_LDB(B0, 1, 0); PG8_LDB(B1, 1, 1); PG8_SCHED; PG8_LDA(At, 1, 0); PG8_STAGE(PG8_SA(0, 1), a2 + hstep, voffA);
;             PG8_WAIT_V(8); PG8_WAIT_L(0); PG8_BAR; PG8_MMA(0, 0, At, B0); PG8_MMA(0, 1, At, B1); PG8_BAR; PG8_SCHED;
	s_setprio 1
	s_waitcnt lgkmcnt(0)
	v_mfma_f32_16x16x32_bf16 v[60:63], v[140:143], v[182:185], v[60:63]
	v_mfma_f32_16x16x32_bf16 v[56:59], v[158:161], v[182:185], v[56:59]
	v_mfma_f32_16x16x32_bf16 v[48:51], v[140:143], v[190:193], v[48:51]
	v_mfma_f32_16x16x32_bf16 v[40:43], v[158:161], v[190:193], v[40:43]
	v_mfma_f32_16x16x32_bf16 v[32:35], v[140:143], v[202:205], v[32:35]
	v_mfma_f32_16x16x32_bf16 v[24:27], v[158:161], v[202:205], v[24:27]
	v_mfma_f32_16x16x32_bf16 v[16:19], v[140:143], v[210:213], v[16:19]
	v_mfma_f32_16x16x32_bf16 v[8:11], v[158:161], v[210:213], v[8:11]
	v_mfma_f32_16x16x32_bf16 v[60:63], v[154:157], v[186:189], v[60:63]
	v_mfma_f32_16x16x32_bf16 v[56:59], v[162:165], v[186:189], v[56:59]
	v_mfma_f32_16x16x32_bf16 v[48:51], v[154:157], v[194:197], v[48:51]
	v_mfma_f32_16x16x32_bf16 v[40:43], v[162:165], v[194:197], v[40:43]
	v_mfma_f32_16x16x32_bf16 v[32:35], v[154:157], v[206:209], v[32:35]
	v_mfma_f32_16x16x32_bf16 v[24:27], v[162:165], v[206:209], v[24:27]
	v_mfma_f32_16x16x32_bf16 v[16:19], v[154:157], v[214:217], v[16:19]
	v_mfma_f32_16x16x32_bf16 v[8:11], v[162:165], v[214:217], v[8:11]
	s_setprio 0
	s_setprio 1
	v_mfma_f32_16x16x32_bf16 v[52:55], v[166:169], v[182:185], v[52:55]
	v_mfma_f32_16x16x32_bf16 v[44:47], v[174:177], v[182:185], v[44:47]
	v_mfma_f32_16x16x32_bf16 v[36:39], v[166:169], v[190:193], v[36:39]
	v_mfma_f32_16x16x32_bf16 v[28:31], v[174:177], v[190:193], v[28:31]
	v_mfma_f32_16x16x32_bf16 v[20:23], v[166:169], v[202:205], v[20:23]
	v_mfma_f32_16x16x32_bf16 v[12:15], v[174:177], v[202:205], v[12:15]
	v_mfma_f32_16x16x32_bf16 v[4:7], v[166:169], v[210:213], v[4:7]
	v_mfma_f32_16x16x32_bf16 v[0:3], v[174:177], v[210:213], v[0:3]
	v_mfma_f32_16x16x32_bf16 v[52:55], v[170:173], v[186:189], v[52:55]
	v_mfma_f32_16x16x32_bf16 v[44:47], v[178:181], v[186:189], v[44:47]
	v_mfma_f32_16x16x32_bf16 v[36:39], v[170:173], v[194:197], v[36:39]
	v_mfma_f32_16x16x32_bf16 v[28:31], v[178:181], v[194:197], v[28:31]
	v_mfma_f32_16x16x32_bf16 v[20:23], v[170:173], v[206:209], v[20:23]
	v_mfma_f32_16x16x32_bf16 v[12:15], v[178:181], v[206:209], v[12:15]
	v_mfma_f32_16x16x32_bf16 v[4:7], v[170:173], v[214:217], v[4:7]
	v_mfma_f32_16x16x32_bf16 v[0:3], v[178:181], v[214:217], v[0:3]
	s_setprio 0
	s_barrier
	s_add_i32 s76, 0, 0x18000
	v_add_u32_e32 v153, s76, v147
	s_add_i32 s77, 0, 0x1c000
	ds_read_b128 v[140:143], v153
	ds_read_b128 v[154:157], v153 offset:1024
	ds_read_b128 v[158:161], v153 offset:2048
	ds_read_b128 v[162:165], v153 offset:3072
	v_add_u32_e32 v153, s77, v147
	ds_read_b128 v[166:169], v153
	ds_read_b128 v[170:173], v153 offset:1024
	ds_read_b128 v[174:177], v153 offset:2048
	ds_read_b128 v[178:181], v153 offset:3072
	s_add_u32 s62, s62, 0x40000
	s_addc_u32 s63, s63, 0
	s_mov_b32 m0, s30
	v_lshl_add_u64 v[222:223], s[62:63], 0, v[128:129]
	ds_read_b128 v[182:185], v151 offset:32768
	ds_read_b128 v[186:189], v151 offset:33792
	ds_read_b128 v[190:193], v151 offset:34816
	ds_read_b128 v[194:197], v151 offset:35840
	ds_read_b128 v[202:205], v151 offset:36864
	ds_read_b128 v[206:209], v151 offset:37888
	ds_read_b128 v[210:213], v151 offset:38912
	ds_read_b128 v[214:217], v151 offset:39936
	global_load_lds_dwordx4 v[222:223], off
	v_lshl_add_u64 v[222:223], s[62:63], 0, v[132:133]
	s_mov_b32 m0, s31
	s_nop 0
	global_load_lds_dwordx4 v[222:223], off
	s_waitcnt vmcnt(8)
	s_waitcnt lgkmcnt(0)
	s_barrier
	s_setprio 1
	s_waitcnt lgkmcnt(0)
	v_mfma_f32_16x16x32_bf16 v[124:127], v[140:143], v[182:185], v[124:127]
	v_mfma_f32_16x16x32_bf16 v[120:123], v[158:161], v[182:185], v[120:123]
	v_mfma_f32_16x16x32_bf16 v[108:111], v[140:143], v[190:193], v[108:111]
	v_mfma_f32_16x16x32_bf16 v[104:107], v[158:161], v[190:193], v[104:107]
	v_mfma_f32_16x16x32_bf16 v[96:99], v[140:143], v[202:205], v[96:99]
	v_mfma_f32_16x16x32_bf16 v[88:91], v[158:161], v[202:205], v[88:91]
	v_mfma_f32_16x16x32_bf16 v[80:83], v[140:143], v[210:213], v[80:83]
	v_mfma_f32_16x16x32_bf16 v[72:75], v[158:161], v[210:213], v[72:75]
	v_mfma_f32_16x16x32_bf16 v[124:127], v[154:157], v[186:189], v[124:127]
	v_mfma_f32_16x16x32_bf16 v[120:123], v[162:165], v[186:189], v[120:123]
	v_mfma_f32_16x16x32_bf16 v[108:111], v[154:157], v[194:197], v[108:111]
	v_mfma_f32_16x16x32_bf16 v[104:107], v[162:165], v[194:197], v[104:107]
	v_mfma_f32_16x16x32_bf16 v[96:99], v[154:157], v[206:209], v[96:99]
	v_mfma_f32_16x16x32_bf16 v[88:91], v[162:165], v[206:209], v[88:91]
	v_mfma_f32_16x16x32_bf16 v[80:83], v[154:157], v[214:217], v[80:83]
	v_mfma_f32_16x16x32_bf16 v[72:75], v[162:165], v[214:217], v[72:75]
	s_setprio 0
	s_setprio 1
	v_mfma_f32_16x16x32_bf16 v[116:119], v[166:169], v[182:185], v[116:119]
	v_mfma_f32_16x16x32_bf16 v[112:115], v[174:177], v[182:185], v[112:115]
	v_mfma_f32_16x16x32_bf16 v[100:103], v[166:169], v[190:193], v[100:103]
	v_mfma_f32_16x16x32_bf16 v[92:95], v[174:177], v[190:193], v[92:95]
	v_mfma_f32_16x16x32_bf16 v[84:87], v[166:169], v[202:205], v[84:87]
	v_mfma_f32_16x16x32_bf16 v[76:79], v[174:177], v[202:205], v[76:79]
	v_mfma_f32_16x16x32_bf16 v[68:71], v[166:169], v[210:213], v[68:71]
	v_mfma_f32_16x16x32_bf16 v[64:67], v[174:177], v[210:213], v[64:67]
	v_mfma_f32_16x16x32_bf16 v[116:119], v[170:173], v[186:189], v[116:119]
	v_mfma_f32_16x16x32_bf16 v[112:115], v[178:181], v[186:189], v[112:115]
	v_mfma_f32_16x16x32_bf16 v[100:103], v[170:173], v[194:197], v[100:103]
	v_mfma_f32_16x16x32_bf16 v[92:95], v[178:181], v[194:197], v[92:95]
	v_mfma_f32_16x16x32_bf16 v[84:87], v[170:173], v[206:209], v[84:87]
	v_mfma_f32_16x16x32_bf16 v[76:79], v[178:181], v[206:209], v[76:79]
	v_mfma_f32_16x16x32_bf16 v[68:71], v[170:173], v[214:217], v[68:71]
	v_mfma_f32_16x16x32_bf16 v[64:67], v[178:181], v[214:217], v[64:67]
	s_setprio 0
	s_barrier
; #define PG8_STAGE(bufoff, gbase, voff) do { _Pragma("unroll") for (int _i = 0; _i < 2; ++_i) \
;         __builtin_amdgcn_global_load_lds((const unsigned*)((const char*)(gbase) + (voff)[_i]), (PG8_LAS unsigned*)(lds + (bufoff) + ldsw + _i * 8192), 16, 0, 0); } while (0)
; #define PG8_LDA(dst, b, h) do { _Pragma("unroll") for (int m = 0; m < 4; ++m) _Pragma("unroll") for (int k = 0; k < 2; ++k) dst[m][k] = *(const PG8_LAS bf16x8*)(lds + PG8_SA(b, h) + aoff + m * 2048 + k * 1024); } while (0)
; #define PG8_MMA(ai, bj, At, Bt) do { __builtin_amdgcn_s_setprio(1); _Pragma("unroll") for (int m = 0; m < 4; ++m) _Pragma("unroll") for (int n = 0; n < 2; ++n) _Pragma("unroll") for (int k = 0; k < 2; ++k) \
;         acc[ai][bj][m][n] = __builtin_amdgcn_mfma_f32_16x16x32_bf16(Bt[n][k], At[m][k], acc[ai][bj][m][n], 0, 0, 0); __builtin_amdgcn_s_setprio(0); } while (0)
; #define PG8_WAIT_V(n) asm volatile("s_waitcnt vmcnt(" #n ")" ::: "memory")
; #define PG8_WAIT_L(n) asm volatile("s_waitcnt lgkmcnt(" #n ")" ::: "memory")
; #define PG8_BAR __builtin_amdgcn_s_barrier()
; #define PG8_SCHED __builtin_amdgcn_sched_barrier(0)
; template <class Epi, class Sched, bool ALIGN_EPI = false, bool SP2 = false>
; __device__ __forceinline__ void gemm_phase(PG8_LAS unsigned char* lds, const Gemm g, const Sched& S, const Epi& E) {
;     ...
;         for (int t = 0; t < nt; t += 2) {
;     ...
;             PG8_LDA(At, 1, 1); PG8_STAGE(PG8_SB(1, 0), b3, voffB); PG8_STAGE(PG8_SB(1, 1), b3 + hstep, voffB); PG8_STAGE(PG8_SA(1, 0), a3, voffA);
;             PG8_WAIT_V(8); PG8_WAIT_L(0); PG8_BAR; PG8_MMA(1, 0, At, B0); PG8_MMA(1, 1, At, B1); PG8_BAR; PG8_SCHED;
	s_add_i32 s62, s76, s21
	v_lshl_add_u64 v[144:145], v[144:145], 0, s[12:13]
	s_mov_b32 m0, s62
	ds_read_b128 v[182:185], v151 offset:49152
	ds_read_b128 v[186:189], v151 offset:50176
	ds_read_b128 v[190:193], v151 offset:51200
	ds_read_b128 v[194:197], v151 offset:52224
	ds_read_b128 v[202:205], v151 offset:53248
	ds_read_b128 v[206:209], v151 offset:54272
	ds_read_b128 v[210:213], v151 offset:55296
	ds_read_b128 v[214:217], v151 offset:56320
	global_load_lds_dwordx4 v[144:145], off
	s_add_i32 m0, s62, 0x2000
	s_add_u32 s60, s60, 0x40080
	v_lshl_add_u64 v[144:145], v[198:199], 0, s[12:13]
	s_addc_u32 s61, s61, 0
	s_add_i32 s62, s77, s21
	global_load_lds_dwordx4 v[144:145], off
	v_lshl_add_u64 v[144:145], s[60:61], 0, v[130:131]
	s_mov_b32 m0, s62
	s_nop 0
	global_load_lds_dwordx4 v[144:145], off
	v_lshl_add_u64 v[144:145], s[60:61], 0, v[134:135]
	s_add_i32 m0, s62, 0x2000
	s_nop 0
	global_load_lds_dwordx4 v[144:145], off
	v_lshl_add_u64 v[144:145], v[218:219], 0, s[12:13]
	s_mov_b32 m0, s57
	s_nop 0
	global_load_lds_dwordx4 v[144:145], off
	v_lshl_add_u64 v[144:145], v[220:221], 0, s[12:13]
	s_mov_b32 m0, s64
	s_nop 0
	global_load_lds_dwordx4 v[144:145], off
	s_waitcnt vmcnt(8)
	s_waitcnt lgkmcnt(0)
	s_barrier
	s_setprio 1
	s_waitcnt lgkmcnt(0)
	v_mfma_f32_16x16x32_bf16 v[60:63], v[140:143], v[182:185], v[60:63]
	v_mfma_f32_16x16x32_bf16 v[56:59], v[158:161], v[182:185], v[56:59]
	v_mfma_f32_16x16x32_bf16 v[48:51], v[140:143], v[190:193], v[48:51]
	v_mfma_f32_16x16x32_bf16 v[40:43], v[158:161], v[190:193], v[40:43]
	v_mfma_f32_16x16x32_bf16 v[32:35], v[140:143], v[202:205], v[32:35]
	v_mfma_f32_16x16x32_bf16 v[24:27], v[158:161], v[202:205], v[24:27]
	v_mfma_f32_16x16x32_bf16 v[16:19], v[140:143], v[210:213], v[16:19]
	v_mfma_f32_16x16x32_bf16 v[8:11], v[158:161], v[210:213], v[8:11]
	v_mfma_f32_16x16x32_bf16 v[60:63], v[154:157], v[186:189], v[60:63]
	v_mfma_f32_16x16x32_bf16 v[56:59], v[162:165], v[186:189], v[56:59]
	v_mfma_f32_16x16x32_bf16 v[48:51], v[154:157], v[194:197], v[48:51]
	v_mfma_f32_16x16x32_bf16 v[40:43], v[162:165], v[194:197], v[40:43]
	v_mfma_f32_16x16x32_bf16 v[32:35], v[154:157], v[206:209], v[32:35]
	v_mfma_f32_16x16x32_bf16 v[24:27], v[162:165], v[206:209], v[24:27]
	v_mfma_f32_16x16x32_bf16 v[16:19], v[154:157], v[214:217], v[16:19]
	v_mfma_f32_16x16x32_bf16 v[8:11], v[162:165], v[214:217], v[8:11]
	s_setprio 0
	s_setprio 1
	v_mfma_f32_16x16x32_bf16 v[52:55], v[166:169], v[182:185], v[52:55]
	v_mfma_f32_16x16x32_bf16 v[44:47], v[174:177], v[182:185], v[44:47]
	v_mfma_f32_16x16x32_bf16 v[36:39], v[166:169], v[190:193], v[36:39]
	v_mfma_f32_16x16x32_bf16 v[28:31], v[174:177], v[190:193], v[28:31]
	v_mfma_f32_16x16x32_bf16 v[20:23], v[166:169], v[202:205], v[20:23]
	v_mfma_f32_16x16x32_bf16 v[12:15], v[174:177], v[202:205], v[12:15]
	v_mfma_f32_16x16x32_bf16 v[4:7], v[166:169], v[210:213], v[4:7]
	v_mfma_f32_16x16x32_bf16 v[0:3], v[174:177], v[210:213], v[0:3]
	v_mfma_f32_16x16x32_bf16 v[52:55], v[170:173], v[186:189], v[52:55]
	v_mfma_f32_16x16x32_bf16 v[44:47], v[178:181], v[186:189], v[44:47]
	v_mfma_f32_16x16x32_bf16 v[36:39], v[170:173], v[194:197], v[36:39]
	v_mfma_f32_16x16x32_bf16 v[28:31], v[178:181], v[194:197], v[28:31]
	v_mfma_f32_16x16x32_bf16 v[20:23], v[170:173], v[206:209], v[20:23]
	v_mfma_f32_16x16x32_bf16 v[12:15], v[178:181], v[206:209], v[12:15]
	v_mfma_f32_16x16x32_bf16 v[4:7], v[170:173], v[214:217], v[4:7]
	v_mfma_f32_16x16x32_bf16 v[0:3], v[178:181], v[214:217], v[0:3]
	s_setprio 0
	s_add_i32 s75, s75, 2
	s_add_u32 s58, s58, 0x100
	s_addc_u32 s59, s59, 0
	s_add_u32 s73, s73, 0x100
	s_addc_u32 s74, s74, 0
	s_barrier
	s_cmp_gt_u32 s75, 13
	s_cbranch_scc0 .LBB0_1215
	s_and_b64 vcc, exec, s[14:15]
	s_cbranch_vccz .LBB0_1218
	s_barrier

; #define PG8_STAGE(bufoff, gbase, voff) do { _Pragma("unroll") for (int _i = 0; _i < 2; ++_i) \
;         __builtin_amdgcn_global_load_lds((const unsigned*)((const char*)(gbase) + (voff)[_i]), (PG8_LAS unsigned*)(lds + (bufoff) + ldsw + _i * 8192), 16, 0, 0); } while (0)
; #define PG8_LDA(dst, b, h) do { _Pragma("unroll") for (int m = 0; m < 4; ++m) _Pragma("unroll") for (int k = 0; k < 2; ++k) dst[m][k] = *(const PG8_LAS bf16x8*)(lds + PG8_SA(b, h) + aoff + m * 2048 + k * 1024); } while (0)
; #define PG8_LDB(dst, b, h) do { _Pragma("unroll") for (int n = 0; n < 2; ++n) _Pragma("unroll") for (int k = 0; k < 2; ++k) dst[n][k] = *(const PG8_LAS bf16x8*)(lds + PG8_SB(b, h) + boff + n * 2048 + k * 1024); } while (0)
; #define PG8_MMA(ai, bj, At, Bt) do { __builtin_amdgcn_s_setprio(1); _Pragma("unroll") for (int m = 0; m < 4; ++m) _Pragma("unroll") for (int n = 0; n < 2; ++n) _Pragma("unroll") for (int k = 0; k < 2; ++k) \
;         acc[ai][bj][m][n] = __builtin_amdgcn_mfma_f32_16x16x32_bf16(Bt[n][k], At[m][k], acc[ai][bj][m][n], 0, 0, 0); __builtin_amdgcn_s_setprio(0); } while (0)
; #define PG8_WAIT_V(n) asm volatile("s_waitcnt vmcnt(" #n ")" ::: "memory")
; #define PG8_WAIT_L(n) asm volatile("s_waitcnt lgkmcnt(" #n ")" ::: "memory")
; template <class Epi, class Sched, bool ALIGN_EPI = false, bool SP2 = false>
; __device__ __forceinline__ void gemm_phase(PG8_LAS unsigned char* lds, const Gemm g, const Sched& S, const Epi& E) {
;     ...
;             const bool last = (t == nt - 2);
;             const char* a1 = cA + (size_t)(t + 1) * kstep;
;             const char* a2 = last ? nA : cA + (size_t)(t + 2) * kstep; const char* b2 = last ? nB : cB + (size_t)(t + 2) * kstep;
;             const char* a3 = a2 + kstep; const char* b3 = b2 + kstep;
;             if (last && has_next) S.a_ready(nxt);
;             if constexpr (SP2) {
;             PG8_LDB(B0, 0, 0); PG8_LDB(B1, 0, 1); PG8_SCHED; PG8_LDA(At, 0, 0); PG8_STAGE(PG8_SA(1, 1), a1 + hstep, voffA);
;             PG8_WAIT_V(8); PG8_WAIT_L(0); PG8_BAR; PG8_MMA(0, 0, At, B0); PG8_MMA(0, 1, At, B1); PG8_BAR; PG8_SCHED;
;             PG8_LDA(At, 0, 1); PG8_STAGE(PG8_SB(0, 0), b2, voffB); PG8_STAGE(PG8_SB(0, 1), b2 + hstep, voffB); PG8_STAGE(PG8_SA(0, 0), a2, voffA);
;             PG8_WAIT_V(8); PG8_WAIT_L(0); PG8_BAR; PG8_MMA(1, 0, At, B0); PG8_MMA(1, 1, At, B1); PG8_BAR; PG8_SCHED;
.LBB0_1293:
	ds_read_b128 v[140:143], v189
	ds_read_b128 v[144:147], v189 offset:1024
	ds_read_b128 v[148:151], v189 offset:2048
	ds_read_b128 v[152:155], v189 offset:3072
	ds_read_b128 v[156:159], v190
	ds_read_b128 v[160:163], v190 offset:1024
	ds_read_b128 v[164:167], v190 offset:2048
	ds_read_b128 v[168:171], v190 offset:3072
	s_add_u32 s50, s48, 0xfffc0080
	s_addc_u32 s51, s49, -1
	s_cmp_eq_u32 s66, 12
	s_cselect_b32 s57, s3, s51
	s_cselect_b32 s56, s17, s50
	s_cselect_b32 s51, s19, s65
	s_cselect_b32 s50, s63, s64
	v_lshl_add_u64 v[184:185], s[48:49], 0, v[136:137]
	s_add_i32 m0, s28, 0xc000
	ds_read_b128 v[172:175], v191
	ds_read_b128 v[176:179], v191 offset:1024
	ds_read_b128 v[180:183], v191 offset:2048
	ds_read_b128 v[194:197], v191 offset:3072
	ds_read_b128 v[202:205], v191 offset:4096
	ds_read_b128 v[206:209], v191 offset:5120
	ds_read_b128 v[210:213], v191 offset:6144
	ds_read_b128 v[214:217], v191 offset:7168
	global_load_lds_dwordx4 v[184:185], off
	v_lshl_add_u64 v[184:185], s[48:49], 0, v[138:139]
	s_add_i32 m0, s28, 0xe000
	s_nop 0
	global_load_lds_dwordx4 v[184:185], off
	s_waitcnt vmcnt(8)
	s_waitcnt lgkmcnt(0)
	s_barrier
	s_setprio 1
	s_waitcnt lgkmcnt(0)
	v_mfma_f32_16x16x32_bf16 v[124:127], v[140:143], v[172:175], v[124:127]
	v_mfma_f32_16x16x32_bf16 v[120:123], v[148:151], v[172:175], v[120:123]
	v_mfma_f32_16x16x32_bf16 v[108:111], v[140:143], v[180:183], v[108:111]
	v_mfma_f32_16x16x32_bf16 v[104:107], v[148:151], v[180:183], v[104:107]
	v_mfma_f32_16x16x32_bf16 v[92:95], v[140:143], v[202:205], v[92:95]
	v_mfma_f32_16x16x32_bf16 v[88:91], v[148:151], v[202:205], v[88:91]
	v_mfma_f32_16x16x32_bf16 v[76:79], v[140:143], v[210:213], v[76:79]
	v_mfma_f32_16x16x32_bf16 v[72:75], v[148:151], v[210:213], v[72:75]
	v_mfma_f32_16x16x32_bf16 v[124:127], v[144:147], v[176:179], v[124:127]
	v_mfma_f32_16x16x32_bf16 v[120:123], v[152:155], v[176:179], v[120:123]
	v_mfma_f32_16x16x32_bf16 v[108:111], v[144:147], v[194:197], v[108:111]
	v_mfma_f32_16x16x32_bf16 v[104:107], v[152:155], v[194:197], v[104:107]
	v_mfma_f32_16x16x32_bf16 v[92:95], v[144:147], v[206:209], v[92:95]
	v_mfma_f32_16x16x32_bf16 v[88:91], v[152:155], v[206:209], v[88:91]
	v_mfma_f32_16x16x32_bf16 v[76:79], v[144:147], v[214:217], v[76:79]
	v_mfma_f32_16x16x32_bf16 v[72:75], v[152:155], v[214:217], v[72:75]
	s_setprio 0
	s_setprio 1
	v_mfma_f32_16x16x32_bf16 v[116:119], v[156:159], v[172:175], v[116:119]
	v_mfma_f32_16x16x32_bf16 v[112:115], v[164:167], v[172:175], v[112:115]
	v_mfma_f32_16x16x32_bf16 v[100:103], v[156:159], v[180:183], v[100:103]
	v_mfma_f32_16x16x32_bf16 v[96:99], v[164:167], v[180:183], v[96:99]
	v_mfma_f32_16x16x32_bf16 v[84:87], v[156:159], v[202:205], v[84:87]
	v_mfma_f32_16x16x32_bf16 v[80:83], v[164:167], v[202:205], v[80:83]
	v_mfma_f32_16x16x32_bf16 v[68:71], v[156:159], v[210:213], v[68:71]
	v_mfma_f32_16x16x32_bf16 v[64:67], v[164:167], v[210:213], v[64:67]
	v_mfma_f32_16x16x32_bf16 v[116:119], v[160:163], v[176:179], v[116:119]
	v_mfma_f32_16x16x32_bf16 v[112:115], v[168:171], v[176:179], v[112:115]
	v_mfma_f32_16x16x32_bf16 v[100:103], v[160:163], v[194:197], v[100:103]
	v_mfma_f32_16x16x32_bf16 v[96:99], v[168:171], v[194:197], v[96:99]
	v_mfma_f32_16x16x32_bf16 v[84:87], v[160:163], v[206:209], v[84:87]
	v_mfma_f32_16x16x32_bf16 v[80:83], v[168:171], v[206:209], v[80:83]
	v_mfma_f32_16x16x32_bf16 v[68:71], v[160:163], v[214:217], v[68:71]
	v_mfma_f32_16x16x32_bf16 v[64:67], v[168:171], v[214:217], v[64:67]
	s_setprio 0
	s_barrier
	s_add_i32 s67, s59, s21
	v_lshl_add_u64 v[184:185], s[50:51], 0, v[132:133]
	s_mov_b32 m0, s67
	ds_read_b128 v[172:175], v191 offset:16384
	ds_read_b128 v[176:179], v191 offset:17408
	ds_read_b128 v[180:183], v191 offset:18432
	ds_read_b128 v[194:197], v191 offset:19456
	ds_read_b128 v[202:205], v191 offset:20480
	ds_read_b128 v[206:209], v191 offset:21504
	ds_read_b128 v[210:213], v191 offset:22528
	ds_read_b128 v[214:217], v191 offset:23552
	global_load_lds_dwordx4 v[184:185], off
	s_add_i32 m0, s67, 0x2000
	s_add_u32 s68, s50, 0x40000
	v_lshl_add_u64 v[198:199], s[50:51], 0, v[128:129]
	s_addc_u32 s69, s51, 0
	s_add_i32 s67, s60, s21
	global_load_lds_dwordx4 v[198:199], off
	v_lshl_add_u64 v[218:219], s[68:69], 0, v[132:133]
	s_mov_b32 m0, s67
	v_lshl_add_u64 v[220:221], s[56:57], 0, v[130:131]
	global_load_lds_dwordx4 v[218:219], off
	v_lshl_add_u64 v[218:219], s[68:69], 0, v[128:129]
	s_add_i32 m0, s67, 0x2000
	s_nop 0
	global_load_lds_dwordx4 v[218:219], off
	v_lshl_add_u64 v[218:219], s[56:57], 0, v[134:135]
	s_mov_b32 m0, s28
	s_nop 0
	global_load_lds_dwordx4 v[218:219], off
	s_mov_b32 m0, s29
	s_nop 0
	global_load_lds_dwordx4 v[220:221], off
	s_waitcnt vmcnt(8)
	s_waitcnt lgkmcnt(0)
	s_barrier
; #define PG8_STAGE(bufoff, gbase, voff) do { _Pragma("unroll") for (int _i = 0; _i < 2; ++_i) \
;         __builtin_amdgcn_global_load_lds((const unsigned*)((const char*)(gbase) + (voff)[_i]), (PG8_LAS unsigned*)(lds + (bufoff) + ldsw + _i * 8192), 16, 0, 0); } while (0)
; #define PG8_LDA(dst, b, h) do { _Pragma("unroll") for (int m = 0; m < 4; ++m) _Pragma("unroll") for (int k = 0; k < 2; ++k) dst[m][k] = *(const PG8_LAS bf16x8*)(lds + PG8_SA(b, h) + aoff + m * 2048 + k * 1024); } while (0)
; #define PG8_LDB(dst, b, h) do { _Pragma("unroll") for (int n = 0; n < 2; ++n) _Pragma("unroll") for (int k = 0; k < 2; ++k) dst[n][k] = *(const PG8_LAS bf16x8*)(lds + PG8_SB(b, h) + boff + n * 2048 + k * 1024); } while (0)
; #define PG8_MMA(ai, bj, At, Bt) do { __builtin_amdgcn_s_setprio(1); _Pragma("unroll") for (int m = 0; m < 4; ++m) _Pragma("unroll") for (int n = 0; n < 2; ++n) _Pragma("unroll") for (int k = 0; k < 2; ++k) \
;         acc[ai][bj][m][n] = __builtin_amdgcn_mfma_f32_16x16x32_bf16(Bt[n][k], At[m][k], acc[ai][bj][m][n], 0, 0, 0); __builtin_amdgcn_s_setprio(0); } while (0)
; #define PG8_WAIT_V(n) asm volatile("s_waitcnt vmcnt(" #n ")" ::: "memory")
; #define PG8_WAIT_L(n) asm volatile("s_waitcnt lgkmcnt(" #n ")" ::: "memory")
; #define PG8_BAR __builtin_amdgcn_s_barrier()
; #define PG8_SCHED __builtin_amdgcn_sched_barrier(0)
; template <class Epi, class Sched, bool ALIGN_EPI = false, bool SP2 = false>
; __device__ __forceinline__ void gemm_phase(PG8_LAS unsigned char* lds, const Gemm g, const Sched& S, const Epi& E) {
;     ...
;             PG8_WAIT_V(8); PG8_WAIT_L(0); PG8_BAR; PG8_MMA(1, 0, At, B0); PG8_MMA(1, 1, At, B1); PG8_BAR; PG8_SCHED;
;             PG8_LDB(B0, 1, 0); PG8_LDB(B1, 1, 1); PG8_SCHED; PG8_LDA(At, 1, 0); PG8_STAGE(PG8_SA(0, 1), a2 + hstep, voffA);
;             PG8_WAIT_V(8); PG8_WAIT_L(0); PG8_BAR; PG8_MMA(0, 0, At, B0); PG8_MMA(0, 1, At, B1); PG8_BAR; PG8_SCHED;
	s_setprio 1
	s_waitcnt lgkmcnt(0)
	v_mfma_f32_16x16x32_bf16 v[60:63], v[140:143], v[172:175], v[60:63]
	v_mfma_f32_16x16x32_bf16 v[56:59], v[148:151], v[172:175], v[56:59]
	v_mfma_f32_16x16x32_bf16 v[44:47], v[140:143], v[180:183], v[44:47]
	v_mfma_f32_16x16x32_bf16 v[40:43], v[148:151], v[180:183], v[40:43]
	v_mfma_f32_16x16x32_bf16 v[28:31], v[140:143], v[202:205], v[28:31]
	v_mfma_f32_16x16x32_bf16 v[24:27], v[148:151], v[202:205], v[24:27]
	v_mfma_f32_16x16x32_bf16 v[12:15], v[140:143], v[210:213], v[12:15]
	v_mfma_f32_16x16x32_bf16 v[8:11], v[148:151], v[210:213], v[8:11]
	v_mfma_f32_16x16x32_bf16 v[60:63], v[144:147], v[176:179], v[60:63]
	v_mfma_f32_16x16x32_bf16 v[56:59], v[152:155], v[176:179], v[56:59]
	v_mfma_f32_16x16x32_bf16 v[44:47], v[144:147], v[194:197], v[44:47]
	v_mfma_f32_16x16x32_bf16 v[40:43], v[152:155], v[194:197], v[40:43]
	v_mfma_f32_16x16x32_bf16 v[28:31], v[144:147], v[206:209], v[28:31]
	v_mfma_f32_16x16x32_bf16 v[24:27], v[152:155], v[206:209], v[24:27]
	v_mfma_f32_16x16x32_bf16 v[12:15], v[144:147], v[214:217], v[12:15]
	v_mfma_f32_16x16x32_bf16 v[8:11], v[152:155], v[214:217], v[8:11]
	s_setprio 0
	s_setprio 1
	v_mfma_f32_16x16x32_bf16 v[52:55], v[156:159], v[172:175], v[52:55]
	v_mfma_f32_16x16x32_bf16 v[48:51], v[164:167], v[172:175], v[48:51]
	v_mfma_f32_16x16x32_bf16 v[36:39], v[156:159], v[180:183], v[36:39]
	v_mfma_f32_16x16x32_bf16 v[32:35], v[164:167], v[180:183], v[32:35]
	v_mfma_f32_16x16x32_bf16 v[20:23], v[156:159], v[202:205], v[20:23]
	v_mfma_f32_16x16x32_bf16 v[16:19], v[164:167], v[202:205], v[16:19]
	v_mfma_f32_16x16x32_bf16 v[4:7], v[156:159], v[210:213], v[4:7]
	v_mfma_f32_16x16x32_bf16 v[0:3], v[164:167], v[210:213], v[0:3]
	v_mfma_f32_16x16x32_bf16 v[52:55], v[160:163], v[176:179], v[52:55]
	v_mfma_f32_16x16x32_bf16 v[48:51], v[168:171], v[176:179], v[48:51]
	v_mfma_f32_16x16x32_bf16 v[36:39], v[160:163], v[194:197], v[36:39]
	v_mfma_f32_16x16x32_bf16 v[32:35], v[168:171], v[194:197], v[32:35]
	v_mfma_f32_16x16x32_bf16 v[20:23], v[160:163], v[206:209], v[20:23]
	v_mfma_f32_16x16x32_bf16 v[16:19], v[168:171], v[206:209], v[16:19]
	v_mfma_f32_16x16x32_bf16 v[4:7], v[160:163], v[214:217], v[4:7]
	v_mfma_f32_16x16x32_bf16 v[0:3], v[168:171], v[214:217], v[0:3]
	s_setprio 0
	s_barrier
	s_add_i32 s67, 0, 0x18000
	s_add_i32 s68, 0, 0x1c000
	v_add_u32_e32 v152, s67, v187
	v_add_u32_e32 v168, s68, v187
	ds_read_b128 v[140:143], v152
	ds_read_b128 v[144:147], v152 offset:1024
	ds_read_b128 v[148:151], v152 offset:2048
	ds_read_b128 v[152:155], v152 offset:3072
	ds_read_b128 v[156:159], v168
	ds_read_b128 v[160:163], v168 offset:1024
	ds_read_b128 v[164:167], v168 offset:2048
	ds_read_b128 v[168:171], v168 offset:3072
	s_add_u32 s56, s56, 0x40000
	s_addc_u32 s57, s57, 0
	s_mov_b32 m0, s30
	v_lshl_add_u64 v[222:223], s[56:57], 0, v[134:135]
	ds_read_b128 v[172:175], v191 offset:32768
	ds_read_b128 v[176:179], v191 offset:33792
	ds_read_b128 v[180:183], v191 offset:34816
	ds_read_b128 v[194:197], v191 offset:35840
	ds_read_b128 v[202:205], v191 offset:36864
	ds_read_b128 v[206:209], v191 offset:37888
	ds_read_b128 v[210:213], v191 offset:38912
	ds_read_b128 v[214:217], v191 offset:39936
	global_load_lds_dwordx4 v[222:223], off
	v_lshl_add_u64 v[222:223], s[56:57], 0, v[130:131]
	s_mov_b32 m0, s31
	s_nop 0
	global_load_lds_dwordx4 v[222:223], off
	s_waitcnt vmcnt(8)
	s_waitcnt lgkmcnt(0)
	s_barrier
	s_setprio 1
	s_waitcnt lgkmcnt(0)
	v_mfma_f32_16x16x32_bf16 v[124:127], v[140:143], v[172:175], v[124:127]
	v_mfma_f32_16x16x32_bf16 v[120:123], v[148:151], v[172:175], v[120:123]
	v_mfma_f32_16x16x32_bf16 v[108:111], v[140:143], v[180:183], v[108:111]
	v_mfma_f32_16x16x32_bf16 v[104:107], v[148:151], v[180:183], v[104:107]
	v_mfma_f32_16x16x32_bf16 v[92:95], v[140:143], v[202:205], v[92:95]
	v_mfma_f32_16x16x32_bf16 v[88:91], v[148:151], v[202:205], v[88:91]
	v_mfma_f32_16x16x32_bf16 v[76:79], v[140:143], v[210:213], v[76:79]
	v_mfma_f32_16x16x32_bf16 v[72:75], v[148:151], v[210:213], v[72:75]
	v_mfma_f32_16x16x32_bf16 v[124:127], v[144:147], v[176:179], v[124:127]
	v_mfma_f32_16x16x32_bf16 v[120:123], v[152:155], v[176:179], v[120:123]
	v_mfma_f32_16x16x32_bf16 v[108:111], v[144:147], v[194:197], v[108:111]
	v_mfma_f32_16x16x32_bf16 v[104:107], v[152:155], v[194:197], v[104:107]
	v_mfma_f32_16x16x32_bf16 v[92:95], v[144:147], v[206:209], v[92:95]
	v_mfma_f32_16x16x32_bf16 v[88:91], v[152:155], v[206:209], v[88:91]
	v_mfma_f32_16x16x32_bf16 v[76:79], v[144:147], v[214:217], v[76:79]
	v_mfma_f32_16x16x32_bf16 v[72:75], v[152:155], v[214:217], v[72:75]
	s_setprio 0
	s_setprio 1
	v_mfma_f32_16x16x32_bf16 v[116:119], v[156:159], v[172:175], v[116:119]
	v_mfma_f32_16x16x32_bf16 v[112:115], v[164:167], v[172:175], v[112:115]
	v_mfma_f32_16x16x32_bf16 v[100:103], v[156:159], v[180:183], v[100:103]
	v_mfma_f32_16x16x32_bf16 v[96:99], v[164:167], v[180:183], v[96:99]
	v_mfma_f32_16x16x32_bf16 v[84:87], v[156:159], v[202:205], v[84:87]
	v_mfma_f32_16x16x32_bf16 v[80:83], v[164:167], v[202:205], v[80:83]
	v_mfma_f32_16x16x32_bf16 v[68:71], v[156:159], v[210:213], v[68:71]
	v_mfma_f32_16x16x32_bf16 v[64:67], v[164:167], v[210:213], v[64:67]
	v_mfma_f32_16x16x32_bf16 v[116:119], v[160:163], v[176:179], v[116:119]
	v_mfma_f32_16x16x32_bf16 v[112:115], v[168:171], v[176:179], v[112:115]
	v_mfma_f32_16x16x32_bf16 v[100:103], v[160:163], v[194:197], v[100:103]
	v_mfma_f32_16x16x32_bf16 v[96:99], v[168:171], v[194:197], v[96:99]
	v_mfma_f32_16x16x32_bf16 v[84:87], v[160:163], v[206:209], v[84:87]
	v_mfma_f32_16x16x32_bf16 v[80:83], v[168:171], v[206:209], v[80:83]
	v_mfma_f32_16x16x32_bf16 v[68:71], v[160:163], v[214:217], v[68:71]
	v_mfma_f32_16x16x32_bf16 v[64:67], v[168:171], v[214:217], v[64:67]
	s_setprio 0
	s_barrier
; #define PG8_STAGE(bufoff, gbase, voff) do { _Pragma("unroll") for (int _i = 0; _i < 2; ++_i) \
;         __builtin_amdgcn_global_load_lds((const unsigned*)((const char*)(gbase) + (voff)[_i]), (PG8_LAS unsigned*)(lds + (bufoff) + ldsw + _i * 8192), 16, 0, 0); } while (0)
; #define PG8_LDA(dst, b, h) do { _Pragma("unroll") for (int m = 0; m < 4; ++m) _Pragma("unroll") for (int k = 0; k < 2; ++k) dst[m][k] = *(const PG8_LAS bf16x8*)(lds + PG8_SA(b, h) + aoff + m * 2048 + k * 1024); } while (0)
; #define PG8_MMA(ai, bj, At, Bt) do { __builtin_amdgcn_s_setprio(1); _Pragma("unroll") for (int m = 0; m < 4; ++m) _Pragma("unroll") for (int n = 0; n < 2; ++n) _Pragma("unroll") for (int k = 0; k < 2; ++k) \
;         acc[ai][bj][m][n] = __builtin_amdgcn_mfma_f32_16x16x32_bf16(Bt[n][k], At[m][k], acc[ai][bj][m][n], 0, 0, 0); __builtin_amdgcn_s_setprio(0); } while (0)
; #define PG8_WAIT_V(n) asm volatile("s_waitcnt vmcnt(" #n ")" ::: "memory")
; #define PG8_WAIT_L(n) asm volatile("s_waitcnt lgkmcnt(" #n ")" ::: "memory")
; #define PG8_BAR __builtin_amdgcn_s_barrier()
; #define PG8_SCHED __builtin_amdgcn_sched_barrier(0)
; template <class Epi, class Sched, bool ALIGN_EPI = false, bool SP2 = false>
; __device__ __forceinline__ void gemm_phase(PG8_LAS unsigned char* lds, const Gemm g, const Sched& S, const Epi& E) {
;     ...
;         for (int t = 0; t < nt; t += 2) {
;     ...
;             PG8_LDA(At, 1, 1); PG8_STAGE(PG8_SB(1, 0), b3, voffB); PG8_STAGE(PG8_SB(1, 1), b3 + hstep, voffB); PG8_STAGE(PG8_SA(1, 0), a3, voffA);
;             PG8_WAIT_V(8); PG8_WAIT_L(0); PG8_BAR; PG8_MMA(1, 0, At, B0); PG8_MMA(1, 1, At, B1); PG8_BAR; PG8_SCHED;
	s_add_i32 s56, s67, s21
	v_lshl_add_u64 v[184:185], v[184:185], 0, s[12:13]
	s_mov_b32 m0, s56
	ds_read_b128 v[172:175], v191 offset:49152
	ds_read_b128 v[176:179], v191 offset:50176
	ds_read_b128 v[180:183], v191 offset:51200
	ds_read_b128 v[194:197], v191 offset:52224
	ds_read_b128 v[202:205], v191 offset:53248
	ds_read_b128 v[206:209], v191 offset:54272
	ds_read_b128 v[210:213], v191 offset:55296
	ds_read_b128 v[214:217], v191 offset:56320
	global_load_lds_dwordx4 v[184:185], off
	s_add_i32 m0, s56, 0x2000
	s_add_u32 s50, s50, 0x40080
	v_lshl_add_u64 v[184:185], v[198:199], 0, s[12:13]
	s_addc_u32 s51, s51, 0
	s_add_i32 s56, s68, s21
	global_load_lds_dwordx4 v[184:185], off
	v_lshl_add_u64 v[184:185], s[50:51], 0, v[132:133]
	s_mov_b32 m0, s56
	s_nop 0
	global_load_lds_dwordx4 v[184:185], off
	v_lshl_add_u64 v[184:185], s[50:51], 0, v[128:129]
	s_add_i32 m0, s56, 0x2000
	s_nop 0
	global_load_lds_dwordx4 v[184:185], off
	v_lshl_add_u64 v[184:185], v[218:219], 0, s[12:13]
	s_mov_b32 m0, s39
	s_nop 0
	global_load_lds_dwordx4 v[184:185], off
	v_lshl_add_u64 v[184:185], v[220:221], 0, s[12:13]
	s_mov_b32 m0, s58
	s_nop 0
	global_load_lds_dwordx4 v[184:185], off
	s_waitcnt vmcnt(8)
	s_waitcnt lgkmcnt(0)
	s_barrier
	s_setprio 1
	s_waitcnt lgkmcnt(0)
	v_mfma_f32_16x16x32_bf16 v[60:63], v[140:143], v[172:175], v[60:63]
	v_mfma_f32_16x16x32_bf16 v[56:59], v[148:151], v[172:175], v[56:59]
	v_mfma_f32_16x16x32_bf16 v[44:47], v[140:143], v[180:183], v[44:47]
	v_mfma_f32_16x16x32_bf16 v[40:43], v[148:151], v[180:183], v[40:43]
	v_mfma_f32_16x16x32_bf16 v[28:31], v[140:143], v[202:205], v[28:31]
	v_mfma_f32_16x16x32_bf16 v[24:27], v[148:151], v[202:205], v[24:27]
	v_mfma_f32_16x16x32_bf16 v[12:15], v[140:143], v[210:213], v[12:15]
	v_mfma_f32_16x16x32_bf16 v[8:11], v[148:151], v[210:213], v[8:11]
	v_mfma_f32_16x16x32_bf16 v[60:63], v[144:147], v[176:179], v[60:63]
	v_mfma_f32_16x16x32_bf16 v[56:59], v[152:155], v[176:179], v[56:59]
	v_mfma_f32_16x16x32_bf16 v[44:47], v[144:147], v[194:197], v[44:47]
	v_mfma_f32_16x16x32_bf16 v[40:43], v[152:155], v[194:197], v[40:43]
	v_mfma_f32_16x16x32_bf16 v[28:31], v[144:147], v[206:209], v[28:31]
	v_mfma_f32_16x16x32_bf16 v[24:27], v[152:155], v[206:209], v[24:27]
	v_mfma_f32_16x16x32_bf16 v[12:15], v[144:147], v[214:217], v[12:15]
	v_mfma_f32_16x16x32_bf16 v[8:11], v[152:155], v[214:217], v[8:11]
	s_setprio 0
	s_setprio 1
	v_mfma_f32_16x16x32_bf16 v[52:55], v[156:159], v[172:175], v[52:55]
	v_mfma_f32_16x16x32_bf16 v[48:51], v[164:167], v[172:175], v[48:51]
	v_mfma_f32_16x16x32_bf16 v[36:39], v[156:159], v[180:183], v[36:39]
	v_mfma_f32_16x16x32_bf16 v[32:35], v[164:167], v[180:183], v[32:35]
	v_mfma_f32_16x16x32_bf16 v[20:23], v[156:159], v[202:205], v[20:23]
	v_mfma_f32_16x16x32_bf16 v[16:19], v[164:167], v[202:205], v[16:19]
	v_mfma_f32_16x16x32_bf16 v[4:7], v[156:159], v[210:213], v[4:7]
	v_mfma_f32_16x16x32_bf16 v[0:3], v[164:167], v[210:213], v[0:3]
	v_mfma_f32_16x16x32_bf16 v[52:55], v[160:163], v[176:179], v[52:55]
	v_mfma_f32_16x16x32_bf16 v[48:51], v[168:171], v[176:179], v[48:51]
	v_mfma_f32_16x16x32_bf16 v[36:39], v[160:163], v[194:197], v[36:39]
	v_mfma_f32_16x16x32_bf16 v[32:35], v[168:171], v[194:197], v[32:35]
	v_mfma_f32_16x16x32_bf16 v[20:23], v[160:163], v[206:209], v[20:23]
	v_mfma_f32_16x16x32_bf16 v[16:19], v[168:171], v[206:209], v[16:19]
	v_mfma_f32_16x16x32_bf16 v[4:7], v[160:163], v[214:217], v[4:7]
	v_mfma_f32_16x16x32_bf16 v[0:3], v[168:171], v[214:217], v[0:3]
	s_setprio 0
	s_add_i32 s66, s66, 2
	s_add_u32 s48, s48, 0x100
	s_addc_u32 s49, s49, 0
	s_add_u32 s64, s64, 0x100
	s_addc_u32 s65, s65, 0
	s_barrier
	s_cmp_gt_u32 s66, 13
	s_cbranch_scc0 .LBB0_1293
	s_and_b64 vcc, exec, s[14:15]
	s_cbranch_vccz .LBB0_1296
	s_barrier

; #define PG8_STAGE(bufoff, gbase, voff) do { _Pragma("unroll") for (int _i = 0; _i < 2; ++_i) \
;         __builtin_amdgcn_global_load_lds((const unsigned*)((const char*)(gbase) + (voff)[_i]), (PG8_LAS unsigned*)(lds + (bufoff) + ldsw + _i * 8192), 16, 0, 0); } while (0)
; #define PG8_LDA(dst, b, h) do { _Pragma("unroll") for (int m = 0; m < 4; ++m) _Pragma("unroll") for (int k = 0; k < 2; ++k) dst[m][k] = *(const PG8_LAS bf16x8*)(lds + PG8_SA(b, h) + aoff + m * 2048 + k * 1024); } while (0)
; #define PG8_LDB(dst, b, h) do { _Pragma("unroll") for (int n = 0; n < 2; ++n) _Pragma("unroll") for (int k = 0; k < 2; ++k) dst[n][k] = *(const PG8_LAS bf16x8*)(lds + PG8_SB(b, h) + boff + n * 2048 + k * 1024); } while (0)
; #define PG8_MMA(ai, bj, At, Bt) do { __builtin_amdgcn_s_setprio(1); _Pragma("unroll") for (int m = 0; m < 4; ++m) _Pragma("unroll") for (int n = 0; n < 2; ++n) _Pragma("unroll") for (int k = 0; k < 2; ++k) \
;         acc[ai][bj][m][n] = __builtin_amdgcn_mfma_f32_16x16x32_bf16(Bt[n][k], At[m][k], acc[ai][bj][m][n], 0, 0, 0); __builtin_amdgcn_s_setprio(0); } while (0)
; #define PG8_WAIT_V(n) asm volatile("s_waitcnt vmcnt(" #n ")" ::: "memory")
; #define PG8_WAIT_L(n) asm volatile("s_waitcnt lgkmcnt(" #n ")" ::: "memory")
; template <class Epi, class Sched, bool ALIGN_EPI = false, bool SP2 = false>
; __device__ __forceinline__ void gemm_phase(PG8_LAS unsigned char* lds, const Gemm g, const Sched& S, const Epi& E) {
;     ...
;             const bool last = (t == nt - 2);
;             const char* a1 = cA + (size_t)(t + 1) * kstep;
;             const char* a2 = last ? nA : cA + (size_t)(t + 2) * kstep; const char* b2 = last ? nB : cB + (size_t)(t + 2) * kstep;
;             const char* a3 = a2 + kstep; const char* b3 = b2 + kstep;
;             if (last && has_next) S.a_ready(nxt);
;             if constexpr (SP2) {
;             PG8_LDB(B0, 0, 0); PG8_LDB(B1, 0, 1); PG8_SCHED; PG8_LDA(At, 0, 0); PG8_STAGE(PG8_SA(1, 1), a1 + hstep, voffA);
;             PG8_WAIT_V(8); PG8_WAIT_L(0); PG8_BAR; PG8_MMA(0, 0, At, B0); PG8_MMA(0, 1, At, B1); PG8_BAR; PG8_SCHED;
;             PG8_LDA(At, 0, 1); PG8_STAGE(PG8_SB(0, 0), b2, voffB); PG8_STAGE(PG8_SB(0, 1), b2 + hstep, voffB); PG8_STAGE(PG8_SA(0, 0), a2, voffA);
;             PG8_WAIT_V(8); PG8_WAIT_L(0); PG8_BAR; PG8_MMA(1, 0, At, B0); PG8_MMA(1, 1, At, B1); PG8_BAR; PG8_SCHED;
.LBB0_1363:
	ds_read_b128 v[128:131], v156
	ds_read_b128 v[132:135], v156 offset:1024
	ds_read_b128 v[148:151], v156 offset:2048
	ds_read_b128 v[162:165], v156 offset:3072
	ds_read_b128 v[166:169], v157
	ds_read_b128 v[170:173], v157 offset:1024
	ds_read_b128 v[174:177], v157 offset:2048
	ds_read_b128 v[178:181], v157 offset:3072
	s_add_u32 s42, s26, 0xfff50080
	s_addc_u32 s43, s27, -1
	s_cmp_eq_u32 s72, 40
	s_cselect_b32 s45, s17, s43
	s_cselect_b32 s44, s16, s42
	s_cselect_b32 s43, s19, s71
	s_cselect_b32 s42, s18, s70
	s_mov_b32 m0, s58
	v_lshl_add_u64 v[152:153], s[26:27], 0, v[144:145]
	ds_read_b128 v[182:185], v158
	ds_read_b128 v[186:189], v158 offset:1024
	ds_read_b128 v[190:193], v158 offset:2048
	ds_read_b128 v[194:197], v158 offset:3072
	ds_read_b128 v[202:205], v158 offset:4096
	ds_read_b128 v[206:209], v158 offset:5120
	ds_read_b128 v[210:213], v158 offset:6144
	ds_read_b128 v[214:217], v158 offset:7168
	global_load_lds_dwordx4 v[152:153], off
	v_lshl_add_u64 v[152:153], s[26:27], 0, v[146:147]
	s_mov_b32 m0, s59
	s_nop 0
	global_load_lds_dwordx4 v[152:153], off
	s_waitcnt vmcnt(8)
	s_waitcnt lgkmcnt(0)
	s_barrier
	s_setprio 1
	s_waitcnt lgkmcnt(0)
	v_mfma_f32_16x16x32_bf16 v[124:127], v[128:131], v[182:185], v[124:127]
	v_mfma_f32_16x16x32_bf16 v[120:123], v[148:151], v[182:185], v[120:123]
	v_mfma_f32_16x16x32_bf16 v[108:111], v[128:131], v[190:193], v[108:111]
	v_mfma_f32_16x16x32_bf16 v[104:107], v[148:151], v[190:193], v[104:107]
	v_mfma_f32_16x16x32_bf16 v[92:95], v[128:131], v[202:205], v[92:95]
	v_mfma_f32_16x16x32_bf16 v[88:91], v[148:151], v[202:205], v[88:91]
	v_mfma_f32_16x16x32_bf16 v[76:79], v[128:131], v[210:213], v[76:79]
	v_mfma_f32_16x16x32_bf16 v[72:75], v[148:151], v[210:213], v[72:75]
	v_mfma_f32_16x16x32_bf16 v[124:127], v[132:135], v[186:189], v[124:127]
	v_mfma_f32_16x16x32_bf16 v[120:123], v[162:165], v[186:189], v[120:123]
	v_mfma_f32_16x16x32_bf16 v[108:111], v[132:135], v[194:197], v[108:111]
	v_mfma_f32_16x16x32_bf16 v[104:107], v[162:165], v[194:197], v[104:107]
	v_mfma_f32_16x16x32_bf16 v[92:95], v[132:135], v[206:209], v[92:95]
	v_mfma_f32_16x16x32_bf16 v[88:91], v[162:165], v[206:209], v[88:91]
	v_mfma_f32_16x16x32_bf16 v[76:79], v[132:135], v[214:217], v[76:79]
	v_mfma_f32_16x16x32_bf16 v[72:75], v[162:165], v[214:217], v[72:75]
	s_setprio 0
	s_setprio 1
	v_mfma_f32_16x16x32_bf16 v[116:119], v[166:169], v[182:185], v[116:119]
	v_mfma_f32_16x16x32_bf16 v[112:115], v[174:177], v[182:185], v[112:115]
	v_mfma_f32_16x16x32_bf16 v[100:103], v[166:169], v[190:193], v[100:103]
	v_mfma_f32_16x16x32_bf16 v[96:99], v[174:177], v[190:193], v[96:99]
	v_mfma_f32_16x16x32_bf16 v[84:87], v[166:169], v[202:205], v[84:87]
	v_mfma_f32_16x16x32_bf16 v[80:83], v[174:177], v[202:205], v[80:83]
	v_mfma_f32_16x16x32_bf16 v[68:71], v[166:169], v[210:213], v[68:71]
	v_mfma_f32_16x16x32_bf16 v[64:67], v[174:177], v[210:213], v[64:67]
	v_mfma_f32_16x16x32_bf16 v[116:119], v[170:173], v[186:189], v[116:119]
	v_mfma_f32_16x16x32_bf16 v[112:115], v[178:181], v[186:189], v[112:115]
	v_mfma_f32_16x16x32_bf16 v[100:103], v[170:173], v[194:197], v[100:103]
	v_mfma_f32_16x16x32_bf16 v[96:99], v[178:181], v[194:197], v[96:99]
	v_mfma_f32_16x16x32_bf16 v[84:87], v[170:173], v[206:209], v[84:87]
	v_mfma_f32_16x16x32_bf16 v[80:83], v[178:181], v[206:209], v[80:83]
	v_mfma_f32_16x16x32_bf16 v[68:71], v[170:173], v[214:217], v[68:71]
	v_mfma_f32_16x16x32_bf16 v[64:67], v[178:181], v[214:217], v[64:67]
	s_setprio 0
	s_barrier
	s_mov_b32 m0, s60
	v_lshl_add_u64 v[152:153], s[42:43], 0, v[138:139]
	s_add_u32 s74, s42, 0xb0000
	ds_read_b128 v[182:185], v158 offset:16384
	ds_read_b128 v[186:189], v158 offset:17408
	ds_read_b128 v[190:193], v158 offset:18432
	ds_read_b128 v[194:197], v158 offset:19456
	ds_read_b128 v[202:205], v158 offset:20480
	ds_read_b128 v[206:209], v158 offset:21504
	ds_read_b128 v[210:213], v158 offset:22528
	ds_read_b128 v[214:217], v158 offset:23552
	global_load_lds_dwordx4 v[152:153], off
	v_lshl_add_u64 v[198:199], s[42:43], 0, v[142:143]
	s_mov_b32 m0, s61
	s_addc_u32 s75, s43, 0
	global_load_lds_dwordx4 v[198:199], off
	v_lshl_add_u64 v[218:219], s[74:75], 0, v[138:139]
	s_mov_b32 m0, s62
	v_lshl_add_u64 v[220:221], s[44:45], 0, v[140:141]
	global_load_lds_dwordx4 v[218:219], off
	v_lshl_add_u64 v[218:219], s[74:75], 0, v[142:143]
	s_mov_b32 m0, s63
	s_nop 0
	global_load_lds_dwordx4 v[218:219], off
	v_lshl_add_u64 v[218:219], s[44:45], 0, v[136:137]
	s_mov_b32 m0, s29
	s_nop 0
	global_load_lds_dwordx4 v[218:219], off
	s_mov_b32 m0, s30
	s_nop 0
	global_load_lds_dwordx4 v[220:221], off
	s_waitcnt vmcnt(8)
	s_waitcnt lgkmcnt(0)
	s_barrier
; #define PG8_STAGE(bufoff, gbase, voff) do { _Pragma("unroll") for (int _i = 0; _i < 2; ++_i) \
;         __builtin_amdgcn_global_load_lds((const unsigned*)((const char*)(gbase) + (voff)[_i]), (PG8_LAS unsigned*)(lds + (bufoff) + ldsw + _i * 8192), 16, 0, 0); } while (0)
; #define PG8_LDA(dst, b, h) do { _Pragma("unroll") for (int m = 0; m < 4; ++m) _Pragma("unroll") for (int k = 0; k < 2; ++k) dst[m][k] = *(const PG8_LAS bf16x8*)(lds + PG8_SA(b, h) + aoff + m * 2048 + k * 1024); } while (0)
; #define PG8_LDB(dst, b, h) do { _Pragma("unroll") for (int n = 0; n < 2; ++n) _Pragma("unroll") for (int k = 0; k < 2; ++k) dst[n][k] = *(const PG8_LAS bf16x8*)(lds + PG8_SB(b, h) + boff + n * 2048 + k * 1024); } while (0)
; #define PG8_MMA(ai, bj, At, Bt) do { __builtin_amdgcn_s_setprio(1); _Pragma("unroll") for (int m = 0; m < 4; ++m) _Pragma("unroll") for (int n = 0; n < 2; ++n) _Pragma("unroll") for (int k = 0; k < 2; ++k) \
;         acc[ai][bj][m][n] = __builtin_amdgcn_mfma_f32_16x16x32_bf16(Bt[n][k], At[m][k], acc[ai][bj][m][n], 0, 0, 0); __builtin_amdgcn_s_setprio(0); } while (0)
; #define PG8_WAIT_V(n) asm volatile("s_waitcnt vmcnt(" #n ")" ::: "memory")
; #define PG8_WAIT_L(n) asm volatile("s_waitcnt lgkmcnt(" #n ")" ::: "memory")
; #define PG8_BAR __builtin_amdgcn_s_barrier()
; #define PG8_SCHED __builtin_amdgcn_sched_barrier(0)
; template <class Epi, class Sched, bool ALIGN_EPI = false, bool SP2 = false>
; __device__ __forceinline__ void gemm_phase(PG8_LAS unsigned char* lds, const Gemm g, const Sched& S, const Epi& E) {
;     ...
;             PG8_WAIT_V(8); PG8_WAIT_L(0); PG8_BAR; PG8_MMA(1, 0, At, B0); PG8_MMA(1, 1, At, B1); PG8_BAR; PG8_SCHED;
;             PG8_LDB(B0, 1, 0); PG8_LDB(B1, 1, 1); PG8_SCHED; PG8_LDA(At, 1, 0); PG8_STAGE(PG8_SA(0, 1), a2 + hstep, voffA);
;             PG8_WAIT_V(8); PG8_WAIT_L(0); PG8_BAR; PG8_MMA(0, 0, At, B0); PG8_MMA(0, 1, At, B1); PG8_BAR; PG8_SCHED;
	s_setprio 1
	s_waitcnt lgkmcnt(0)
	v_mfma_f32_16x16x32_bf16 v[60:63], v[128:131], v[182:185], v[60:63]
	v_mfma_f32_16x16x32_bf16 v[56:59], v[148:151], v[182:185], v[56:59]
	v_mfma_f32_16x16x32_bf16 v[44:47], v[128:131], v[190:193], v[44:47]
	v_mfma_f32_16x16x32_bf16 v[40:43], v[148:151], v[190:193], v[40:43]
	v_mfma_f32_16x16x32_bf16 v[32:35], v[128:131], v[202:205], v[32:35]
	v_mfma_f32_16x16x32_bf16 v[24:27], v[148:151], v[202:205], v[24:27]
	v_mfma_f32_16x16x32_bf16 v[16:19], v[128:131], v[210:213], v[16:19]
	v_mfma_f32_16x16x32_bf16 v[8:11], v[148:151], v[210:213], v[8:11]
	v_mfma_f32_16x16x32_bf16 v[60:63], v[132:135], v[186:189], v[60:63]
	v_mfma_f32_16x16x32_bf16 v[56:59], v[162:165], v[186:189], v[56:59]
	v_mfma_f32_16x16x32_bf16 v[44:47], v[132:135], v[194:197], v[44:47]
	v_mfma_f32_16x16x32_bf16 v[40:43], v[162:165], v[194:197], v[40:43]
	v_mfma_f32_16x16x32_bf16 v[32:35], v[132:135], v[206:209], v[32:35]
	v_mfma_f32_16x16x32_bf16 v[24:27], v[162:165], v[206:209], v[24:27]
	v_mfma_f32_16x16x32_bf16 v[16:19], v[132:135], v[214:217], v[16:19]
	v_mfma_f32_16x16x32_bf16 v[8:11], v[162:165], v[214:217], v[8:11]
	s_setprio 0
	s_setprio 1
	v_mfma_f32_16x16x32_bf16 v[52:55], v[166:169], v[182:185], v[52:55]
	v_mfma_f32_16x16x32_bf16 v[48:51], v[174:177], v[182:185], v[48:51]
	v_mfma_f32_16x16x32_bf16 v[36:39], v[166:169], v[190:193], v[36:39]
	v_mfma_f32_16x16x32_bf16 v[28:31], v[174:177], v[190:193], v[28:31]
	v_mfma_f32_16x16x32_bf16 v[20:23], v[166:169], v[202:205], v[20:23]
	v_mfma_f32_16x16x32_bf16 v[12:15], v[174:177], v[202:205], v[12:15]
	v_mfma_f32_16x16x32_bf16 v[4:7], v[166:169], v[210:213], v[4:7]
	v_mfma_f32_16x16x32_bf16 v[0:3], v[174:177], v[210:213], v[0:3]
	v_mfma_f32_16x16x32_bf16 v[52:55], v[170:173], v[186:189], v[52:55]
	v_mfma_f32_16x16x32_bf16 v[48:51], v[178:181], v[186:189], v[48:51]
	v_mfma_f32_16x16x32_bf16 v[36:39], v[170:173], v[194:197], v[36:39]
	v_mfma_f32_16x16x32_bf16 v[28:31], v[178:181], v[194:197], v[28:31]
	v_mfma_f32_16x16x32_bf16 v[20:23], v[170:173], v[206:209], v[20:23]
	v_mfma_f32_16x16x32_bf16 v[12:15], v[178:181], v[206:209], v[12:15]
	v_mfma_f32_16x16x32_bf16 v[4:7], v[170:173], v[214:217], v[4:7]
	v_mfma_f32_16x16x32_bf16 v[0:3], v[178:181], v[214:217], v[0:3]
	s_setprio 0
	s_barrier
	ds_read_b128 v[128:131], v160
	ds_read_b128 v[132:135], v160 offset:1024
	ds_read_b128 v[148:151], v160 offset:2048
	ds_read_b128 v[162:165], v160 offset:3072
	ds_read_b128 v[166:169], v161
	ds_read_b128 v[170:173], v161 offset:1024
	ds_read_b128 v[174:177], v161 offset:2048
	ds_read_b128 v[178:181], v161 offset:3072
	s_add_u32 s44, s44, 0xb0000
	s_addc_u32 s45, s45, 0
	s_mov_b32 m0, s31
	v_lshl_add_u64 v[222:223], s[44:45], 0, v[136:137]
	ds_read_b128 v[182:185], v158 offset:32768
	ds_read_b128 v[186:189], v158 offset:33792
	ds_read_b128 v[190:193], v158 offset:34816
	ds_read_b128 v[194:197], v158 offset:35840
	ds_read_b128 v[202:205], v158 offset:36864
	ds_read_b128 v[206:209], v158 offset:37888
	ds_read_b128 v[210:213], v158 offset:38912
	ds_read_b128 v[214:217], v158 offset:39936
	global_load_lds_dwordx4 v[222:223], off
	v_lshl_add_u64 v[222:223], s[44:45], 0, v[140:141]
	s_mov_b32 m0, s37
	s_nop 0
	global_load_lds_dwordx4 v[222:223], off
	s_waitcnt vmcnt(8)
	s_waitcnt lgkmcnt(0)
	s_barrier
	s_setprio 1
	s_waitcnt lgkmcnt(0)
	v_mfma_f32_16x16x32_bf16 v[124:127], v[128:131], v[182:185], v[124:127]
	v_mfma_f32_16x16x32_bf16 v[120:123], v[148:151], v[182:185], v[120:123]
	v_mfma_f32_16x16x32_bf16 v[108:111], v[128:131], v[190:193], v[108:111]
	v_mfma_f32_16x16x32_bf16 v[104:107], v[148:151], v[190:193], v[104:107]
	v_mfma_f32_16x16x32_bf16 v[92:95], v[128:131], v[202:205], v[92:95]
	v_mfma_f32_16x16x32_bf16 v[88:91], v[148:151], v[202:205], v[88:91]
	v_mfma_f32_16x16x32_bf16 v[76:79], v[128:131], v[210:213], v[76:79]
	v_mfma_f32_16x16x32_bf16 v[72:75], v[148:151], v[210:213], v[72:75]
	v_mfma_f32_16x16x32_bf16 v[124:127], v[132:135], v[186:189], v[124:127]
	v_mfma_f32_16x16x32_bf16 v[120:123], v[162:165], v[186:189], v[120:123]
	v_mfma_f32_16x16x32_bf16 v[108:111], v[132:135], v[194:197], v[108:111]
	v_mfma_f32_16x16x32_bf16 v[104:107], v[162:165], v[194:197], v[104:107]
	v_mfma_f32_16x16x32_bf16 v[92:95], v[132:135], v[206:209], v[92:95]
	v_mfma_f32_16x16x32_bf16 v[88:91], v[162:165], v[206:209], v[88:91]
	v_mfma_f32_16x16x32_bf16 v[76:79], v[132:135], v[214:217], v[76:79]
	v_mfma_f32_16x16x32_bf16 v[72:75], v[162:165], v[214:217], v[72:75]
	s_setprio 0
	s_setprio 1
	v_mfma_f32_16x16x32_bf16 v[116:119], v[166:169], v[182:185], v[116:119]
	v_mfma_f32_16x16x32_bf16 v[112:115], v[174:177], v[182:185], v[112:115]
	v_mfma_f32_16x16x32_bf16 v[100:103], v[166:169], v[190:193], v[100:103]
	v_mfma_f32_16x16x32_bf16 v[96:99], v[174:177], v[190:193], v[96:99]
	v_mfma_f32_16x16x32_bf16 v[84:87], v[166:169], v[202:205], v[84:87]
	v_mfma_f32_16x16x32_bf16 v[80:83], v[174:177], v[202:205], v[80:83]
	v_mfma_f32_16x16x32_bf16 v[68:71], v[166:169], v[210:213], v[68:71]
	v_mfma_f32_16x16x32_bf16 v[64:67], v[174:177], v[210:213], v[64:67]
	v_mfma_f32_16x16x32_bf16 v[116:119], v[170:173], v[186:189], v[116:119]
	v_mfma_f32_16x16x32_bf16 v[112:115], v[178:181], v[186:189], v[112:115]
	v_mfma_f32_16x16x32_bf16 v[100:103], v[170:173], v[194:197], v[100:103]
	v_mfma_f32_16x16x32_bf16 v[96:99], v[178:181], v[194:197], v[96:99]
	v_mfma_f32_16x16x32_bf16 v[84:87], v[170:173], v[206:209], v[84:87]
	v_mfma_f32_16x16x32_bf16 v[80:83], v[178:181], v[206:209], v[80:83]
	v_mfma_f32_16x16x32_bf16 v[68:71], v[170:173], v[214:217], v[68:71]
	v_mfma_f32_16x16x32_bf16 v[64:67], v[178:181], v[214:217], v[64:67]
	s_setprio 0
	s_barrier
; #define PG8_STAGE(bufoff, gbase, voff) do { _Pragma("unroll") for (int _i = 0; _i < 2; ++_i) \
;         __builtin_amdgcn_global_load_lds((const unsigned*)((const char*)(gbase) + (voff)[_i]), (PG8_LAS unsigned*)(lds + (bufoff) + ldsw + _i * 8192), 16, 0, 0); } while (0)
; #define PG8_LDA(dst, b, h) do { _Pragma("unroll") for (int m = 0; m < 4; ++m) _Pragma("unroll") for (int k = 0; k < 2; ++k) dst[m][k] = *(const PG8_LAS bf16x8*)(lds + PG8_SA(b, h) + aoff + m * 2048 + k * 1024); } while (0)
; #define PG8_MMA(ai, bj, At, Bt) do { __builtin_amdgcn_s_setprio(1); _Pragma("unroll") for (int m = 0; m < 4; ++m) _Pragma("unroll") for (int n = 0; n < 2; ++n) _Pragma("unroll") for (int k = 0; k < 2; ++k) \
;         acc[ai][bj][m][n] = __builtin_amdgcn_mfma_f32_16x16x32_bf16(Bt[n][k], At[m][k], acc[ai][bj][m][n], 0, 0, 0); __builtin_amdgcn_s_setprio(0); } while (0)
; #define PG8_WAIT_V(n) asm volatile("s_waitcnt vmcnt(" #n ")" ::: "memory")
; #define PG8_WAIT_L(n) asm volatile("s_waitcnt lgkmcnt(" #n ")" ::: "memory")
; #define PG8_BAR __builtin_amdgcn_s_barrier()
; #define PG8_SCHED __builtin_amdgcn_sched_barrier(0)
; template <class Epi, class Sched, bool ALIGN_EPI = false, bool SP2 = false>
; __device__ __forceinline__ void gemm_phase(PG8_LAS unsigned char* lds, const Gemm g, const Sched& S, const Epi& E) {
;     ...
;         for (int t = 0; t < nt; t += 2) {
;     ...
;             PG8_LDA(At, 1, 1); PG8_STAGE(PG8_SB(1, 0), b3, voffB); PG8_STAGE(PG8_SB(1, 1), b3 + hstep, voffB); PG8_STAGE(PG8_SA(1, 0), a3, voffA);
;             PG8_WAIT_V(8); PG8_WAIT_L(0); PG8_BAR; PG8_MMA(1, 0, At, B0); PG8_MMA(1, 1, At, B1); PG8_BAR; PG8_SCHED;
	s_add_i32 s44, s64, s28
	v_lshl_add_u64 v[152:153], v[152:153], 0, s[12:13]
	s_mov_b32 m0, s44
	ds_read_b128 v[182:185], v158 offset:49152
	ds_read_b128 v[186:189], v158 offset:50176
	ds_read_b128 v[190:193], v158 offset:51200
	ds_read_b128 v[194:197], v158 offset:52224
	ds_read_b128 v[202:205], v158 offset:53248
	ds_read_b128 v[206:209], v158 offset:54272
	ds_read_b128 v[210:213], v158 offset:55296
	ds_read_b128 v[214:217], v158 offset:56320
	global_load_lds_dwordx4 v[152:153], off
	s_add_i32 m0, s44, 0x2000
	s_add_u32 s42, s42, 0xb0080
	v_lshl_add_u64 v[152:153], v[198:199], 0, s[12:13]
	s_addc_u32 s43, s43, 0
	s_add_i32 s44, s65, s28
	global_load_lds_dwordx4 v[152:153], off
	v_lshl_add_u64 v[152:153], s[42:43], 0, v[138:139]
	s_mov_b32 m0, s44
	s_nop 0
	global_load_lds_dwordx4 v[152:153], off
	v_lshl_add_u64 v[152:153], s[42:43], 0, v[142:143]
	s_add_i32 m0, s44, 0x2000
	s_nop 0
	global_load_lds_dwordx4 v[152:153], off
	v_lshl_add_u64 v[152:153], v[218:219], 0, s[12:13]
	s_mov_b32 m0, s47
	s_nop 0
	global_load_lds_dwordx4 v[152:153], off
	v_lshl_add_u64 v[152:153], v[220:221], 0, s[12:13]
	s_mov_b32 m0, s48
	s_nop 0
	global_load_lds_dwordx4 v[152:153], off
	s_waitcnt vmcnt(8)
	s_waitcnt lgkmcnt(0)
	s_barrier
	s_setprio 1
	s_waitcnt lgkmcnt(0)
	v_mfma_f32_16x16x32_bf16 v[60:63], v[128:131], v[182:185], v[60:63]
	v_mfma_f32_16x16x32_bf16 v[56:59], v[148:151], v[182:185], v[56:59]
	v_mfma_f32_16x16x32_bf16 v[44:47], v[128:131], v[190:193], v[44:47]
	v_mfma_f32_16x16x32_bf16 v[40:43], v[148:151], v[190:193], v[40:43]
	v_mfma_f32_16x16x32_bf16 v[32:35], v[128:131], v[202:205], v[32:35]
	v_mfma_f32_16x16x32_bf16 v[24:27], v[148:151], v[202:205], v[24:27]
	v_mfma_f32_16x16x32_bf16 v[16:19], v[128:131], v[210:213], v[16:19]
	v_mfma_f32_16x16x32_bf16 v[8:11], v[148:151], v[210:213], v[8:11]
	v_mfma_f32_16x16x32_bf16 v[60:63], v[132:135], v[186:189], v[60:63]
	v_mfma_f32_16x16x32_bf16 v[56:59], v[162:165], v[186:189], v[56:59]
	v_mfma_f32_16x16x32_bf16 v[44:47], v[132:135], v[194:197], v[44:47]
	v_mfma_f32_16x16x32_bf16 v[40:43], v[162:165], v[194:197], v[40:43]
	v_mfma_f32_16x16x32_bf16 v[32:35], v[132:135], v[206:209], v[32:35]
	v_mfma_f32_16x16x32_bf16 v[24:27], v[162:165], v[206:209], v[24:27]
	v_mfma_f32_16x16x32_bf16 v[16:19], v[132:135], v[214:217], v[16:19]
	v_mfma_f32_16x16x32_bf16 v[8:11], v[162:165], v[214:217], v[8:11]
	s_setprio 0
	s_setprio 1
	v_mfma_f32_16x16x32_bf16 v[52:55], v[166:169], v[182:185], v[52:55]
	v_mfma_f32_16x16x32_bf16 v[48:51], v[174:177], v[182:185], v[48:51]
	v_mfma_f32_16x16x32_bf16 v[36:39], v[166:169], v[190:193], v[36:39]
	v_mfma_f32_16x16x32_bf16 v[28:31], v[174:177], v[190:193], v[28:31]
	v_mfma_f32_16x16x32_bf16 v[20:23], v[166:169], v[202:205], v[20:23]
	v_mfma_f32_16x16x32_bf16 v[12:15], v[174:177], v[202:205], v[12:15]
	v_mfma_f32_16x16x32_bf16 v[4:7], v[166:169], v[210:213], v[4:7]
	v_mfma_f32_16x16x32_bf16 v[0:3], v[174:177], v[210:213], v[0:3]
	v_mfma_f32_16x16x32_bf16 v[52:55], v[170:173], v[186:189], v[52:55]
	v_mfma_f32_16x16x32_bf16 v[48:51], v[178:181], v[186:189], v[48:51]
	v_mfma_f32_16x16x32_bf16 v[36:39], v[170:173], v[194:197], v[36:39]
	v_mfma_f32_16x16x32_bf16 v[28:31], v[178:181], v[194:197], v[28:31]
	v_mfma_f32_16x16x32_bf16 v[20:23], v[170:173], v[206:209], v[20:23]
	v_mfma_f32_16x16x32_bf16 v[12:15], v[178:181], v[206:209], v[12:15]
	v_mfma_f32_16x16x32_bf16 v[4:7], v[170:173], v[214:217], v[4:7]
	v_mfma_f32_16x16x32_bf16 v[0:3], v[178:181], v[214:217], v[0:3]
	s_setprio 0
	s_add_i32 s72, s72, 2
	s_add_u32 s26, s26, 0x100
	s_addc_u32 s27, s27, 0
	s_add_u32 s70, s70, 0x100
	s_addc_u32 s71, s71, 0
	s_barrier
	s_cmp_gt_u32 s72, 41
	s_cbranch_scc0 .LBB0_1363
	s_and_b64 vcc, exec, s[14:15]
	s_cbranch_vccz .LBB0_1366
	s_barrier
